# wide GEMM K-loops switched to 16x16x32 bf16 MFMA (same bf16 operands, f32 accumulate) with in-register accumulator layout conversion; conflict-free LDS swizzle; batched merge-epilogue loads
# speedup vs baseline: 1.0141x; 1.0141x over previous
; __device__ __forceinline__ unsigned xb_xcc_id() { return (unsigned)__builtin_amdgcn_s_getreg((3 << 11) | 20) & 0xFu; }
; __device__ __forceinline__ void h_tile(WideCtx& c, const u16* __restrict__ A, int lda, int M, int m0, const u16* __restrict__ W, int ldw, int n0) {
; #pragma unroll
;   for (int i = 0; i < 2; ++i) {
;     const int q = c.tid + 256 * i, row = q >> 2, ch = (q & 3) ^ ((row >> 2) & 3);
;     c.wp[i] = W + (size_t)(n0 + row) * ldw + ch * 8;
;   }
; #pragma unroll
;   for (int i = 0; i < 4; ++i) {
;     const int q = c.tid + 256 * i, row = q >> 2, ch = (q & 3) ^ ((row >> 2) & 3);
;     int ar = m0 + row; ar = ar < M ? ar : M - 1;
;     c.ap[i] = A + (size_t)ar * lda + ch * 8;
;   }
; }
; __device__ __forceinline__ void h_stage(const WideCtx& c, int kt) {
;   const unsigned sb = c.lds0 + (kt & 1) * 24576;
; #pragma unroll
;   for (int i = 0; i < 2; ++i) glds16(c.wp[i] + kt * 32, sb + i * 4096);
; #pragma unroll
;   for (int i = 0; i < 4; ++i) glds16(c.ap[i] + kt * 32, sb + 8192 + i * 4096);
; }
; template <class F>
; __device__ __forceinline__ void gemm_phase_w(const u16* A, int lda, int M, const u16* W, int K, int N, char* lds, int* ctr, F&& epi) {
;   const int nN = N >> 7, nM = (M + 255) >> 8, nt = nN * nM, nk = K >> 5;
;   const int xcd = (int)xb_xcc_id() & 7;
;   const int tq = nt >> 3, trm = nt & 7;
;   const int tstart = xcd < trm ? xcd * (tq + 1) : trm * (tq + 1) + (xcd - trm) * tq;
;   const int tcnt = tq + (xcd < trm ? 1 : 0);
;   auto decode = [&](int off, int& tm, int& tn) {
;     const int id = tstart + off, nig = 4 * nN, grp = id / nig, fm = grp * 4;
;     const int gsz = (nM - fm) < 4 ? (nM - fm) : 4, idl = id - grp * nig;
;     tm = fm + idl % gsz; tn = idl / gsz;
;   };
;   WideCtx c;
;   h_init(c, lds);
;   const int wave = c.tid >> 6;
;   volatile int* bw = (volatile int*)(lds + 65536);
;   int* myctr = ctr + xcd;
;   int par = 0;
;   if (c.tid == 0) bw[2] = atomicAdd(myctr, 1);
;   asm volatile("s_waitcnt vmcnt(0) lgkmcnt(0)" ::: "memory");
;   __builtin_amdgcn_s_barrier();
;   int off = bw[2];
;   int tm = 0, tn = 0;
;   if (off < tcnt) { decode(off, tm, tn); h_tile(c, A, lda, M, tm * 256, W, K, tn * 128); h_stage(c, 0); }
.LBB0_43:
	s_or_b64 exec, exec, s[6:7]
	s_mov_b64 s[0:1], src_shared_base
	s_waitcnt vmcnt(0)
	v_mov_b32_e32 v163, s1
	s_waitcnt vmcnt(0) lgkmcnt(0)
	s_barrier
	flat_load_dword v1, v[162:163] sc0 sc1
	s_waitcnt vmcnt(0)
	s_add_i32 s0, s62, 0xff
	s_lshr_b32 s10, s0, 8
	s_waitcnt lgkmcnt(0)
	v_cmp_gt_i32_e64 s[38:39], s10, v1
	s_and_saveexec_b64 s[48:49], s[38:39]
	s_cbranch_execz .LBB0_70
	s_mul_i32 s11, s11, s10
	v_and_b32_e32 v2, 31, v0
	v_lshrrev_b32_e32 v6, 1, v0
	s_mov_b32 s0, 0x3ffffc0
	v_and_or_b32 v2, v6, s0, v2
	v_add_u32_e32 v1, s11, v1
	v_lshlrev_b32_e32 v157, 6, v2
	v_ashrrev_i32_e32 v2, 31, v1
	v_lshrrev_b32_e32 v2, 27, v2
	v_lshlrev_b32_e32 v6, 6, v0
	v_add_u32_e32 v2, v1, v2
	v_and_b32_e32 v156, 0x17c0, v6
	v_ashrrev_i32_e32 v6, 5, v2
	v_lshlrev_b32_e32 v6, 2, v6
	v_sub_u32_e32 v7, s10, v6
	v_min_i32_e32 v7, 4, v7
	v_sub_u32_e32 v8, 0, v7
	v_max_i32_e32 v8, v7, v8
	v_cvt_f32_u32_e32 v9, v8
	v_and_b32_e32 v2, 0xffffffe0, v2
	v_sub_u32_e32 v1, v1, v2
	v_sub_u32_e32 v11, 0, v8
	v_rcp_iflag_f32_e32 v2, v9
	v_sub_u32_e32 v10, 0, v1
	v_max_i32_e32 v10, v1, v10
	v_xor_b32_e32 v9, v1, v7
	v_mul_f32_e32 v2, 0x4f7ffffe, v2
	v_cvt_u32_f32_e32 v2, v2
	v_ashrrev_i32_e32 v9, 31, v9
	s_lshl_b32 s0, s9, 4
	s_and_b32 s54, s0, 0xfffffc00
	v_mul_lo_u32 v11, v11, v2
	v_mul_hi_u32 v11, v2, v11
	v_add_u32_e32 v2, v2, v11
	v_mul_hi_u32 v2, v10, v2
	v_mul_lo_u32 v11, v2, v8
	v_sub_u32_e32 v10, v10, v11
	v_add_u32_e32 v11, 1, v2
	v_cmp_ge_u32_e64 s[38:39], v10, v8
	s_load_dwordx2 s[0:1], s[64:65], 0x158
	v_ashrrev_i32_e32 v158, 2, v0
	v_cndmask_b32_e64 v2, v2, v11, s[38:39]
	v_sub_u32_e32 v11, v10, v8
	v_cndmask_b32_e64 v10, v10, v11, s[38:39]
	v_add_u32_e32 v11, 1, v2
	v_cmp_ge_u32_e64 s[38:39], v10, v8
	s_add_i32 s58, s62, -1
	s_add_i32 s59, s54, 0x1000
	v_cndmask_b32_e64 v2, v2, v11, s[38:39]
	v_xor_b32_e32 v2, v2, v9
	v_sub_u32_e32 v152, v2, v9
	v_mul_lo_u32 v2, v152, v7
	v_sub_u32_e32 v1, v1, v2
	v_add_u32_e32 v153, v1, v6
	v_lshrrev_b32_e32 v6, 4, v0
	v_and_b32_e32 v250, 1, v6
	v_lshlrev_b32_e32 v250, 1, v250
	v_xor_b32_e32 v6, v6, v250
	v_xor_b32_e32 v6, v6, v0
	v_lshlrev_b32_e32 v6, 4, v6
	v_lshlrev_b32_e32 v2, 7, v152
	v_and_b32_e32 v160, 48, v6
	s_waitcnt lgkmcnt(0)
	v_lshl_add_u64 v[128:129], s[0:1], 0, v[160:161]
	v_add_u32_e32 v6, v2, v158
	v_mad_i64_i32 v[132:133], s[0:1], v6, s56, v[128:129]
	v_add_u32_e32 v6, 0x100, v0
	v_ashrrev_i32_e32 v159, 2, v6
	v_add_u32_e32 v2, v2, v159
	v_mad_i64_i32 v[134:135], s[0:1], v2, s56, v[128:129]
	s_load_dwordx2 s[0:1], s[64:65], 0x1c8
	v_lshlrev_b32_e32 v1, 8, v153
	v_add_u32_e32 v2, v1, v158
	v_min_i32_e32 v2, s58, v2
	s_add_i32 s63, s54, 0x2000
	s_waitcnt lgkmcnt(0)
	v_lshl_add_u64 v[130:131], s[0:1], 0, v[160:161]
	v_mad_i64_i32 v[136:137], s[0:1], v2, s56, v[130:131]
	v_add_u32_e32 v2, v1, v159
	v_min_i32_e32 v2, s58, v2
	v_mad_i64_i32 v[138:139], s[0:1], v2, s56, v[130:131]
	v_add_u32_e32 v2, 0x200, v0
	v_ashrrev_i32_e32 v160, 2, v2
	v_add_u32_e32 v2, v1, v160
	v_min_i32_e32 v2, s58, v2
	s_mov_b32 s0, m0
	s_mov_b32 m0, s54
	s_nop 0
	global_load_lds_dwordx4 v[132:133], off
	s_mov_b32 m0, s0
	s_add_i32 s81, s54, 0x3000
	v_mad_i64_i32 v[140:141], s[0:1], v2, s56, v[130:131]
	v_add_u32_e32 v2, 0x300, v0
	s_mov_b32 s0, m0
	s_mov_b32 m0, s59
	s_nop 0
	global_load_lds_dwordx4 v[134:135], off
	s_mov_b32 m0, s0
	v_ashrrev_i32_e32 v163, 2, v2
	s_mov_b32 s0, m0
	s_mov_b32 m0, s63
	s_nop 0
	global_load_lds_dwordx4 v[136:137], off
	s_mov_b32 m0, s0
	v_add_u32_e32 v1, v1, v163
	s_mov_b32 s0, m0
	s_mov_b32 m0, s81
	s_nop 0
	global_load_lds_dwordx4 v[138:139], off
	s_mov_b32 m0, s0
	v_min_i32_e32 v1, s58, v1
	s_add_i32 s84, s54, 0x4000
	s_mov_b32 s0, m0
	s_mov_b32 m0, s84
	s_nop 0
	global_load_lds_dwordx4 v[140:141], off
	s_mov_b32 m0, s0
	s_add_i32 s88, s54, 0x5000
	v_mad_i64_i32 v[142:143], s[0:1], v1, s56, v[130:131]
	s_mov_b32 s0, m0
	s_mov_b32 m0, s88
	s_nop 0
	global_load_lds_dwordx4 v[142:143], off
	s_mov_b32 m0, s0
	s_add_i32 m0, s54, 0x5fc0
	s_nop 0
	global_load_lds_dwordx4 v[132:133], off offset:64
	s_add_i32 m0, s59, 0x5fc0
	s_nop 0
	global_load_lds_dwordx4 v[134:135], off offset:64
	s_add_i32 m0, s63, 0x5fc0
	s_nop 0
	global_load_lds_dwordx4 v[136:137], off offset:64
	s_add_i32 m0, s81, 0x5fc0
	s_nop 0
	global_load_lds_dwordx4 v[138:139], off offset:64
	s_add_i32 m0, s84, 0x5fc0
	s_nop 0
	global_load_lds_dwordx4 v[140:141], off offset:64
	s_add_i32 m0, s88, 0x5fc0
	s_nop 0
	global_load_lds_dwordx4 v[142:143], off offset:64
	s_load_dwordx2 s[50:51], s[64:65], 0x238
	s_load_dwordx4 s[44:47], s[64:65], 0x1b8
	v_bfe_u32 v3, v0, 5, 1
	v_lshrrev_b32_e32 v4, 2, v0
	v_bfe_u32 v5, v0, 2, 2
	v_bitop3_b32 v1, v4, v3, 3 bitop3:0x6c
	v_lshlrev_b32_e32 v164, 4, v1
	v_bitop3_b32 v1, v3, v5, 2 bitop3:0x36
	v_and_b32_e32 v166, 64, v0
	v_ashrrev_i32_e32 v0, 1, v0
	s_mov_b32 s55, 0
	v_lshlrev_b32_e32 v165, 4, v1
	v_and_b32_e32 v167, 0xffffffc0, v0
	s_mov_b64 s[52:53], 0
	s_branch .LBB0_46

; __device__ __forceinline__ void h_main(f32x16 (&acc0)[2][2], f32x16 (&acc1)[2][2], const WideCtx& c, int nk, char* lds) {
;   const int h = c.h;
;   for (int kt = 0; kt < nk; ++kt) {
;     asm volatile("s_waitcnt vmcnt(0)" ::: "memory");
;     __builtin_amdgcn_s_barrier();
;     if (kt + 1 < nk) h_stage(c, kt + 1);
;     const char* st = lds + (kt & 1) * 24576;
; #pragma unroll
;     for (int ks = 0; ks < 2; ++ks) {
;       bf16x8 wf[2], a0[2], a1[2];
; #pragma unroll
;       for (int b = 0; b < 2; ++b) {
;         wf[b] = *(const bf16x8*)(st + c.wro[b] + (((ks * 2 + h) ^ c.wsw[b]) << 4));
;         a0[b] = *(const bf16x8*)(st + c.aro[0][b] + (((ks * 2 + h) ^ c.asw[0][b]) << 4));
;         a1[b] = *(const bf16x8*)(st + c.aro[1][b] + (((ks * 2 + h) ^ c.asw[1][b]) << 4));
;       }
; #pragma unroll
;       for (int nb = 0; nb < 2; ++nb)
; #pragma unroll
;         for (int tb = 0; tb < 2; ++tb) {
;           acc0[nb][tb] = __builtin_amdgcn_mfma_f32_32x32x16_bf16(wf[nb], a0[tb], acc0[nb][tb], 0, 0, 0);
;           acc1[nb][tb] = __builtin_amdgcn_mfma_f32_32x32x16_bf16(wf[nb], a1[tb], acc1[nb][tb], 0, 0, 0);
;         }
.LBB0_46:
	v_mov_b32_e32 v64, 0
	v_mov_b32_e32 v168, v153
	v_mov_b32_e32 v169, v152
	s_load_dwordx2 s[0:1], s[64:65], 0x120
	s_waitcnt lgkmcnt(0)
	v_subrev_u32_e32 v144, s0, v142
	v_subrev_u32_e32 v146, s0, v140
	v_subrev_u32_e32 v148, s0, v138
	v_subrev_u32_e32 v150, s0, v136
	v_subrev_u32_e32 v152, s0, v134
	v_subrev_u32_e32 v154, s0, v132
	s_add_u32 s0, s0, 0x80
	s_addc_u32 s1, s1, 0
	s_mov_b32 s9, 2
	s_mov_b32 s6, 0
	v_and_b32_e32 v250, 15, v204
	v_lshlrev_b32_e32 v250, 6, v250
	v_bfe_u32 v251, v204, 2, 2
	v_and_b32_e32 v247, 1, v251
	v_lshlrev_b32_e32 v247, 1, v247
	v_xor_b32_e32 v251, v251, v247
	v_bfe_u32 v247, v204, 4, 2
	v_xor_b32_e32 v251, v251, v247
	v_lshl_or_b32 v250, v251, 4, v250
	v_bfe_u32 v247, v204, 6, 1
	v_lshl_or_b32 v248, v247, 12, v250
	v_lshrrev_b32_e32 v247, 7, v204
	v_lshl_or_b32 v249, v247, 12, v250
	v_mov_b32_e32 v65, v64
	v_mov_b32_e32 v66, v64
	v_mov_b32_e32 v67, v64
	v_mov_b32_e32 v68, v64
	v_mov_b32_e32 v69, v64
	v_mov_b32_e32 v70, v64
	v_mov_b32_e32 v71, v64
	v_mov_b32_e32 v72, v64
	v_mov_b32_e32 v73, v64
	v_mov_b32_e32 v74, v64
	v_mov_b32_e32 v75, v64
	v_mov_b32_e32 v76, v64
	v_mov_b32_e32 v77, v64
	v_mov_b32_e32 v78, v64
	v_mov_b32_e32 v79, v64
	v_mov_b32_e32 v96, v64
	v_mov_b32_e32 v97, v64
	v_mov_b32_e32 v98, v64
	v_mov_b32_e32 v99, v64
	v_mov_b32_e32 v100, v64
	v_mov_b32_e32 v101, v64
	v_mov_b32_e32 v102, v64
	v_mov_b32_e32 v103, v64
	v_mov_b32_e32 v104, v64
	v_mov_b32_e32 v105, v64
	v_mov_b32_e32 v106, v64
	v_mov_b32_e32 v107, v64
	v_mov_b32_e32 v108, v64
	v_mov_b32_e32 v109, v64
	v_mov_b32_e32 v110, v64
	v_mov_b32_e32 v111, v64
	v_mov_b32_e32 v80, v64
	v_mov_b32_e32 v81, v64
	v_mov_b32_e32 v82, v64
	v_mov_b32_e32 v83, v64
	v_mov_b32_e32 v84, v64
	v_mov_b32_e32 v85, v64
	v_mov_b32_e32 v86, v64
	v_mov_b32_e32 v87, v64
	v_mov_b32_e32 v88, v64
	v_mov_b32_e32 v89, v64
	v_mov_b32_e32 v90, v64
	v_mov_b32_e32 v91, v64
	v_mov_b32_e32 v92, v64
	v_mov_b32_e32 v93, v64
	v_mov_b32_e32 v94, v64
	v_mov_b32_e32 v95, v64
	v_mov_b32_e32 v112, v64
	v_mov_b32_e32 v113, v64
	v_mov_b32_e32 v114, v64
	v_mov_b32_e32 v115, v64
	v_mov_b32_e32 v116, v64
	v_mov_b32_e32 v117, v64
	v_mov_b32_e32 v118, v64
	v_mov_b32_e32 v119, v64
	v_mov_b32_e32 v120, v64
	v_mov_b32_e32 v121, v64
	v_mov_b32_e32 v122, v64
	v_mov_b32_e32 v123, v64
	v_mov_b32_e32 v124, v64
	v_mov_b32_e32 v125, v64
	v_mov_b32_e32 v126, v64
	v_mov_b32_e32 v127, v64
	s_waitcnt lgkmcnt(0)
	v_mov_b32_e32 v0, v64
	v_mov_b32_e32 v1, v64
	v_mov_b32_e32 v2, v64
	v_mov_b32_e32 v3, v64
	v_mov_b32_e32 v4, v64
	v_mov_b32_e32 v5, v64
	v_mov_b32_e32 v6, v64
	v_mov_b32_e32 v7, v64
	v_mov_b32_e32 v8, v64
	v_mov_b32_e32 v9, v64
	v_mov_b32_e32 v10, v64
	v_mov_b32_e32 v11, v64
	v_mov_b32_e32 v12, v64
	v_mov_b32_e32 v13, v64
	v_mov_b32_e32 v14, v64
	v_mov_b32_e32 v15, v64
	v_mov_b32_e32 v32, v64
	v_mov_b32_e32 v33, v64
	v_mov_b32_e32 v34, v64
	v_mov_b32_e32 v35, v64
	v_mov_b32_e32 v36, v64
	v_mov_b32_e32 v37, v64
	v_mov_b32_e32 v38, v64
	v_mov_b32_e32 v39, v64
	v_mov_b32_e32 v40, v64
	v_mov_b32_e32 v41, v64
	v_mov_b32_e32 v42, v64
	v_mov_b32_e32 v43, v64
	v_mov_b32_e32 v44, v64
	v_mov_b32_e32 v45, v64
	v_mov_b32_e32 v46, v64
	v_mov_b32_e32 v47, v64
	v_mov_b32_e32 v16, v64
	v_mov_b32_e32 v17, v64
	v_mov_b32_e32 v18, v64
	v_mov_b32_e32 v19, v64
	v_mov_b32_e32 v20, v64
	v_mov_b32_e32 v21, v64
	v_mov_b32_e32 v22, v64
	v_mov_b32_e32 v23, v64
	v_mov_b32_e32 v24, v64
	v_mov_b32_e32 v25, v64
	v_mov_b32_e32 v26, v64
	v_mov_b32_e32 v27, v64
	v_mov_b32_e32 v28, v64
	v_mov_b32_e32 v29, v64
	v_mov_b32_e32 v30, v64
	v_mov_b32_e32 v31, v64
	v_mov_b32_e32 v48, v64
	v_mov_b32_e32 v49, v64
	v_mov_b32_e32 v50, v64
	v_mov_b32_e32 v51, v64
	v_mov_b32_e32 v52, v64
	v_mov_b32_e32 v53, v64
	v_mov_b32_e32 v54, v64
	v_mov_b32_e32 v55, v64
	v_mov_b32_e32 v56, v64
	v_mov_b32_e32 v57, v64
	v_mov_b32_e32 v58, v64
	v_mov_b32_e32 v59, v64
	v_mov_b32_e32 v60, v64
	v_mov_b32_e32 v61, v64
	v_mov_b32_e32 v62, v64
	v_mov_b32_e32 v63, v64
.LBB0_47:
	s_waitcnt vmcnt(6)
	s_barrier
	v_add_u32_e32 v194, s6, v248
	v_add_u32_e32 v195, s6, v249
	ds_read_b128 v[170:173], v194
	ds_read_b128 v[174:177], v195 offset:8192
	ds_read_b128 v[186:189], v195 offset:9216
	ds_read_b128 v[178:181], v195 offset:10240
	ds_read_b128 v[190:193], v195 offset:11264
	ds_read_b128 v[230:233], v195 offset:16384
	ds_read_b128 v[234:237], v195 offset:17408
	ds_read_b128 v[238:241], v195 offset:18432
	ds_read_b128 v[242:245], v195 offset:19456
	ds_read_b128 v[182:185], v194 offset:1024
	ds_read_b128 v[222:225], v194 offset:2048
	ds_read_b128 v[226:229], v194 offset:3072
	s_add_i32 s7, s6, 0xffffa000
	s_cmp_eq_u32 s6, 0
	s_cselect_b32 s7, 0xc000, s7
	s_add_i32 m0, s7, s54
	s_add_i32 s7, s6, 0x6000
	global_load_lds_dwordx4 v154, s[0:1]
	s_add_i32 m0, m0, 0x1000
	s_cmp_eq_u32 s6, 0xc000
	global_load_lds_dwordx4 v152, s[0:1]
	s_cselect_b32 s6, 0, s7
	s_add_i32 m0, m0, 0x1000
	s_waitcnt lgkmcnt(10)
	v_mfma_f32_16x16x32_bf16 v[112:115], v[170:173], v[174:177], v[112:115]
	global_load_lds_dwordx4 v150, s[0:1]
	s_add_i32 m0, m0, 0x1000
	s_waitcnt lgkmcnt(9)
	v_mfma_f32_16x16x32_bf16 v[116:119], v[170:173], v[186:189], v[116:119]
	global_load_lds_dwordx4 v148, s[0:1]
	s_add_i32 m0, m0, 0x1000
	s_waitcnt lgkmcnt(8)
	v_mfma_f32_16x16x32_bf16 v[80:83], v[170:173], v[178:181], v[80:83]
	global_load_lds_dwordx4 v146, s[0:1]
	s_add_i32 m0, m0, 0x1000
	s_waitcnt lgkmcnt(7)
	v_mfma_f32_16x16x32_bf16 v[84:87], v[170:173], v[190:193], v[84:87]
	global_load_lds_dwordx4 v144, s[0:1]
	s_add_u32 s0, s0, 64
	s_addc_u32 s1, s1, 0
	s_waitcnt lgkmcnt(6)
	v_mfma_f32_16x16x32_bf16 v[48:51], v[170:173], v[230:233], v[48:51]
	s_waitcnt lgkmcnt(5)
; __device__ __forceinline__ void h_main(f32x16 (&acc0)[2][2], f32x16 (&acc1)[2][2], const WideCtx& c, int nk, char* lds) {
;   const int h = c.h;
;   for (int kt = 0; kt < nk; ++kt) {
;     asm volatile("s_waitcnt vmcnt(0)" ::: "memory");
;     __builtin_amdgcn_s_barrier();
;     if (kt + 1 < nk) h_stage(c, kt + 1);
;     const char* st = lds + (kt & 1) * 24576;
; #pragma unroll
;     for (int ks = 0; ks < 2; ++ks) {
;       bf16x8 wf[2], a0[2], a1[2];
; #pragma unroll
;       for (int b = 0; b < 2; ++b) {
;         wf[b] = *(const bf16x8*)(st + c.wro[b] + (((ks * 2 + h) ^ c.wsw[b]) << 4));
;         a0[b] = *(const bf16x8*)(st + c.aro[0][b] + (((ks * 2 + h) ^ c.asw[0][b]) << 4));
;         a1[b] = *(const bf16x8*)(st + c.aro[1][b] + (((ks * 2 + h) ^ c.asw[1][b]) << 4));
;       }
; #pragma unroll
;       for (int nb = 0; nb < 2; ++nb)
; #pragma unroll
;         for (int tb = 0; tb < 2; ++tb) {
;           acc0[nb][tb] = __builtin_amdgcn_mfma_f32_32x32x16_bf16(wf[nb], a0[tb], acc0[nb][tb], 0, 0, 0);
;           acc1[nb][tb] = __builtin_amdgcn_mfma_f32_32x32x16_bf16(wf[nb], a1[tb], acc1[nb][tb], 0, 0, 0);
;         }
;     }
;   }
; }
	v_mfma_f32_16x16x32_bf16 v[52:55], v[170:173], v[234:237], v[52:55]
	s_waitcnt lgkmcnt(4)
	v_mfma_f32_16x16x32_bf16 v[16:19], v[170:173], v[238:241], v[16:19]
	s_waitcnt lgkmcnt(3)
	v_mfma_f32_16x16x32_bf16 v[20:23], v[170:173], v[242:245], v[20:23]
	s_waitcnt lgkmcnt(2)
	v_mfma_f32_16x16x32_bf16 v[120:123], v[182:185], v[174:177], v[120:123]
	v_mfma_f32_16x16x32_bf16 v[124:127], v[182:185], v[186:189], v[124:127]
	v_mfma_f32_16x16x32_bf16 v[88:91], v[182:185], v[178:181], v[88:91]
	v_mfma_f32_16x16x32_bf16 v[92:95], v[182:185], v[190:193], v[92:95]
	v_mfma_f32_16x16x32_bf16 v[56:59], v[182:185], v[230:233], v[56:59]
	v_mfma_f32_16x16x32_bf16 v[60:63], v[182:185], v[234:237], v[60:63]
	v_mfma_f32_16x16x32_bf16 v[24:27], v[182:185], v[238:241], v[24:27]
	v_mfma_f32_16x16x32_bf16 v[28:31], v[182:185], v[242:245], v[28:31]
	s_waitcnt lgkmcnt(1)
	v_mfma_f32_16x16x32_bf16 v[96:99], v[222:225], v[174:177], v[96:99]
	v_mfma_f32_16x16x32_bf16 v[100:103], v[222:225], v[186:189], v[100:103]
	v_mfma_f32_16x16x32_bf16 v[64:67], v[222:225], v[178:181], v[64:67]
	v_mfma_f32_16x16x32_bf16 v[68:71], v[222:225], v[190:193], v[68:71]
	v_mfma_f32_16x16x32_bf16 v[32:35], v[222:225], v[230:233], v[32:35]
	v_mfma_f32_16x16x32_bf16 v[36:39], v[222:225], v[234:237], v[36:39]
	v_mfma_f32_16x16x32_bf16 v[0:3], v[222:225], v[238:241], v[0:3]
	v_mfma_f32_16x16x32_bf16 v[4:7], v[222:225], v[242:245], v[4:7]
	s_waitcnt lgkmcnt(0)
	v_mfma_f32_16x16x32_bf16 v[104:107], v[226:229], v[174:177], v[104:107]
	v_mfma_f32_16x16x32_bf16 v[108:111], v[226:229], v[186:189], v[108:111]
	v_mfma_f32_16x16x32_bf16 v[72:75], v[226:229], v[178:181], v[72:75]
	v_mfma_f32_16x16x32_bf16 v[76:79], v[226:229], v[190:193], v[76:79]
	v_mfma_f32_16x16x32_bf16 v[40:43], v[226:229], v[230:233], v[40:43]
	v_mfma_f32_16x16x32_bf16 v[44:47], v[226:229], v[234:237], v[44:47]
	v_mfma_f32_16x16x32_bf16 v[8:11], v[226:229], v[238:241], v[8:11]
	v_mfma_f32_16x16x32_bf16 v[12:15], v[226:229], v[242:245], v[12:15]
	s_add_i32 s9, s9, 1
	s_cmp_eq_u32 s9, 88
	s_cbranch_scc0 .LBB0_47
	s_waitcnt vmcnt(6)
	s_barrier
	v_add_u32_e32 v194, s6, v248
	v_add_u32_e32 v195, s6, v249
	ds_read_b128 v[170:173], v194
	ds_read_b128 v[174:177], v195 offset:8192
	ds_read_b128 v[186:189], v195 offset:9216
	ds_read_b128 v[178:181], v195 offset:10240
	ds_read_b128 v[190:193], v195 offset:11264
	ds_read_b128 v[230:233], v195 offset:16384
	ds_read_b128 v[234:237], v195 offset:17408
	ds_read_b128 v[238:241], v195 offset:18432
	ds_read_b128 v[242:245], v195 offset:19456
	ds_read_b128 v[182:185], v194 offset:1024
	ds_read_b128 v[222:225], v194 offset:2048
	ds_read_b128 v[226:229], v194 offset:3072
	s_add_i32 s7, s6, 0x6000
	s_cmp_eq_u32 s6, 0xc000
	s_cselect_b32 s6, 0, s7
	s_waitcnt lgkmcnt(10)
	v_mfma_f32_16x16x32_bf16 v[112:115], v[170:173], v[174:177], v[112:115]
	s_waitcnt lgkmcnt(9)
	v_mfma_f32_16x16x32_bf16 v[116:119], v[170:173], v[186:189], v[116:119]
	s_waitcnt lgkmcnt(8)
	v_mfma_f32_16x16x32_bf16 v[80:83], v[170:173], v[178:181], v[80:83]
	s_waitcnt lgkmcnt(7)
	v_mfma_f32_16x16x32_bf16 v[84:87], v[170:173], v[190:193], v[84:87]
	s_waitcnt lgkmcnt(6)
	v_mfma_f32_16x16x32_bf16 v[48:51], v[170:173], v[230:233], v[48:51]
	s_waitcnt lgkmcnt(5)
	v_mfma_f32_16x16x32_bf16 v[52:55], v[170:173], v[234:237], v[52:55]
	s_waitcnt lgkmcnt(4)
	v_mfma_f32_16x16x32_bf16 v[16:19], v[170:173], v[238:241], v[16:19]
	s_waitcnt lgkmcnt(3)
	v_mfma_f32_16x16x32_bf16 v[20:23], v[170:173], v[242:245], v[20:23]
	s_waitcnt lgkmcnt(2)
	v_mfma_f32_16x16x32_bf16 v[120:123], v[182:185], v[174:177], v[120:123]
	v_mfma_f32_16x16x32_bf16 v[124:127], v[182:185], v[186:189], v[124:127]
	v_mfma_f32_16x16x32_bf16 v[88:91], v[182:185], v[178:181], v[88:91]
	v_mfma_f32_16x16x32_bf16 v[92:95], v[182:185], v[190:193], v[92:95]
	v_mfma_f32_16x16x32_bf16 v[56:59], v[182:185], v[230:233], v[56:59]
	v_mfma_f32_16x16x32_bf16 v[60:63], v[182:185], v[234:237], v[60:63]
	v_mfma_f32_16x16x32_bf16 v[24:27], v[182:185], v[238:241], v[24:27]
	v_mfma_f32_16x16x32_bf16 v[28:31], v[182:185], v[242:245], v[28:31]
	s_waitcnt lgkmcnt(1)
	v_mfma_f32_16x16x32_bf16 v[96:99], v[222:225], v[174:177], v[96:99]
	v_mfma_f32_16x16x32_bf16 v[100:103], v[222:225], v[186:189], v[100:103]
	v_mfma_f32_16x16x32_bf16 v[64:67], v[222:225], v[178:181], v[64:67]
	v_mfma_f32_16x16x32_bf16 v[68:71], v[222:225], v[190:193], v[68:71]
	v_mfma_f32_16x16x32_bf16 v[32:35], v[222:225], v[230:233], v[32:35]
	v_mfma_f32_16x16x32_bf16 v[36:39], v[222:225], v[234:237], v[36:39]
	v_mfma_f32_16x16x32_bf16 v[0:3], v[222:225], v[238:241], v[0:3]
	v_mfma_f32_16x16x32_bf16 v[4:7], v[222:225], v[242:245], v[4:7]
	s_waitcnt lgkmcnt(0)
	v_mfma_f32_16x16x32_bf16 v[104:107], v[226:229], v[174:177], v[104:107]
	v_mfma_f32_16x16x32_bf16 v[108:111], v[226:229], v[186:189], v[108:111]
	v_mfma_f32_16x16x32_bf16 v[72:75], v[226:229], v[178:181], v[72:75]
	v_mfma_f32_16x16x32_bf16 v[76:79], v[226:229], v[190:193], v[76:79]
	v_mfma_f32_16x16x32_bf16 v[40:43], v[226:229], v[230:233], v[40:43]
	v_mfma_f32_16x16x32_bf16 v[44:47], v[226:229], v[234:237], v[44:47]
	v_mfma_f32_16x16x32_bf16 v[8:11], v[226:229], v[238:241], v[8:11]
	v_mfma_f32_16x16x32_bf16 v[12:15], v[226:229], v[242:245], v[12:15]
	s_waitcnt vmcnt(0)
	s_barrier
; __device__ __forceinline__ void h_main(f32x16 (&acc0)[2][2], f32x16 (&acc1)[2][2], const WideCtx& c, int nk, char* lds) {
;     ...
;     const char* st = lds + (kt & 1) * 24576;
; #pragma unroll
;     for (int ks = 0; ks < 2; ++ks) {
;       bf16x8 wf[2], a0[2], a1[2];
; #pragma unroll
;       for (int b = 0; b < 2; ++b) {
;         wf[b] = *(const bf16x8*)(st + c.wro[b] + (((ks * 2 + h) ^ c.wsw[b]) << 4));
;         a0[b] = *(const bf16x8*)(st + c.aro[0][b] + (((ks * 2 + h) ^ c.asw[0][b]) << 4));
;         a1[b] = *(const bf16x8*)(st + c.aro[1][b] + (((ks * 2 + h) ^ c.asw[1][b]) << 4));
;       }
; #pragma unroll
;       for (int nb = 0; nb < 2; ++nb)
; #pragma unroll
;         for (int tb = 0; tb < 2; ++tb) {
;           acc0[nb][tb] = __builtin_amdgcn_mfma_f32_32x32x16_bf16(wf[nb], a0[tb], acc0[nb][tb], 0, 0, 0);
;           acc1[nb][tb] = __builtin_amdgcn_mfma_f32_32x32x16_bf16(wf[nb], a1[tb], acc1[nb][tb], 0, 0, 0);
;         }
	v_add_u32_e32 v194, s6, v248
	v_add_u32_e32 v195, s6, v249
	ds_read_b128 v[170:173], v194
	ds_read_b128 v[174:177], v195 offset:8192
	ds_read_b128 v[186:189], v195 offset:9216
	ds_read_b128 v[178:181], v195 offset:10240
	ds_read_b128 v[190:193], v195 offset:11264
	ds_read_b128 v[230:233], v195 offset:16384
	ds_read_b128 v[234:237], v195 offset:17408
	ds_read_b128 v[238:241], v195 offset:18432
	ds_read_b128 v[242:245], v195 offset:19456
	ds_read_b128 v[182:185], v194 offset:1024
	ds_read_b128 v[222:225], v194 offset:2048
	ds_read_b128 v[226:229], v194 offset:3072
	s_add_i32 s7, s6, 0x6000
	s_cmp_eq_u32 s6, 0xc000
	s_cselect_b32 s6, 0, s7
	s_waitcnt lgkmcnt(10)
	v_mfma_f32_16x16x32_bf16 v[112:115], v[170:173], v[174:177], v[112:115]
	s_waitcnt lgkmcnt(9)
	v_mfma_f32_16x16x32_bf16 v[116:119], v[170:173], v[186:189], v[116:119]
	s_waitcnt lgkmcnt(8)
	v_mfma_f32_16x16x32_bf16 v[80:83], v[170:173], v[178:181], v[80:83]
	s_waitcnt lgkmcnt(7)
	v_mfma_f32_16x16x32_bf16 v[84:87], v[170:173], v[190:193], v[84:87]
	s_waitcnt lgkmcnt(6)
	v_mfma_f32_16x16x32_bf16 v[48:51], v[170:173], v[230:233], v[48:51]
	s_waitcnt lgkmcnt(5)
	v_mfma_f32_16x16x32_bf16 v[52:55], v[170:173], v[234:237], v[52:55]
	s_waitcnt lgkmcnt(4)
	v_mfma_f32_16x16x32_bf16 v[16:19], v[170:173], v[238:241], v[16:19]
	s_waitcnt lgkmcnt(3)
	v_mfma_f32_16x16x32_bf16 v[20:23], v[170:173], v[242:245], v[20:23]
	s_waitcnt lgkmcnt(2)
	v_mfma_f32_16x16x32_bf16 v[120:123], v[182:185], v[174:177], v[120:123]
	v_mfma_f32_16x16x32_bf16 v[124:127], v[182:185], v[186:189], v[124:127]
	v_mfma_f32_16x16x32_bf16 v[88:91], v[182:185], v[178:181], v[88:91]
	v_mfma_f32_16x16x32_bf16 v[92:95], v[182:185], v[190:193], v[92:95]
	v_mfma_f32_16x16x32_bf16 v[56:59], v[182:185], v[230:233], v[56:59]
	v_mfma_f32_16x16x32_bf16 v[60:63], v[182:185], v[234:237], v[60:63]
	v_mfma_f32_16x16x32_bf16 v[24:27], v[182:185], v[238:241], v[24:27]
	v_mfma_f32_16x16x32_bf16 v[28:31], v[182:185], v[242:245], v[28:31]
	s_waitcnt lgkmcnt(1)
	v_mfma_f32_16x16x32_bf16 v[96:99], v[222:225], v[174:177], v[96:99]
	v_mfma_f32_16x16x32_bf16 v[100:103], v[222:225], v[186:189], v[100:103]
	v_mfma_f32_16x16x32_bf16 v[64:67], v[222:225], v[178:181], v[64:67]
	v_mfma_f32_16x16x32_bf16 v[68:71], v[222:225], v[190:193], v[68:71]
	v_mfma_f32_16x16x32_bf16 v[32:35], v[222:225], v[230:233], v[32:35]
	v_mfma_f32_16x16x32_bf16 v[36:39], v[222:225], v[234:237], v[36:39]
	v_mfma_f32_16x16x32_bf16 v[0:3], v[222:225], v[238:241], v[0:3]
	v_mfma_f32_16x16x32_bf16 v[4:7], v[222:225], v[242:245], v[4:7]
	s_waitcnt lgkmcnt(0)
; __device__ __forceinline__ void h_main(f32x16 (&acc0)[2][2], f32x16 (&acc1)[2][2], const WideCtx& c, int nk, char* lds) {
;     ...
;       for (int nb = 0; nb < 2; ++nb)
; #pragma unroll
;         for (int tb = 0; tb < 2; ++tb) {
;           acc0[nb][tb] = __builtin_amdgcn_mfma_f32_32x32x16_bf16(wf[nb], a0[tb], acc0[nb][tb], 0, 0, 0);
;           acc1[nb][tb] = __builtin_amdgcn_mfma_f32_32x32x16_bf16(wf[nb], a1[tb], acc1[nb][tb], 0, 0, 0);
;         }
; template <class F>
; __device__ __forceinline__ void gemm_phase_w(const u16* A, int lda, int M, const u16* W, int K, int N, char* lds, int* ctr, F&& epi) {
;     ...
;     const int ctm = tm, ctn = tn;
;     par ^= 1;
;     if (c.tid == 0) bw[2 + par] = atomicAdd(myctr, 1);
	v_mfma_f32_16x16x32_bf16 v[104:107], v[226:229], v[174:177], v[104:107]
	v_mfma_f32_16x16x32_bf16 v[108:111], v[226:229], v[186:189], v[108:111]
	v_mfma_f32_16x16x32_bf16 v[72:75], v[226:229], v[178:181], v[72:75]
	v_mfma_f32_16x16x32_bf16 v[76:79], v[226:229], v[190:193], v[76:79]
	v_mfma_f32_16x16x32_bf16 v[40:43], v[226:229], v[230:233], v[40:43]
	v_mfma_f32_16x16x32_bf16 v[44:47], v[226:229], v[234:237], v[44:47]
	v_mfma_f32_16x16x32_bf16 v[8:11], v[226:229], v[238:241], v[8:11]
	v_mfma_f32_16x16x32_bf16 v[12:15], v[226:229], v[242:245], v[12:15]
	s_xor_b32 s55, s55, 1
	s_nop 7
	s_nop 7
	v_permlane16_swap_b32_e32 v112, v116
	v_permlane16_swap_b32_e32 v113, v117
	v_permlane16_swap_b32_e32 v114, v118
	v_permlane16_swap_b32_e32 v115, v119
	v_permlane16_swap_b32_e32 v120, v124
	v_permlane16_swap_b32_e32 v121, v125
	v_permlane16_swap_b32_e32 v122, v126
	v_permlane16_swap_b32_e32 v123, v127
	v_permlane16_swap_b32_e32 v80, v84
	v_permlane16_swap_b32_e32 v81, v85
	v_permlane16_swap_b32_e32 v82, v86
	v_permlane16_swap_b32_e32 v83, v87
	v_permlane16_swap_b32_e32 v88, v92
	v_permlane16_swap_b32_e32 v89, v93
	v_permlane16_swap_b32_e32 v90, v94
	v_permlane16_swap_b32_e32 v91, v95
	v_permlane16_swap_b32_e32 v48, v52
	v_permlane16_swap_b32_e32 v49, v53
	v_permlane16_swap_b32_e32 v50, v54
	v_permlane16_swap_b32_e32 v51, v55
	v_permlane16_swap_b32_e32 v56, v60
	v_permlane16_swap_b32_e32 v57, v61
	v_permlane16_swap_b32_e32 v58, v62
	v_permlane16_swap_b32_e32 v59, v63
	v_permlane16_swap_b32_e32 v16, v20
	v_permlane16_swap_b32_e32 v17, v21
	v_permlane16_swap_b32_e32 v18, v22
	v_permlane16_swap_b32_e32 v19, v23
	v_permlane16_swap_b32_e32 v24, v28
	v_permlane16_swap_b32_e32 v25, v29
	v_permlane16_swap_b32_e32 v26, v30
	v_permlane16_swap_b32_e32 v27, v31
	v_permlane16_swap_b32_e32 v96, v100
	v_permlane16_swap_b32_e32 v97, v101
	v_permlane16_swap_b32_e32 v98, v102
	v_permlane16_swap_b32_e32 v99, v103
	v_permlane16_swap_b32_e32 v104, v108
	v_permlane16_swap_b32_e32 v105, v109
	v_permlane16_swap_b32_e32 v106, v110
	v_permlane16_swap_b32_e32 v107, v111
	v_permlane16_swap_b32_e32 v64, v68
	v_permlane16_swap_b32_e32 v65, v69
	v_permlane16_swap_b32_e32 v66, v70
	v_permlane16_swap_b32_e32 v67, v71
	v_permlane16_swap_b32_e32 v72, v76
	v_permlane16_swap_b32_e32 v73, v77
	v_permlane16_swap_b32_e32 v74, v78
	v_permlane16_swap_b32_e32 v75, v79
	v_permlane16_swap_b32_e32 v32, v36
	v_permlane16_swap_b32_e32 v33, v37
	v_permlane16_swap_b32_e32 v34, v38
	v_permlane16_swap_b32_e32 v35, v39
	v_permlane16_swap_b32_e32 v40, v44
	v_permlane16_swap_b32_e32 v41, v45
	v_permlane16_swap_b32_e32 v42, v46
	v_permlane16_swap_b32_e32 v43, v47
	v_permlane16_swap_b32_e32 v0, v4
	v_permlane16_swap_b32_e32 v1, v5
	v_permlane16_swap_b32_e32 v2, v6
	v_permlane16_swap_b32_e32 v3, v7
	v_permlane16_swap_b32_e32 v8, v12
	v_permlane16_swap_b32_e32 v9, v13
	v_permlane16_swap_b32_e32 v10, v14
	v_permlane16_swap_b32_e32 v11, v15
	v_permlane32_swap_b32_e32 v112, v116
	v_permlane32_swap_b32_e32 v113, v117
	v_permlane32_swap_b32_e32 v114, v118
	v_permlane32_swap_b32_e32 v115, v119
	v_permlane32_swap_b32_e32 v120, v124
	v_permlane32_swap_b32_e32 v121, v125
	v_permlane32_swap_b32_e32 v122, v126
	v_permlane32_swap_b32_e32 v123, v127
	v_permlane32_swap_b32_e32 v80, v84
	v_permlane32_swap_b32_e32 v81, v85
	v_permlane32_swap_b32_e32 v82, v86
	v_permlane32_swap_b32_e32 v83, v87
	v_permlane32_swap_b32_e32 v88, v92
	v_permlane32_swap_b32_e32 v89, v93
	v_permlane32_swap_b32_e32 v90, v94
	v_permlane32_swap_b32_e32 v91, v95
	v_permlane32_swap_b32_e32 v48, v52
	v_permlane32_swap_b32_e32 v49, v53
	v_permlane32_swap_b32_e32 v50, v54
	v_permlane32_swap_b32_e32 v51, v55
	v_permlane32_swap_b32_e32 v56, v60
	v_permlane32_swap_b32_e32 v57, v61
	v_permlane32_swap_b32_e32 v58, v62
	v_permlane32_swap_b32_e32 v59, v63
	v_permlane32_swap_b32_e32 v16, v20
	v_permlane32_swap_b32_e32 v17, v21
	v_permlane32_swap_b32_e32 v18, v22
	v_permlane32_swap_b32_e32 v19, v23
	v_permlane32_swap_b32_e32 v24, v28
	v_permlane32_swap_b32_e32 v25, v29
	v_permlane32_swap_b32_e32 v26, v30
	v_permlane32_swap_b32_e32 v27, v31
	v_permlane32_swap_b32_e32 v96, v100
	v_permlane32_swap_b32_e32 v97, v101
	v_permlane32_swap_b32_e32 v98, v102
	v_permlane32_swap_b32_e32 v99, v103
	v_permlane32_swap_b32_e32 v104, v108
	v_permlane32_swap_b32_e32 v105, v109
	v_permlane32_swap_b32_e32 v106, v110
	v_permlane32_swap_b32_e32 v107, v111
	v_permlane32_swap_b32_e32 v64, v68
	v_permlane32_swap_b32_e32 v65, v69
	v_permlane32_swap_b32_e32 v66, v70
	v_permlane32_swap_b32_e32 v67, v71
	v_permlane32_swap_b32_e32 v72, v76
	v_permlane32_swap_b32_e32 v73, v77
	v_permlane32_swap_b32_e32 v74, v78
	v_permlane32_swap_b32_e32 v75, v79
	v_permlane32_swap_b32_e32 v32, v36
	v_permlane32_swap_b32_e32 v33, v37
	v_permlane32_swap_b32_e32 v34, v38
	v_permlane32_swap_b32_e32 v35, v39
	v_permlane32_swap_b32_e32 v40, v44
	v_permlane32_swap_b32_e32 v41, v45
	v_permlane32_swap_b32_e32 v42, v46
	v_permlane32_swap_b32_e32 v43, v47
	v_permlane32_swap_b32_e32 v0, v4
	v_permlane32_swap_b32_e32 v1, v5
	v_permlane32_swap_b32_e32 v2, v6
	v_permlane32_swap_b32_e32 v3, v7
	v_permlane32_swap_b32_e32 v8, v12
	v_permlane32_swap_b32_e32 v9, v13
	v_permlane32_swap_b32_e32 v10, v14
	v_permlane32_swap_b32_e32 v11, v15
	s_and_saveexec_b64 s[6:7], vcc
	s_cbranch_execz .LBB0_52
	s_mov_b64 s[34:35], exec
	v_mbcnt_lo_u32_b32 v144, s34, 0
	v_mbcnt_hi_u32_b32 v144, s35, v144
	v_cmp_eq_u32_e64 s[38:39], 0, v144
	s_and_saveexec_b64 s[0:1], s[38:39]
	s_cbranch_execz .LBB0_51
	s_bcnt1_i32_b64 s9, s[34:35]
	v_mov_b32_e32 v145, s9
	global_atomic_add v145, v161, v145, s[30:31] offset:256 sc0

; __device__ __forceinline__ unsigned xb_xcc_id() { return (unsigned)__builtin_amdgcn_s_getreg((3 << 11) | 20) & 0xFu; }
; __device__ __forceinline__ void h_tile(WideCtx& c, const u16* __restrict__ A, int lda, int M, int m0, const u16* __restrict__ W, int ldw, int n0) {
; #pragma unroll
;   for (int i = 0; i < 2; ++i) {
;     const int q = c.tid + 256 * i, row = q >> 2, ch = (q & 3) ^ ((row >> 2) & 3);
;     c.wp[i] = W + (size_t)(n0 + row) * ldw + ch * 8;
;   }
; #pragma unroll
;   for (int i = 0; i < 4; ++i) {
;     const int q = c.tid + 256 * i, row = q >> 2, ch = (q & 3) ^ ((row >> 2) & 3);
;     int ar = m0 + row; ar = ar < M ? ar : M - 1;
;     c.ap[i] = A + (size_t)ar * lda + ch * 8;
;   }
; }
; __device__ __forceinline__ void h_stage(const WideCtx& c, int kt) {
;   const unsigned sb = c.lds0 + (kt & 1) * 24576;
; #pragma unroll
;   for (int i = 0; i < 2; ++i) glds16(c.wp[i] + kt * 32, sb + i * 4096);
; #pragma unroll
;   for (int i = 0; i < 4; ++i) glds16(c.ap[i] + kt * 32, sb + 8192 + i * 4096);
; }
; template <class F>
; __device__ __forceinline__ void gemm_phase_w(const u16* A, int lda, int M, const u16* W, int K, int N, char* lds, int* ctr, F&& epi) {
;   const int nN = N >> 7, nM = (M + 255) >> 8, nt = nN * nM, nk = K >> 5;
;   const int xcd = (int)xb_xcc_id() & 7;
;   const int tq = nt >> 3, trm = nt & 7;
;   const int tstart = xcd < trm ? xcd * (tq + 1) : trm * (tq + 1) + (xcd - trm) * tq;
;   const int tcnt = tq + (xcd < trm ? 1 : 0);
;   auto decode = [&](int off, int& tm, int& tn) {
;     const int id = tstart + off, nig = 4 * nN, grp = id / nig, fm = grp * 4;
;     const int gsz = (nM - fm) < 4 ? (nM - fm) : 4, idl = id - grp * nig;
;     tm = fm + idl % gsz; tn = idl / gsz;
;   };
;   WideCtx c;
;   h_init(c, lds);
;   const int wave = c.tid >> 6;
;   volatile int* bw = (volatile int*)(lds + 65536);
;   int* myctr = ctr + xcd;
;   int par = 0;
;   if (c.tid == 0) bw[2] = atomicAdd(myctr, 1);
;   asm volatile("s_waitcnt vmcnt(0) lgkmcnt(0)" ::: "memory");
;   __builtin_amdgcn_s_barrier();
;   int off = bw[2];
;   int tm = 0, tn = 0;
;   if (off < tcnt) { decode(off, tm, tn); h_tile(c, A, lda, M, tm * 256, W, K, tn * 128); h_stage(c, 0); }
.LBB0_82:
	s_or_b64 exec, exec, s[34:35]
	s_mov_b64 s[0:1], src_shared_base
	v_cndmask_b32_e64 v1, 0, 1, s[6:7]
	s_waitcnt vmcnt(0)
	v_mov_b32_e32 v163, s1
	v_add_u32_e32 v156, s24, v1
	s_waitcnt vmcnt(0) lgkmcnt(0)
	s_barrier
	flat_load_dword v1, v[162:163] sc0 sc1
	s_waitcnt vmcnt(0) lgkmcnt(0)
	v_cmp_lt_i32_e64 s[38:39], v1, v156
	s_and_saveexec_b64 s[42:43], s[38:39]
	s_cbranch_execz .LBB0_101
	v_and_b32_e32 v2, 31, v0
	v_lshrrev_b32_e32 v3, 1, v0
	s_mov_b32 s0, 0x3ffffc0
	v_and_or_b32 v2, v3, s0, v2
	v_lshlrev_b32_e32 v158, 6, v2
	v_add_u32_e32 v2, s11, v1
	s_mov_b32 s1, 0x2e8ba2e9
	v_lshlrev_b32_e32 v3, 6, v0
	v_mul_hi_i32 v1, v2, s1
	v_and_b32_e32 v157, 0x17c0, v3
	v_lshrrev_b32_e32 v3, 31, v1
	v_ashrrev_i32_e32 v1, 5, v1
	v_add_u32_e32 v1, v1, v3
	v_lshlrev_b32_e32 v7, 2, v1
	v_sub_u32_e32 v3, s10, v7
	v_min_i32_e32 v8, 4, v3
	v_sub_u32_e32 v3, 0, v8
	v_max_i32_e32 v9, v8, v3
	v_cvt_f32_u32_e32 v10, v9
	s_lshl_b32 s0, s9, 4
	s_and_b32 s48, s0, 0xfffffc00
	s_movk_i32 s0, 0xff50
	v_mad_u64_u32 v[2:3], s[0:1], v1, s0, v[2:3]
	v_rcp_iflag_f32_e32 v1, v10
	v_sub_u32_e32 v11, 0, v9
	v_sub_u32_e32 v10, 0, v2
	v_max_i32_e32 v10, v2, v10
	v_mul_f32_e32 v1, 0x4f7ffffe, v1
	v_cvt_u32_f32_e32 v1, v1
	v_xor_b32_e32 v3, v2, v8
	v_ashrrev_i32_e32 v3, 31, v3
	s_load_dwordx2 s[0:1], s[64:65], 0x150
	v_mul_lo_u32 v11, v11, v1
	v_mul_hi_u32 v11, v1, v11
	v_add_u32_e32 v1, v1, v11
	v_mul_hi_u32 v1, v10, v1
	v_mul_lo_u32 v11, v1, v9
	v_sub_u32_e32 v10, v10, v11
	v_add_u32_e32 v11, 1, v1
	v_cmp_ge_u32_e64 s[38:39], v10, v9
	v_ashrrev_i32_e32 v159, 2, v0
	s_add_i32 s50, s62, -1
	v_cndmask_b32_e64 v1, v1, v11, s[38:39]
	v_sub_u32_e32 v11, v10, v9
	v_cndmask_b32_e64 v10, v10, v11, s[38:39]
	v_add_u32_e32 v11, 1, v1
	v_cmp_ge_u32_e64 s[38:39], v10, v9
	s_add_i32 s51, s48, 0x1000
	s_add_i32 s52, s48, 0x2000
	v_cndmask_b32_e64 v1, v1, v11, s[38:39]
	v_xor_b32_e32 v1, v1, v3
	v_sub_u32_e32 v153, v1, v3
	v_mul_lo_u32 v1, v153, v8
	v_sub_u32_e32 v1, v2, v1
	v_lshrrev_b32_e32 v2, 4, v0
	v_and_b32_e32 v250, 1, v2
	v_lshlrev_b32_e32 v250, 1, v250
	v_xor_b32_e32 v2, v2, v250
	v_xor_b32_e32 v2, v2, v0
	v_add_u32_e32 v154, v1, v7
	v_lshlrev_b32_e32 v7, 7, v153
	v_lshlrev_b32_e32 v2, 4, v2
	v_and_b32_e32 v160, 48, v2
	v_add_u32_e32 v2, v7, v159
	v_ashrrev_i32_e32 v3, 31, v2
	s_waitcnt lgkmcnt(0)
	v_lshl_add_u64 v[128:129], s[0:1], 0, v[160:161]
	v_lshlrev_b64 v[2:3], 11, v[2:3]
	v_lshl_add_u64 v[132:133], v[128:129], 0, v[2:3]
	v_add_u32_e32 v2, 0x100, v0
	v_ashrrev_i32_e32 v163, 2, v2
	v_add_u32_e32 v2, v7, v163
	v_ashrrev_i32_e32 v3, 31, v2
	s_load_dwordx2 s[0:1], s[64:65], 0x1c0
	v_lshlrev_b32_e32 v1, 8, v154
	v_lshlrev_b64 v[2:3], 11, v[2:3]
	v_lshl_add_u64 v[134:135], v[128:129], 0, v[2:3]
	v_add_u32_e32 v2, v1, v159
	v_min_i32_e32 v2, s50, v2
	v_ashrrev_i32_e32 v3, 31, v2
	s_waitcnt lgkmcnt(0)
	v_lshl_add_u64 v[130:131], s[0:1], 0, v[160:161]
	v_lshlrev_b64 v[2:3], 11, v[2:3]
	v_lshl_add_u64 v[136:137], v[130:131], 0, v[2:3]
	v_add_u32_e32 v2, v1, v163
	v_min_i32_e32 v2, s50, v2
	v_ashrrev_i32_e32 v3, 31, v2
	v_lshlrev_b64 v[2:3], 11, v[2:3]
	v_lshl_add_u64 v[138:139], v[130:131], 0, v[2:3]
	v_add_u32_e32 v2, 0x200, v0
	v_ashrrev_i32_e32 v164, 2, v2
	v_add_u32_e32 v2, v1, v164
	v_min_i32_e32 v2, s50, v2
	v_ashrrev_i32_e32 v3, 31, v2
	v_lshlrev_b64 v[2:3], 11, v[2:3]
	v_lshl_add_u64 v[140:141], v[130:131], 0, v[2:3]
	v_add_u32_e32 v2, 0x300, v0
	v_ashrrev_i32_e32 v165, 2, v2
	s_mov_b32 s0, m0
	s_mov_b32 m0, s48
	s_nop 0
	global_load_lds_dwordx4 v[132:133], off
	s_mov_b32 m0, s0
	v_add_u32_e32 v1, v1, v165
	s_mov_b32 s0, m0
	s_mov_b32 m0, s51
	s_nop 0
	global_load_lds_dwordx4 v[134:135], off
	s_mov_b32 m0, s0
	v_min_i32_e32 v2, s50, v1
	s_mov_b32 s0, m0
	s_mov_b32 m0, s52
	s_nop 0
	global_load_lds_dwordx4 v[136:137], off
	s_mov_b32 m0, s0
	v_ashrrev_i32_e32 v3, 31, v2
	s_add_i32 s53, s48, 0x3000
	s_mov_b32 s0, m0
	s_mov_b32 m0, s53
	s_nop 0
	global_load_lds_dwordx4 v[138:139], off
	s_mov_b32 m0, s0
	v_lshlrev_b64 v[2:3], 11, v[2:3]
	s_add_i32 s54, s48, 0x4000
	s_mov_b32 s0, m0
	s_mov_b32 m0, s54
	s_nop 0
	global_load_lds_dwordx4 v[140:141], off
	s_mov_b32 m0, s0
	v_lshl_add_u64 v[142:143], v[130:131], 0, v[2:3]
	s_add_i32 s55, s48, 0x5000
	s_mov_b32 s0, m0
	s_mov_b32 m0, s55
	s_nop 0
	global_load_lds_dwordx4 v[142:143], off
	s_mov_b32 m0, s0
	s_add_i32 m0, s48, 0x5fc0
	s_nop 0
	global_load_lds_dwordx4 v[132:133], off offset:64
	s_add_i32 m0, s51, 0x5fc0
	s_nop 0
	global_load_lds_dwordx4 v[134:135], off offset:64
	s_add_i32 m0, s52, 0x5fc0
	s_nop 0
	global_load_lds_dwordx4 v[136:137], off offset:64
	s_add_i32 m0, s53, 0x5fc0
	s_nop 0
	global_load_lds_dwordx4 v[138:139], off offset:64
	s_add_i32 m0, s54, 0x5fc0
	s_nop 0
	global_load_lds_dwordx4 v[140:141], off offset:64
	s_add_i32 m0, s55, 0x5fc0
	s_nop 0
	global_load_lds_dwordx4 v[142:143], off offset:64
	s_load_dwordx2 s[44:45], s[64:65], 0x230
	v_bfe_u32 v4, v0, 5, 1
	v_lshrrev_b32_e32 v5, 2, v0
	v_bfe_u32 v6, v0, 2, 2
	v_bitop3_b32 v1, v5, v4, 3 bitop3:0x6c
	v_lshlrev_b32_e32 v166, 4, v1
	v_bitop3_b32 v1, v4, v6, 2 bitop3:0x36
	v_and_b32_e32 v168, 64, v0
	v_ashrrev_i32_e32 v0, 1, v0
	s_mov_b32 s49, 0
	v_lshlrev_b32_e32 v167, 4, v1
	v_and_b32_e32 v169, 0xffffffc0, v0
	s_mov_b64 s[46:47], 0
	s_branch .LBB0_85

; __device__ __forceinline__ void h_main(f32x16 (&acc0)[2][2], f32x16 (&acc1)[2][2], const WideCtx& c, int nk, char* lds) {
;   const int h = c.h;
;   for (int kt = 0; kt < nk; ++kt) {
;     asm volatile("s_waitcnt vmcnt(0)" ::: "memory");
;     __builtin_amdgcn_s_barrier();
;     if (kt + 1 < nk) h_stage(c, kt + 1);
;     const char* st = lds + (kt & 1) * 24576;
; #pragma unroll
;     for (int ks = 0; ks < 2; ++ks) {
;       bf16x8 wf[2], a0[2], a1[2];
; #pragma unroll
;       for (int b = 0; b < 2; ++b) {
;         wf[b] = *(const bf16x8*)(st + c.wro[b] + (((ks * 2 + h) ^ c.wsw[b]) << 4));
;         a0[b] = *(const bf16x8*)(st + c.aro[0][b] + (((ks * 2 + h) ^ c.asw[0][b]) << 4));
;         a1[b] = *(const bf16x8*)(st + c.aro[1][b] + (((ks * 2 + h) ^ c.asw[1][b]) << 4));
;       }
; #pragma unroll
;       for (int nb = 0; nb < 2; ++nb)
; #pragma unroll
;         for (int tb = 0; tb < 2; ++tb) {
;           acc0[nb][tb] = __builtin_amdgcn_mfma_f32_32x32x16_bf16(wf[nb], a0[tb], acc0[nb][tb], 0, 0, 0);
;           acc1[nb][tb] = __builtin_amdgcn_mfma_f32_32x32x16_bf16(wf[nb], a1[tb], acc1[nb][tb], 0, 0, 0);
;         }
.LBB0_85:
	v_mov_b32_e32 v64, 0
	v_mov_b32_e32 v160, v154
	v_mov_b32_e32 v170, v153
	s_load_dwordx2 s[0:1], s[64:65], 0x120
	s_waitcnt lgkmcnt(0)
	v_subrev_u32_e32 v144, s0, v142
	v_subrev_u32_e32 v146, s0, v140
	v_subrev_u32_e32 v148, s0, v138
	v_subrev_u32_e32 v150, s0, v136
	v_subrev_u32_e32 v152, s0, v134
	v_subrev_u32_e32 v154, s0, v132
	s_add_u32 s0, s0, 0x80
	s_addc_u32 s1, s1, 0
	s_mov_b32 s9, 2
	s_mov_b32 s6, 0
	v_and_b32_e32 v250, 15, v204
	v_lshlrev_b32_e32 v250, 6, v250
	v_bfe_u32 v251, v204, 2, 2
	v_and_b32_e32 v247, 1, v251
	v_lshlrev_b32_e32 v247, 1, v247
	v_xor_b32_e32 v251, v251, v247
	v_bfe_u32 v247, v204, 4, 2
	v_xor_b32_e32 v251, v251, v247
	v_lshl_or_b32 v250, v251, 4, v250
	v_bfe_u32 v247, v204, 6, 1
	v_lshl_or_b32 v248, v247, 12, v250
	v_lshrrev_b32_e32 v247, 7, v204
	v_lshl_or_b32 v249, v247, 12, v250
	v_mov_b32_e32 v65, v64
	v_mov_b32_e32 v66, v64
	v_mov_b32_e32 v67, v64
	v_mov_b32_e32 v68, v64
	v_mov_b32_e32 v69, v64
	v_mov_b32_e32 v70, v64
	v_mov_b32_e32 v71, v64
	v_mov_b32_e32 v72, v64
	v_mov_b32_e32 v73, v64
	v_mov_b32_e32 v74, v64
	v_mov_b32_e32 v75, v64
	v_mov_b32_e32 v76, v64
	v_mov_b32_e32 v77, v64
	v_mov_b32_e32 v78, v64
	v_mov_b32_e32 v79, v64
	v_mov_b32_e32 v96, v64
	v_mov_b32_e32 v97, v64
	v_mov_b32_e32 v98, v64
	v_mov_b32_e32 v99, v64
	v_mov_b32_e32 v100, v64
	v_mov_b32_e32 v101, v64
	v_mov_b32_e32 v102, v64
	v_mov_b32_e32 v103, v64
	v_mov_b32_e32 v104, v64
	v_mov_b32_e32 v105, v64
	v_mov_b32_e32 v106, v64
	v_mov_b32_e32 v107, v64
	v_mov_b32_e32 v108, v64
	v_mov_b32_e32 v109, v64
	v_mov_b32_e32 v110, v64
	v_mov_b32_e32 v111, v64
	v_mov_b32_e32 v80, v64
	v_mov_b32_e32 v81, v64
	v_mov_b32_e32 v82, v64
	v_mov_b32_e32 v83, v64
	v_mov_b32_e32 v84, v64
	v_mov_b32_e32 v85, v64
	v_mov_b32_e32 v86, v64
	v_mov_b32_e32 v87, v64
	v_mov_b32_e32 v88, v64
	v_mov_b32_e32 v89, v64
	v_mov_b32_e32 v90, v64
	v_mov_b32_e32 v91, v64
	v_mov_b32_e32 v92, v64
	v_mov_b32_e32 v93, v64
	v_mov_b32_e32 v94, v64
	v_mov_b32_e32 v95, v64
	v_mov_b32_e32 v112, v64
	v_mov_b32_e32 v113, v64
	v_mov_b32_e32 v114, v64
	v_mov_b32_e32 v115, v64
	v_mov_b32_e32 v116, v64
	v_mov_b32_e32 v117, v64
	v_mov_b32_e32 v118, v64
	v_mov_b32_e32 v119, v64
	v_mov_b32_e32 v120, v64
	v_mov_b32_e32 v121, v64
	v_mov_b32_e32 v122, v64
	v_mov_b32_e32 v123, v64
	v_mov_b32_e32 v124, v64
	v_mov_b32_e32 v125, v64
	v_mov_b32_e32 v126, v64
	v_mov_b32_e32 v127, v64
	v_mov_b32_e32 v0, v64
	v_mov_b32_e32 v1, v64
	v_mov_b32_e32 v2, v64
	v_mov_b32_e32 v3, v64
	v_mov_b32_e32 v4, v64
	v_mov_b32_e32 v5, v64
	v_mov_b32_e32 v6, v64
	v_mov_b32_e32 v7, v64
	v_mov_b32_e32 v8, v64
	v_mov_b32_e32 v9, v64
	v_mov_b32_e32 v10, v64
	v_mov_b32_e32 v11, v64
	v_mov_b32_e32 v12, v64
	v_mov_b32_e32 v13, v64
	v_mov_b32_e32 v14, v64
	v_mov_b32_e32 v15, v64
	v_mov_b32_e32 v32, v64
	v_mov_b32_e32 v33, v64
	v_mov_b32_e32 v34, v64
	v_mov_b32_e32 v35, v64
	v_mov_b32_e32 v36, v64
	v_mov_b32_e32 v37, v64
	v_mov_b32_e32 v38, v64
	v_mov_b32_e32 v39, v64
	v_mov_b32_e32 v40, v64
	v_mov_b32_e32 v41, v64
	v_mov_b32_e32 v42, v64
	v_mov_b32_e32 v43, v64
	v_mov_b32_e32 v44, v64
	v_mov_b32_e32 v45, v64
	v_mov_b32_e32 v46, v64
	v_mov_b32_e32 v47, v64
	v_mov_b32_e32 v16, v64
	v_mov_b32_e32 v17, v64
	v_mov_b32_e32 v18, v64
	v_mov_b32_e32 v19, v64
	v_mov_b32_e32 v20, v64
	v_mov_b32_e32 v21, v64
	v_mov_b32_e32 v22, v64
	v_mov_b32_e32 v23, v64
	v_mov_b32_e32 v24, v64
	v_mov_b32_e32 v25, v64
	v_mov_b32_e32 v26, v64
	v_mov_b32_e32 v27, v64
	v_mov_b32_e32 v28, v64
	v_mov_b32_e32 v29, v64
	v_mov_b32_e32 v30, v64
	v_mov_b32_e32 v31, v64
	v_mov_b32_e32 v48, v64
	v_mov_b32_e32 v49, v64
	v_mov_b32_e32 v50, v64
	v_mov_b32_e32 v51, v64
	v_mov_b32_e32 v52, v64
	v_mov_b32_e32 v53, v64
	v_mov_b32_e32 v54, v64
	v_mov_b32_e32 v55, v64
	v_mov_b32_e32 v56, v64
	v_mov_b32_e32 v57, v64
	v_mov_b32_e32 v58, v64
	v_mov_b32_e32 v59, v64
	v_mov_b32_e32 v60, v64
	v_mov_b32_e32 v61, v64
	v_mov_b32_e32 v62, v64
	v_mov_b32_e32 v63, v64
.LBB0_86:
	s_waitcnt vmcnt(6)
	s_barrier
	v_add_u32_e32 v171, s6, v248
	v_add_u32_e32 v196, s6, v249
	ds_read_b128 v[172:175], v171
	ds_read_b128 v[176:179], v196 offset:8192
	ds_read_b128 v[188:191], v196 offset:9216
	ds_read_b128 v[180:183], v196 offset:10240
	ds_read_b128 v[192:195], v196 offset:11264
	ds_read_b128 v[230:233], v196 offset:16384
	ds_read_b128 v[234:237], v196 offset:17408
	ds_read_b128 v[238:241], v196 offset:18432
	ds_read_b128 v[242:245], v196 offset:19456
	ds_read_b128 v[184:187], v171 offset:1024
	ds_read_b128 v[222:225], v171 offset:2048
	ds_read_b128 v[226:229], v171 offset:3072
	s_add_i32 s7, s6, 0xffffa000
	s_cmp_eq_u32 s6, 0
	s_cselect_b32 s7, 0xc000, s7
	s_add_i32 m0, s7, s48
	s_add_i32 s7, s6, 0x6000
	global_load_lds_dwordx4 v154, s[0:1]
	s_add_i32 m0, m0, 0x1000
	s_cmp_eq_u32 s6, 0xc000
	global_load_lds_dwordx4 v152, s[0:1]
	s_cselect_b32 s6, 0, s7
	s_add_i32 m0, m0, 0x1000
	s_waitcnt lgkmcnt(10)
	v_mfma_f32_16x16x32_bf16 v[112:115], v[172:175], v[176:179], v[112:115]
	global_load_lds_dwordx4 v150, s[0:1]
	s_add_i32 m0, m0, 0x1000
	s_waitcnt lgkmcnt(9)
	v_mfma_f32_16x16x32_bf16 v[116:119], v[172:175], v[188:191], v[116:119]
	global_load_lds_dwordx4 v148, s[0:1]
	s_add_i32 m0, m0, 0x1000
	s_waitcnt lgkmcnt(8)
	v_mfma_f32_16x16x32_bf16 v[80:83], v[172:175], v[180:183], v[80:83]
	global_load_lds_dwordx4 v146, s[0:1]
	s_add_i32 m0, m0, 0x1000
	s_waitcnt lgkmcnt(7)
	v_mfma_f32_16x16x32_bf16 v[84:87], v[172:175], v[192:195], v[84:87]
	global_load_lds_dwordx4 v144, s[0:1]
	s_add_u32 s0, s0, 64
	s_addc_u32 s1, s1, 0
	s_waitcnt lgkmcnt(6)
	v_mfma_f32_16x16x32_bf16 v[48:51], v[172:175], v[230:233], v[48:51]
	s_waitcnt lgkmcnt(5)
	v_mfma_f32_16x16x32_bf16 v[52:55], v[172:175], v[234:237], v[52:55]
	s_waitcnt lgkmcnt(4)
; __device__ __forceinline__ void h_main(f32x16 (&acc0)[2][2], f32x16 (&acc1)[2][2], const WideCtx& c, int nk, char* lds) {
;   const int h = c.h;
;   for (int kt = 0; kt < nk; ++kt) {
;     asm volatile("s_waitcnt vmcnt(0)" ::: "memory");
;     __builtin_amdgcn_s_barrier();
;     if (kt + 1 < nk) h_stage(c, kt + 1);
;     const char* st = lds + (kt & 1) * 24576;
; #pragma unroll
;     for (int ks = 0; ks < 2; ++ks) {
;       bf16x8 wf[2], a0[2], a1[2];
; #pragma unroll
;       for (int b = 0; b < 2; ++b) {
;         wf[b] = *(const bf16x8*)(st + c.wro[b] + (((ks * 2 + h) ^ c.wsw[b]) << 4));
;         a0[b] = *(const bf16x8*)(st + c.aro[0][b] + (((ks * 2 + h) ^ c.asw[0][b]) << 4));
;         a1[b] = *(const bf16x8*)(st + c.aro[1][b] + (((ks * 2 + h) ^ c.asw[1][b]) << 4));
;       }
; #pragma unroll
;       for (int nb = 0; nb < 2; ++nb)
; #pragma unroll
;         for (int tb = 0; tb < 2; ++tb) {
;           acc0[nb][tb] = __builtin_amdgcn_mfma_f32_32x32x16_bf16(wf[nb], a0[tb], acc0[nb][tb], 0, 0, 0);
;           acc1[nb][tb] = __builtin_amdgcn_mfma_f32_32x32x16_bf16(wf[nb], a1[tb], acc1[nb][tb], 0, 0, 0);
;         }
;     }
;   }
; }
	v_mfma_f32_16x16x32_bf16 v[16:19], v[172:175], v[238:241], v[16:19]
	s_waitcnt lgkmcnt(3)
	v_mfma_f32_16x16x32_bf16 v[20:23], v[172:175], v[242:245], v[20:23]
	s_waitcnt lgkmcnt(2)
	v_mfma_f32_16x16x32_bf16 v[120:123], v[184:187], v[176:179], v[120:123]
	v_mfma_f32_16x16x32_bf16 v[124:127], v[184:187], v[188:191], v[124:127]
	v_mfma_f32_16x16x32_bf16 v[88:91], v[184:187], v[180:183], v[88:91]
	v_mfma_f32_16x16x32_bf16 v[92:95], v[184:187], v[192:195], v[92:95]
	v_mfma_f32_16x16x32_bf16 v[56:59], v[184:187], v[230:233], v[56:59]
	v_mfma_f32_16x16x32_bf16 v[60:63], v[184:187], v[234:237], v[60:63]
	v_mfma_f32_16x16x32_bf16 v[24:27], v[184:187], v[238:241], v[24:27]
	v_mfma_f32_16x16x32_bf16 v[28:31], v[184:187], v[242:245], v[28:31]
	s_waitcnt lgkmcnt(1)
	v_mfma_f32_16x16x32_bf16 v[96:99], v[222:225], v[176:179], v[96:99]
	v_mfma_f32_16x16x32_bf16 v[100:103], v[222:225], v[188:191], v[100:103]
	v_mfma_f32_16x16x32_bf16 v[64:67], v[222:225], v[180:183], v[64:67]
	v_mfma_f32_16x16x32_bf16 v[68:71], v[222:225], v[192:195], v[68:71]
	v_mfma_f32_16x16x32_bf16 v[32:35], v[222:225], v[230:233], v[32:35]
	v_mfma_f32_16x16x32_bf16 v[36:39], v[222:225], v[234:237], v[36:39]
	v_mfma_f32_16x16x32_bf16 v[0:3], v[222:225], v[238:241], v[0:3]
	v_mfma_f32_16x16x32_bf16 v[4:7], v[222:225], v[242:245], v[4:7]
	s_waitcnt lgkmcnt(0)
	v_mfma_f32_16x16x32_bf16 v[104:107], v[226:229], v[176:179], v[104:107]
	v_mfma_f32_16x16x32_bf16 v[108:111], v[226:229], v[188:191], v[108:111]
	v_mfma_f32_16x16x32_bf16 v[72:75], v[226:229], v[180:183], v[72:75]
	v_mfma_f32_16x16x32_bf16 v[76:79], v[226:229], v[192:195], v[76:79]
	v_mfma_f32_16x16x32_bf16 v[40:43], v[226:229], v[230:233], v[40:43]
	v_mfma_f32_16x16x32_bf16 v[44:47], v[226:229], v[234:237], v[44:47]
	v_mfma_f32_16x16x32_bf16 v[8:11], v[226:229], v[238:241], v[8:11]
	v_mfma_f32_16x16x32_bf16 v[12:15], v[226:229], v[242:245], v[12:15]
	s_add_i32 s9, s9, 1
	s_cmp_eq_u32 s9, 32
	s_cbranch_scc0 .LBB0_86
	s_waitcnt vmcnt(6)
	s_barrier
	v_add_u32_e32 v171, s6, v248
	v_add_u32_e32 v196, s6, v249
	ds_read_b128 v[172:175], v171
	ds_read_b128 v[176:179], v196 offset:8192
	ds_read_b128 v[188:191], v196 offset:9216
	ds_read_b128 v[180:183], v196 offset:10240
	ds_read_b128 v[192:195], v196 offset:11264
	ds_read_b128 v[230:233], v196 offset:16384
	ds_read_b128 v[234:237], v196 offset:17408
	ds_read_b128 v[238:241], v196 offset:18432
	ds_read_b128 v[242:245], v196 offset:19456
	ds_read_b128 v[184:187], v171 offset:1024
	ds_read_b128 v[222:225], v171 offset:2048
	ds_read_b128 v[226:229], v171 offset:3072
	s_add_i32 s7, s6, 0x6000
	s_cmp_eq_u32 s6, 0xc000
	s_cselect_b32 s6, 0, s7
	s_waitcnt lgkmcnt(10)
	v_mfma_f32_16x16x32_bf16 v[112:115], v[172:175], v[176:179], v[112:115]
	s_waitcnt lgkmcnt(9)
	v_mfma_f32_16x16x32_bf16 v[116:119], v[172:175], v[188:191], v[116:119]
	s_waitcnt lgkmcnt(8)
	v_mfma_f32_16x16x32_bf16 v[80:83], v[172:175], v[180:183], v[80:83]
	s_waitcnt lgkmcnt(7)
	v_mfma_f32_16x16x32_bf16 v[84:87], v[172:175], v[192:195], v[84:87]
	s_waitcnt lgkmcnt(6)
	v_mfma_f32_16x16x32_bf16 v[48:51], v[172:175], v[230:233], v[48:51]
	s_waitcnt lgkmcnt(5)
	v_mfma_f32_16x16x32_bf16 v[52:55], v[172:175], v[234:237], v[52:55]
	s_waitcnt lgkmcnt(4)
	v_mfma_f32_16x16x32_bf16 v[16:19], v[172:175], v[238:241], v[16:19]
	s_waitcnt lgkmcnt(3)
	v_mfma_f32_16x16x32_bf16 v[20:23], v[172:175], v[242:245], v[20:23]
	s_waitcnt lgkmcnt(2)
	v_mfma_f32_16x16x32_bf16 v[120:123], v[184:187], v[176:179], v[120:123]
	v_mfma_f32_16x16x32_bf16 v[124:127], v[184:187], v[188:191], v[124:127]
	v_mfma_f32_16x16x32_bf16 v[88:91], v[184:187], v[180:183], v[88:91]
	v_mfma_f32_16x16x32_bf16 v[92:95], v[184:187], v[192:195], v[92:95]
	v_mfma_f32_16x16x32_bf16 v[56:59], v[184:187], v[230:233], v[56:59]
	v_mfma_f32_16x16x32_bf16 v[60:63], v[184:187], v[234:237], v[60:63]
	v_mfma_f32_16x16x32_bf16 v[24:27], v[184:187], v[238:241], v[24:27]
	v_mfma_f32_16x16x32_bf16 v[28:31], v[184:187], v[242:245], v[28:31]
	s_waitcnt lgkmcnt(1)
	v_mfma_f32_16x16x32_bf16 v[96:99], v[222:225], v[176:179], v[96:99]
	v_mfma_f32_16x16x32_bf16 v[100:103], v[222:225], v[188:191], v[100:103]
	v_mfma_f32_16x16x32_bf16 v[64:67], v[222:225], v[180:183], v[64:67]
	v_mfma_f32_16x16x32_bf16 v[68:71], v[222:225], v[192:195], v[68:71]
	v_mfma_f32_16x16x32_bf16 v[32:35], v[222:225], v[230:233], v[32:35]
	v_mfma_f32_16x16x32_bf16 v[36:39], v[222:225], v[234:237], v[36:39]
	v_mfma_f32_16x16x32_bf16 v[0:3], v[222:225], v[238:241], v[0:3]
	v_mfma_f32_16x16x32_bf16 v[4:7], v[222:225], v[242:245], v[4:7]
	s_waitcnt lgkmcnt(0)
	v_mfma_f32_16x16x32_bf16 v[104:107], v[226:229], v[176:179], v[104:107]
	v_mfma_f32_16x16x32_bf16 v[108:111], v[226:229], v[188:191], v[108:111]
	v_mfma_f32_16x16x32_bf16 v[72:75], v[226:229], v[180:183], v[72:75]
	v_mfma_f32_16x16x32_bf16 v[76:79], v[226:229], v[192:195], v[76:79]
	v_mfma_f32_16x16x32_bf16 v[40:43], v[226:229], v[230:233], v[40:43]
	v_mfma_f32_16x16x32_bf16 v[44:47], v[226:229], v[234:237], v[44:47]
	v_mfma_f32_16x16x32_bf16 v[8:11], v[226:229], v[238:241], v[8:11]
	v_mfma_f32_16x16x32_bf16 v[12:15], v[226:229], v[242:245], v[12:15]
	s_waitcnt vmcnt(0)
	s_barrier
; __device__ __forceinline__ void h_main(f32x16 (&acc0)[2][2], f32x16 (&acc1)[2][2], const WideCtx& c, int nk, char* lds) {
;     ...
;     const char* st = lds + (kt & 1) * 24576;
; #pragma unroll
;     for (int ks = 0; ks < 2; ++ks) {
;       bf16x8 wf[2], a0[2], a1[2];
; #pragma unroll
;       for (int b = 0; b < 2; ++b) {
;         wf[b] = *(const bf16x8*)(st + c.wro[b] + (((ks * 2 + h) ^ c.wsw[b]) << 4));
;         a0[b] = *(const bf16x8*)(st + c.aro[0][b] + (((ks * 2 + h) ^ c.asw[0][b]) << 4));
;         a1[b] = *(const bf16x8*)(st + c.aro[1][b] + (((ks * 2 + h) ^ c.asw[1][b]) << 4));
;       }
; #pragma unroll
;       for (int nb = 0; nb < 2; ++nb)
; #pragma unroll
;         for (int tb = 0; tb < 2; ++tb) {
;           acc0[nb][tb] = __builtin_amdgcn_mfma_f32_32x32x16_bf16(wf[nb], a0[tb], acc0[nb][tb], 0, 0, 0);
;           acc1[nb][tb] = __builtin_amdgcn_mfma_f32_32x32x16_bf16(wf[nb], a1[tb], acc1[nb][tb], 0, 0, 0);
;         }
	v_add_u32_e32 v171, s6, v248
	v_add_u32_e32 v196, s6, v249
	ds_read_b128 v[172:175], v171
	ds_read_b128 v[176:179], v196 offset:8192
	ds_read_b128 v[188:191], v196 offset:9216
	ds_read_b128 v[180:183], v196 offset:10240
	ds_read_b128 v[192:195], v196 offset:11264
	ds_read_b128 v[230:233], v196 offset:16384
	ds_read_b128 v[234:237], v196 offset:17408
	ds_read_b128 v[238:241], v196 offset:18432
	ds_read_b128 v[242:245], v196 offset:19456
	ds_read_b128 v[184:187], v171 offset:1024
	ds_read_b128 v[222:225], v171 offset:2048
	ds_read_b128 v[226:229], v171 offset:3072
	s_add_i32 s7, s6, 0x6000
	s_cmp_eq_u32 s6, 0xc000
	s_cselect_b32 s6, 0, s7
	s_waitcnt lgkmcnt(10)
	v_mfma_f32_16x16x32_bf16 v[112:115], v[172:175], v[176:179], v[112:115]
	s_waitcnt lgkmcnt(9)
	v_mfma_f32_16x16x32_bf16 v[116:119], v[172:175], v[188:191], v[116:119]
	s_waitcnt lgkmcnt(8)
	v_mfma_f32_16x16x32_bf16 v[80:83], v[172:175], v[180:183], v[80:83]
	s_waitcnt lgkmcnt(7)
	v_mfma_f32_16x16x32_bf16 v[84:87], v[172:175], v[192:195], v[84:87]
	s_waitcnt lgkmcnt(6)
	v_mfma_f32_16x16x32_bf16 v[48:51], v[172:175], v[230:233], v[48:51]
	s_waitcnt lgkmcnt(5)
	v_mfma_f32_16x16x32_bf16 v[52:55], v[172:175], v[234:237], v[52:55]
	s_waitcnt lgkmcnt(4)
	v_mfma_f32_16x16x32_bf16 v[16:19], v[172:175], v[238:241], v[16:19]
	s_waitcnt lgkmcnt(3)
	v_mfma_f32_16x16x32_bf16 v[20:23], v[172:175], v[242:245], v[20:23]
	s_waitcnt lgkmcnt(2)
	v_mfma_f32_16x16x32_bf16 v[120:123], v[184:187], v[176:179], v[120:123]
	v_mfma_f32_16x16x32_bf16 v[124:127], v[184:187], v[188:191], v[124:127]
	v_mfma_f32_16x16x32_bf16 v[88:91], v[184:187], v[180:183], v[88:91]
	v_mfma_f32_16x16x32_bf16 v[92:95], v[184:187], v[192:195], v[92:95]
	v_mfma_f32_16x16x32_bf16 v[56:59], v[184:187], v[230:233], v[56:59]
	v_mfma_f32_16x16x32_bf16 v[60:63], v[184:187], v[234:237], v[60:63]
	v_mfma_f32_16x16x32_bf16 v[24:27], v[184:187], v[238:241], v[24:27]
	v_mfma_f32_16x16x32_bf16 v[28:31], v[184:187], v[242:245], v[28:31]
	s_waitcnt lgkmcnt(1)
	v_mfma_f32_16x16x32_bf16 v[96:99], v[222:225], v[176:179], v[96:99]
	v_mfma_f32_16x16x32_bf16 v[100:103], v[222:225], v[188:191], v[100:103]
	v_mfma_f32_16x16x32_bf16 v[64:67], v[222:225], v[180:183], v[64:67]
	v_mfma_f32_16x16x32_bf16 v[68:71], v[222:225], v[192:195], v[68:71]
	v_mfma_f32_16x16x32_bf16 v[32:35], v[222:225], v[230:233], v[32:35]
	v_mfma_f32_16x16x32_bf16 v[36:39], v[222:225], v[234:237], v[36:39]
	v_mfma_f32_16x16x32_bf16 v[0:3], v[222:225], v[238:241], v[0:3]
	v_mfma_f32_16x16x32_bf16 v[4:7], v[222:225], v[242:245], v[4:7]
	s_waitcnt lgkmcnt(0)
; __device__ __forceinline__ void h_main(f32x16 (&acc0)[2][2], f32x16 (&acc1)[2][2], const WideCtx& c, int nk, char* lds) {
;     ...
;       for (int nb = 0; nb < 2; ++nb)
; #pragma unroll
;         for (int tb = 0; tb < 2; ++tb) {
;           acc0[nb][tb] = __builtin_amdgcn_mfma_f32_32x32x16_bf16(wf[nb], a0[tb], acc0[nb][tb], 0, 0, 0);
;           acc1[nb][tb] = __builtin_amdgcn_mfma_f32_32x32x16_bf16(wf[nb], a1[tb], acc1[nb][tb], 0, 0, 0);
;         }
; template <class F>
; __device__ __forceinline__ void gemm_phase_w(const u16* A, int lda, int M, const u16* W, int K, int N, char* lds, int* ctr, F&& epi) {
;     ...
;     const int ctm = tm, ctn = tn;
;     par ^= 1;
;     if (c.tid == 0) bw[2 + par] = atomicAdd(myctr, 1);
	v_mfma_f32_16x16x32_bf16 v[104:107], v[226:229], v[176:179], v[104:107]
	v_mfma_f32_16x16x32_bf16 v[108:111], v[226:229], v[188:191], v[108:111]
	v_mfma_f32_16x16x32_bf16 v[72:75], v[226:229], v[180:183], v[72:75]
	v_mfma_f32_16x16x32_bf16 v[76:79], v[226:229], v[192:195], v[76:79]
	v_mfma_f32_16x16x32_bf16 v[40:43], v[226:229], v[230:233], v[40:43]
	v_mfma_f32_16x16x32_bf16 v[44:47], v[226:229], v[234:237], v[44:47]
	v_mfma_f32_16x16x32_bf16 v[8:11], v[226:229], v[238:241], v[8:11]
	v_mfma_f32_16x16x32_bf16 v[12:15], v[226:229], v[242:245], v[12:15]
	s_xor_b32 s49, s49, 1
	s_nop 7
	s_nop 7
	v_permlane16_swap_b32_e32 v112, v116
	v_permlane16_swap_b32_e32 v113, v117
	v_permlane16_swap_b32_e32 v114, v118
	v_permlane16_swap_b32_e32 v115, v119
	v_permlane16_swap_b32_e32 v120, v124
	v_permlane16_swap_b32_e32 v121, v125
	v_permlane16_swap_b32_e32 v122, v126
	v_permlane16_swap_b32_e32 v123, v127
	v_permlane16_swap_b32_e32 v80, v84
	v_permlane16_swap_b32_e32 v81, v85
	v_permlane16_swap_b32_e32 v82, v86
	v_permlane16_swap_b32_e32 v83, v87
	v_permlane16_swap_b32_e32 v88, v92
	v_permlane16_swap_b32_e32 v89, v93
	v_permlane16_swap_b32_e32 v90, v94
	v_permlane16_swap_b32_e32 v91, v95
	v_permlane16_swap_b32_e32 v48, v52
	v_permlane16_swap_b32_e32 v49, v53
	v_permlane16_swap_b32_e32 v50, v54
	v_permlane16_swap_b32_e32 v51, v55
	v_permlane16_swap_b32_e32 v56, v60
	v_permlane16_swap_b32_e32 v57, v61
	v_permlane16_swap_b32_e32 v58, v62
	v_permlane16_swap_b32_e32 v59, v63
	v_permlane16_swap_b32_e32 v16, v20
	v_permlane16_swap_b32_e32 v17, v21
	v_permlane16_swap_b32_e32 v18, v22
	v_permlane16_swap_b32_e32 v19, v23
	v_permlane16_swap_b32_e32 v24, v28
	v_permlane16_swap_b32_e32 v25, v29
	v_permlane16_swap_b32_e32 v26, v30
	v_permlane16_swap_b32_e32 v27, v31
	v_permlane16_swap_b32_e32 v96, v100
	v_permlane16_swap_b32_e32 v97, v101
	v_permlane16_swap_b32_e32 v98, v102
	v_permlane16_swap_b32_e32 v99, v103
	v_permlane16_swap_b32_e32 v104, v108
	v_permlane16_swap_b32_e32 v105, v109
	v_permlane16_swap_b32_e32 v106, v110
	v_permlane16_swap_b32_e32 v107, v111
	v_permlane16_swap_b32_e32 v64, v68
	v_permlane16_swap_b32_e32 v65, v69
	v_permlane16_swap_b32_e32 v66, v70
	v_permlane16_swap_b32_e32 v67, v71
	v_permlane16_swap_b32_e32 v72, v76
	v_permlane16_swap_b32_e32 v73, v77
	v_permlane16_swap_b32_e32 v74, v78
	v_permlane16_swap_b32_e32 v75, v79
	v_permlane16_swap_b32_e32 v32, v36
	v_permlane16_swap_b32_e32 v33, v37
	v_permlane16_swap_b32_e32 v34, v38
	v_permlane16_swap_b32_e32 v35, v39
	v_permlane16_swap_b32_e32 v40, v44
	v_permlane16_swap_b32_e32 v41, v45
	v_permlane16_swap_b32_e32 v42, v46
	v_permlane16_swap_b32_e32 v43, v47
	v_permlane16_swap_b32_e32 v0, v4
	v_permlane16_swap_b32_e32 v1, v5
	v_permlane16_swap_b32_e32 v2, v6
	v_permlane16_swap_b32_e32 v3, v7
	v_permlane16_swap_b32_e32 v8, v12
	v_permlane16_swap_b32_e32 v9, v13
	v_permlane16_swap_b32_e32 v10, v14
	v_permlane16_swap_b32_e32 v11, v15
	v_permlane32_swap_b32_e32 v112, v116
	v_permlane32_swap_b32_e32 v113, v117
	v_permlane32_swap_b32_e32 v114, v118
	v_permlane32_swap_b32_e32 v115, v119
	v_permlane32_swap_b32_e32 v120, v124
	v_permlane32_swap_b32_e32 v121, v125
	v_permlane32_swap_b32_e32 v122, v126
	v_permlane32_swap_b32_e32 v123, v127
	v_permlane32_swap_b32_e32 v80, v84
	v_permlane32_swap_b32_e32 v81, v85
	v_permlane32_swap_b32_e32 v82, v86
	v_permlane32_swap_b32_e32 v83, v87
	v_permlane32_swap_b32_e32 v88, v92
	v_permlane32_swap_b32_e32 v89, v93
	v_permlane32_swap_b32_e32 v90, v94
	v_permlane32_swap_b32_e32 v91, v95
	v_permlane32_swap_b32_e32 v48, v52
	v_permlane32_swap_b32_e32 v49, v53
	v_permlane32_swap_b32_e32 v50, v54
	v_permlane32_swap_b32_e32 v51, v55
	v_permlane32_swap_b32_e32 v56, v60
	v_permlane32_swap_b32_e32 v57, v61
	v_permlane32_swap_b32_e32 v58, v62
	v_permlane32_swap_b32_e32 v59, v63
	v_permlane32_swap_b32_e32 v16, v20
	v_permlane32_swap_b32_e32 v17, v21
	v_permlane32_swap_b32_e32 v18, v22
	v_permlane32_swap_b32_e32 v19, v23
	v_permlane32_swap_b32_e32 v24, v28
	v_permlane32_swap_b32_e32 v25, v29
	v_permlane32_swap_b32_e32 v26, v30
	v_permlane32_swap_b32_e32 v27, v31
	v_permlane32_swap_b32_e32 v96, v100
	v_permlane32_swap_b32_e32 v97, v101
	v_permlane32_swap_b32_e32 v98, v102
	v_permlane32_swap_b32_e32 v99, v103
	v_permlane32_swap_b32_e32 v104, v108
	v_permlane32_swap_b32_e32 v105, v109
	v_permlane32_swap_b32_e32 v106, v110
	v_permlane32_swap_b32_e32 v107, v111
	v_permlane32_swap_b32_e32 v64, v68
	v_permlane32_swap_b32_e32 v65, v69
	v_permlane32_swap_b32_e32 v66, v70
	v_permlane32_swap_b32_e32 v67, v71
	v_permlane32_swap_b32_e32 v72, v76
	v_permlane32_swap_b32_e32 v73, v77
	v_permlane32_swap_b32_e32 v74, v78
	v_permlane32_swap_b32_e32 v75, v79
	v_permlane32_swap_b32_e32 v32, v36
	v_permlane32_swap_b32_e32 v33, v37
	v_permlane32_swap_b32_e32 v34, v38
	v_permlane32_swap_b32_e32 v35, v39
	v_permlane32_swap_b32_e32 v40, v44
	v_permlane32_swap_b32_e32 v41, v45
	v_permlane32_swap_b32_e32 v42, v46
	v_permlane32_swap_b32_e32 v43, v47
	v_permlane32_swap_b32_e32 v0, v4
	v_permlane32_swap_b32_e32 v1, v5
	v_permlane32_swap_b32_e32 v2, v6
	v_permlane32_swap_b32_e32 v3, v7
	v_permlane32_swap_b32_e32 v8, v12
	v_permlane32_swap_b32_e32 v9, v13
	v_permlane32_swap_b32_e32 v10, v14
	v_permlane32_swap_b32_e32 v11, v15
	s_and_saveexec_b64 s[6:7], vcc
	s_cbranch_execz .LBB0_91
	s_mov_b64 s[34:35], exec
	v_mbcnt_lo_u32_b32 v144, s34, 0
	v_mbcnt_hi_u32_b32 v144, s35, v144
	v_cmp_eq_u32_e64 s[38:39], 0, v144
	s_and_saveexec_b64 s[0:1], s[38:39]
	s_cbranch_execz .LBB0_90
	s_bcnt1_i32_b64 s9, s[34:35]
	v_mov_b32_e32 v145, s9
	global_atomic_add v145, v161, v145, s[30:31] offset:256 sc0

; __device__ __forceinline__ unsigned xb_xcc_id() { return (unsigned)__builtin_amdgcn_s_getreg((3 << 11) | 20) & 0xFu; }
; __device__ __forceinline__ void h_tile(WideCtx& c, const u16* __restrict__ A, int lda, int M, int m0, const u16* __restrict__ W, int ldw, int n0) {
; #pragma unroll
;   for (int i = 0; i < 2; ++i) {
;     const int q = c.tid + 256 * i, row = q >> 2, ch = (q & 3) ^ ((row >> 2) & 3);
;     c.wp[i] = W + (size_t)(n0 + row) * ldw + ch * 8;
;   }
; #pragma unroll
;   for (int i = 0; i < 4; ++i) {
;     const int q = c.tid + 256 * i, row = q >> 2, ch = (q & 3) ^ ((row >> 2) & 3);
;     int ar = m0 + row; ar = ar < M ? ar : M - 1;
;     c.ap[i] = A + (size_t)ar * lda + ch * 8;
;   }
; }
; __device__ __forceinline__ void h_stage(const WideCtx& c, int kt) {
;   const unsigned sb = c.lds0 + (kt & 1) * 24576;
; #pragma unroll
;   for (int i = 0; i < 2; ++i) glds16(c.wp[i] + kt * 32, sb + i * 4096);
; #pragma unroll
;   for (int i = 0; i < 4; ++i) glds16(c.ap[i] + kt * 32, sb + 8192 + i * 4096);
; }
; template <class F>
; __device__ __forceinline__ void gemm_phase_w(const u16* A, int lda, int M, const u16* W, int K, int N, char* lds, int* ctr, F&& epi) {
;   const int nN = N >> 7, nM = (M + 255) >> 8, nt = nN * nM, nk = K >> 5;
;   const int xcd = (int)xb_xcc_id() & 7;
;   const int tq = nt >> 3, trm = nt & 7;
;   const int tstart = xcd < trm ? xcd * (tq + 1) : trm * (tq + 1) + (xcd - trm) * tq;
;   const int tcnt = tq + (xcd < trm ? 1 : 0);
;   auto decode = [&](int off, int& tm, int& tn) {
;     const int id = tstart + off, nig = 4 * nN, grp = id / nig, fm = grp * 4;
;     const int gsz = (nM - fm) < 4 ? (nM - fm) : 4, idl = id - grp * nig;
;     tm = fm + idl % gsz; tn = idl / gsz;
;   };
;   WideCtx c;
;   h_init(c, lds);
;   const int wave = c.tid >> 6;
;   volatile int* bw = (volatile int*)(lds + 65536);
;   int* myctr = ctr + xcd;
;   int par = 0;
;   if (c.tid == 0) bw[2] = atomicAdd(myctr, 1);
;   asm volatile("s_waitcnt vmcnt(0) lgkmcnt(0)" ::: "memory");
;   __builtin_amdgcn_s_barrier();
;   int off = bw[2];
;   int tm = 0, tn = 0;
;   if (off < tcnt) { decode(off, tm, tn); h_tile(c, A, lda, M, tm * 256, W, K, tn * 128); h_stage(c, 0); }
.LBB0_107:
	s_or_b64 exec, exec, s[6:7]
	s_mov_b64 s[0:1], src_shared_base
	s_waitcnt vmcnt(0)
	v_mov_b32_e32 v163, s1
	s_waitcnt vmcnt(0) lgkmcnt(0)
	s_barrier
	flat_load_dword v1, v[162:163] sc0 sc1
	s_waitcnt vmcnt(0)
	s_add_i32 s0, s62, 0xff
	s_lshr_b32 s10, s0, 8
	s_waitcnt lgkmcnt(0)
	v_cmp_gt_i32_e64 s[38:39], s10, v1
	s_and_saveexec_b64 s[44:45], s[38:39]
	s_cbranch_execz .LBB0_134
	s_mul_i32 s11, s11, s10
	v_and_b32_e32 v2, 31, v0
	v_lshrrev_b32_e32 v3, 1, v0
	s_mov_b32 s0, 0x3ffffc0
	v_and_or_b32 v2, v3, s0, v2
	v_add_u32_e32 v1, s11, v1
	v_lshlrev_b32_e32 v157, 6, v2
	v_ashrrev_i32_e32 v2, 31, v1
	v_lshrrev_b32_e32 v2, 27, v2
	v_lshlrev_b32_e32 v3, 6, v0
	v_add_u32_e32 v2, v1, v2
	v_and_b32_e32 v156, 0x17c0, v3
	v_ashrrev_i32_e32 v3, 5, v2
	v_lshlrev_b32_e32 v3, 2, v3
	v_sub_u32_e32 v7, s10, v3
	v_min_i32_e32 v7, 4, v7
	v_sub_u32_e32 v8, 0, v7
	v_max_i32_e32 v8, v7, v8
	v_cvt_f32_u32_e32 v9, v8
	v_and_b32_e32 v2, 0xffffffe0, v2
	v_sub_u32_e32 v1, v1, v2
	v_sub_u32_e32 v11, 0, v8
	v_rcp_iflag_f32_e32 v2, v9
	v_sub_u32_e32 v10, 0, v1
	v_max_i32_e32 v10, v1, v10
	v_xor_b32_e32 v9, v1, v7
	v_mul_f32_e32 v2, 0x4f7ffffe, v2
	v_cvt_u32_f32_e32 v2, v2
	v_ashrrev_i32_e32 v9, 31, v9
	s_lshl_b32 s0, s9, 4
	s_and_b32 s52, s0, 0xfffffc00
	v_mul_lo_u32 v11, v11, v2
	v_mul_hi_u32 v11, v2, v11
	v_add_u32_e32 v2, v2, v11
	v_mul_hi_u32 v2, v10, v2
	v_mul_lo_u32 v11, v2, v8
	v_sub_u32_e32 v10, v10, v11
	v_add_u32_e32 v11, 1, v2
	v_cmp_ge_u32_e64 s[38:39], v10, v8
	s_load_dwordx2 s[0:1], s[64:65], 0x148
	v_ashrrev_i32_e32 v158, 2, v0
	v_cndmask_b32_e64 v2, v2, v11, s[38:39]
	v_sub_u32_e32 v11, v10, v8
	v_cndmask_b32_e64 v10, v10, v11, s[38:39]
	v_add_u32_e32 v11, 1, v2
	v_cmp_ge_u32_e64 s[38:39], v10, v8
	s_add_i32 s54, s62, -1
	s_add_i32 s55, s52, 0x1000
	v_cndmask_b32_e64 v2, v2, v11, s[38:39]
	v_xor_b32_e32 v2, v2, v9
	v_sub_u32_e32 v150, v2, v9
	v_mul_lo_u32 v2, v150, v7
	v_sub_u32_e32 v1, v1, v2
	v_lshrrev_b32_e32 v2, 4, v0
	v_and_b32_e32 v250, 1, v2
	v_lshlrev_b32_e32 v250, 1, v250
	v_xor_b32_e32 v2, v2, v250
	v_xor_b32_e32 v2, v2, v0
	v_lshlrev_b32_e32 v7, 7, v150
	v_lshlrev_b32_e32 v2, 4, v2
	v_and_b32_e32 v160, 48, v2
	v_add_u32_e32 v2, v7, v158
	v_add_u32_e32 v151, v1, v3
	v_ashrrev_i32_e32 v3, 31, v2
	s_waitcnt lgkmcnt(0)
	v_lshl_add_u64 v[128:129], s[0:1], 0, v[160:161]
	v_lshlrev_b64 v[2:3], 11, v[2:3]
	v_lshl_add_u64 v[132:133], v[128:129], 0, v[2:3]
	v_add_u32_e32 v2, 0x100, v0
	v_ashrrev_i32_e32 v159, 2, v2
	v_add_u32_e32 v2, v7, v159
	v_ashrrev_i32_e32 v3, 31, v2
	s_load_dwordx2 s[0:1], s[64:65], 0x200
	v_lshlrev_b32_e32 v1, 8, v151
	v_lshlrev_b64 v[2:3], 11, v[2:3]
	v_lshl_add_u64 v[134:135], v[128:129], 0, v[2:3]
	v_add_u32_e32 v2, v1, v158
	v_min_i32_e32 v2, s54, v2
	v_ashrrev_i32_e32 v3, 31, v2
	s_waitcnt lgkmcnt(0)
	v_lshl_add_u64 v[130:131], s[0:1], 0, v[160:161]
	v_lshlrev_b64 v[2:3], 11, v[2:3]
	v_lshl_add_u64 v[136:137], v[130:131], 0, v[2:3]
	v_add_u32_e32 v2, v1, v159
	v_min_i32_e32 v2, s54, v2
	v_ashrrev_i32_e32 v3, 31, v2
	v_lshlrev_b64 v[2:3], 11, v[2:3]
	v_lshl_add_u64 v[138:139], v[130:131], 0, v[2:3]
	v_add_u32_e32 v2, 0x200, v0
	v_ashrrev_i32_e32 v160, 2, v2
	v_add_u32_e32 v2, v1, v160
	v_min_i32_e32 v2, s54, v2
	v_ashrrev_i32_e32 v3, 31, v2
	v_lshlrev_b64 v[2:3], 11, v[2:3]
	v_lshl_add_u64 v[140:141], v[130:131], 0, v[2:3]
	v_add_u32_e32 v2, 0x300, v0
	v_ashrrev_i32_e32 v163, 2, v2
	s_mov_b32 s0, m0
	s_mov_b32 m0, s52
	s_nop 0
	global_load_lds_dwordx4 v[132:133], off
	s_mov_b32 m0, s0
	v_add_u32_e32 v1, v1, v163
	s_mov_b32 s0, m0
	s_mov_b32 m0, s55
	s_nop 0
	global_load_lds_dwordx4 v[134:135], off
	s_mov_b32 m0, s0
	v_min_i32_e32 v2, s54, v1
	s_add_i32 s58, s52, 0x2000
	s_mov_b32 s0, m0
	s_mov_b32 m0, s58
	s_nop 0
	global_load_lds_dwordx4 v[136:137], off
	s_mov_b32 m0, s0
	v_ashrrev_i32_e32 v3, 31, v2
	s_add_i32 s59, s52, 0x3000
	s_mov_b32 s0, m0
	s_mov_b32 m0, s59
	s_nop 0
	global_load_lds_dwordx4 v[138:139], off
	s_mov_b32 m0, s0
	v_lshlrev_b64 v[2:3], 11, v[2:3]
	s_add_i32 s63, s52, 0x4000
	s_mov_b32 s0, m0
	s_mov_b32 m0, s63
	s_nop 0
	global_load_lds_dwordx4 v[140:141], off
	s_mov_b32 m0, s0
	v_lshl_add_u64 v[142:143], v[130:131], 0, v[2:3]
	s_add_i32 s81, s52, 0x5000
	s_mov_b32 s0, m0
	s_mov_b32 m0, s81
	s_nop 0
	global_load_lds_dwordx4 v[142:143], off
	s_mov_b32 m0, s0
	s_add_i32 m0, s52, 0x5fc0
	s_nop 0
	global_load_lds_dwordx4 v[132:133], off offset:64
	s_add_i32 m0, s55, 0x5fc0
	s_nop 0
	global_load_lds_dwordx4 v[134:135], off offset:64
	s_add_i32 m0, s58, 0x5fc0
	s_nop 0
	global_load_lds_dwordx4 v[136:137], off offset:64
	s_add_i32 m0, s59, 0x5fc0
	s_nop 0
	global_load_lds_dwordx4 v[138:139], off offset:64
	s_add_i32 m0, s63, 0x5fc0
	s_nop 0
	global_load_lds_dwordx4 v[140:141], off offset:64
	s_add_i32 m0, s81, 0x5fc0
	s_nop 0
	global_load_lds_dwordx4 v[142:143], off offset:64
	s_load_dwordx2 s[46:47], s[64:65], 0x1c0
	s_load_dwordx2 s[48:49], s[64:65], 0x230
	v_bfe_u32 v4, v0, 5, 1
	v_lshrrev_b32_e32 v5, 2, v0
	v_bfe_u32 v6, v0, 2, 2
	v_bitop3_b32 v1, v5, v4, 3 bitop3:0x6c
	v_lshlrev_b32_e32 v164, 4, v1
	v_bitop3_b32 v1, v4, v6, 2 bitop3:0x36
	v_and_b32_e32 v166, 64, v0
	v_ashrrev_i32_e32 v0, 1, v0
	s_mov_b32 s53, 0
	v_lshlrev_b32_e32 v165, 4, v1
	v_and_b32_e32 v167, 0xffffffc0, v0
	s_mov_b64 s[50:51], 0
	s_branch .LBB0_110

; __device__ __forceinline__ void h_main(f32x16 (&acc0)[2][2], f32x16 (&acc1)[2][2], const WideCtx& c, int nk, char* lds) {
;   const int h = c.h;
;   for (int kt = 0; kt < nk; ++kt) {
;     asm volatile("s_waitcnt vmcnt(0)" ::: "memory");
;     __builtin_amdgcn_s_barrier();
;     if (kt + 1 < nk) h_stage(c, kt + 1);
;     const char* st = lds + (kt & 1) * 24576;
; #pragma unroll
;     for (int ks = 0; ks < 2; ++ks) {
;       bf16x8 wf[2], a0[2], a1[2];
; #pragma unroll
;       for (int b = 0; b < 2; ++b) {
;         wf[b] = *(const bf16x8*)(st + c.wro[b] + (((ks * 2 + h) ^ c.wsw[b]) << 4));
;         a0[b] = *(const bf16x8*)(st + c.aro[0][b] + (((ks * 2 + h) ^ c.asw[0][b]) << 4));
;         a1[b] = *(const bf16x8*)(st + c.aro[1][b] + (((ks * 2 + h) ^ c.asw[1][b]) << 4));
;       }
; #pragma unroll
;       for (int nb = 0; nb < 2; ++nb)
; #pragma unroll
;         for (int tb = 0; tb < 2; ++tb) {
;           acc0[nb][tb] = __builtin_amdgcn_mfma_f32_32x32x16_bf16(wf[nb], a0[tb], acc0[nb][tb], 0, 0, 0);
;           acc1[nb][tb] = __builtin_amdgcn_mfma_f32_32x32x16_bf16(wf[nb], a1[tb], acc1[nb][tb], 0, 0, 0);
;         }
.LBB0_110:
	v_mov_b32_e32 v64, 0
	v_mov_b32_e32 v168, v151
	v_mov_b32_e32 v169, v150
	s_load_dwordx2 s[0:1], s[64:65], 0x120
	s_waitcnt lgkmcnt(0)
	v_subrev_u32_e32 v144, s0, v142
	v_subrev_u32_e32 v146, s0, v140
	v_subrev_u32_e32 v148, s0, v138
	v_subrev_u32_e32 v150, s0, v136
	v_subrev_u32_e32 v152, s0, v134
	v_subrev_u32_e32 v154, s0, v132
	s_add_u32 s0, s0, 0x80
	s_addc_u32 s1, s1, 0
	s_mov_b32 s9, 2
	s_mov_b32 s6, 0
	v_and_b32_e32 v250, 15, v204
	v_lshlrev_b32_e32 v250, 6, v250
	v_bfe_u32 v251, v204, 2, 2
	v_and_b32_e32 v247, 1, v251
	v_lshlrev_b32_e32 v247, 1, v247
	v_xor_b32_e32 v251, v251, v247
	v_bfe_u32 v247, v204, 4, 2
	v_xor_b32_e32 v251, v251, v247
	v_lshl_or_b32 v250, v251, 4, v250
	v_bfe_u32 v247, v204, 6, 1
	v_lshl_or_b32 v248, v247, 12, v250
	v_lshrrev_b32_e32 v247, 7, v204
	v_lshl_or_b32 v249, v247, 12, v250
	v_mov_b32_e32 v65, v64
	v_mov_b32_e32 v66, v64
	v_mov_b32_e32 v67, v64
	v_mov_b32_e32 v68, v64
	v_mov_b32_e32 v69, v64
	v_mov_b32_e32 v70, v64
	v_mov_b32_e32 v71, v64
	v_mov_b32_e32 v72, v64
	v_mov_b32_e32 v73, v64
	v_mov_b32_e32 v74, v64
	v_mov_b32_e32 v75, v64
	v_mov_b32_e32 v76, v64
	v_mov_b32_e32 v77, v64
	v_mov_b32_e32 v78, v64
	v_mov_b32_e32 v79, v64
	v_mov_b32_e32 v96, v64
	v_mov_b32_e32 v97, v64
	v_mov_b32_e32 v98, v64
	v_mov_b32_e32 v99, v64
	v_mov_b32_e32 v100, v64
	v_mov_b32_e32 v101, v64
	v_mov_b32_e32 v102, v64
	v_mov_b32_e32 v103, v64
	v_mov_b32_e32 v104, v64
	v_mov_b32_e32 v105, v64
	v_mov_b32_e32 v106, v64
	v_mov_b32_e32 v107, v64
	v_mov_b32_e32 v108, v64
	v_mov_b32_e32 v109, v64
	v_mov_b32_e32 v110, v64
	v_mov_b32_e32 v111, v64
	v_mov_b32_e32 v80, v64
	v_mov_b32_e32 v81, v64
	v_mov_b32_e32 v82, v64
	v_mov_b32_e32 v83, v64
	v_mov_b32_e32 v84, v64
	v_mov_b32_e32 v85, v64
	v_mov_b32_e32 v86, v64
	v_mov_b32_e32 v87, v64
	v_mov_b32_e32 v88, v64
	v_mov_b32_e32 v89, v64
	v_mov_b32_e32 v90, v64
	v_mov_b32_e32 v91, v64
	v_mov_b32_e32 v92, v64
	v_mov_b32_e32 v93, v64
	v_mov_b32_e32 v94, v64
	v_mov_b32_e32 v95, v64
	v_mov_b32_e32 v112, v64
	v_mov_b32_e32 v113, v64
	v_mov_b32_e32 v114, v64
	v_mov_b32_e32 v115, v64
	v_mov_b32_e32 v116, v64
	v_mov_b32_e32 v117, v64
	v_mov_b32_e32 v118, v64
	v_mov_b32_e32 v119, v64
	v_mov_b32_e32 v120, v64
	v_mov_b32_e32 v121, v64
	v_mov_b32_e32 v122, v64
	v_mov_b32_e32 v123, v64
	v_mov_b32_e32 v124, v64
	v_mov_b32_e32 v125, v64
	v_mov_b32_e32 v126, v64
	v_mov_b32_e32 v127, v64
	s_waitcnt lgkmcnt(0)
	v_mov_b32_e32 v0, v64
	v_mov_b32_e32 v1, v64
	v_mov_b32_e32 v2, v64
	v_mov_b32_e32 v3, v64
	v_mov_b32_e32 v4, v64
	v_mov_b32_e32 v5, v64
	v_mov_b32_e32 v6, v64
	v_mov_b32_e32 v7, v64
	v_mov_b32_e32 v8, v64
	v_mov_b32_e32 v9, v64
	v_mov_b32_e32 v10, v64
	v_mov_b32_e32 v11, v64
	v_mov_b32_e32 v12, v64
	v_mov_b32_e32 v13, v64
	v_mov_b32_e32 v14, v64
	v_mov_b32_e32 v15, v64
	v_mov_b32_e32 v32, v64
	v_mov_b32_e32 v33, v64
	v_mov_b32_e32 v34, v64
	v_mov_b32_e32 v35, v64
	v_mov_b32_e32 v36, v64
	v_mov_b32_e32 v37, v64
	v_mov_b32_e32 v38, v64
	v_mov_b32_e32 v39, v64
	v_mov_b32_e32 v40, v64
	v_mov_b32_e32 v41, v64
	v_mov_b32_e32 v42, v64
	v_mov_b32_e32 v43, v64
	v_mov_b32_e32 v44, v64
	v_mov_b32_e32 v45, v64
	v_mov_b32_e32 v46, v64
	v_mov_b32_e32 v47, v64
	v_mov_b32_e32 v16, v64
	v_mov_b32_e32 v17, v64
	v_mov_b32_e32 v18, v64
	v_mov_b32_e32 v19, v64
	v_mov_b32_e32 v20, v64
	v_mov_b32_e32 v21, v64
	v_mov_b32_e32 v22, v64
	v_mov_b32_e32 v23, v64
	v_mov_b32_e32 v24, v64
	v_mov_b32_e32 v25, v64
	v_mov_b32_e32 v26, v64
	v_mov_b32_e32 v27, v64
	v_mov_b32_e32 v28, v64
	v_mov_b32_e32 v29, v64
	v_mov_b32_e32 v30, v64
	v_mov_b32_e32 v31, v64
	v_mov_b32_e32 v48, v64
	v_mov_b32_e32 v49, v64
	v_mov_b32_e32 v50, v64
	v_mov_b32_e32 v51, v64
	v_mov_b32_e32 v52, v64
	v_mov_b32_e32 v53, v64
	v_mov_b32_e32 v54, v64
	v_mov_b32_e32 v55, v64
	v_mov_b32_e32 v56, v64
	v_mov_b32_e32 v57, v64
	v_mov_b32_e32 v58, v64
	v_mov_b32_e32 v59, v64
	v_mov_b32_e32 v60, v64
	v_mov_b32_e32 v61, v64
	v_mov_b32_e32 v62, v64
	v_mov_b32_e32 v63, v64
.LBB0_111:
	s_waitcnt vmcnt(6)
	s_barrier
	v_add_u32_e32 v194, s6, v248
	v_add_u32_e32 v195, s6, v249
	ds_read_b128 v[170:173], v194
	ds_read_b128 v[174:177], v195 offset:8192
	ds_read_b128 v[186:189], v195 offset:9216
	ds_read_b128 v[178:181], v195 offset:10240
	ds_read_b128 v[190:193], v195 offset:11264
	ds_read_b128 v[230:233], v195 offset:16384
	ds_read_b128 v[234:237], v195 offset:17408
	ds_read_b128 v[238:241], v195 offset:18432
	ds_read_b128 v[242:245], v195 offset:19456
	ds_read_b128 v[182:185], v194 offset:1024
	ds_read_b128 v[222:225], v194 offset:2048
	ds_read_b128 v[226:229], v194 offset:3072
	s_add_i32 s7, s6, 0xffffa000
	s_cmp_eq_u32 s6, 0
	s_cselect_b32 s7, 0xc000, s7
	s_add_i32 m0, s7, s52
	s_add_i32 s7, s6, 0x6000
	global_load_lds_dwordx4 v154, s[0:1]
	s_add_i32 m0, m0, 0x1000
	s_cmp_eq_u32 s6, 0xc000
	global_load_lds_dwordx4 v152, s[0:1]
	s_cselect_b32 s6, 0, s7
	s_add_i32 m0, m0, 0x1000
	s_waitcnt lgkmcnt(10)
	v_mfma_f32_16x16x32_bf16 v[112:115], v[170:173], v[174:177], v[112:115]
	global_load_lds_dwordx4 v150, s[0:1]
	s_add_i32 m0, m0, 0x1000
	s_waitcnt lgkmcnt(9)
	v_mfma_f32_16x16x32_bf16 v[116:119], v[170:173], v[186:189], v[116:119]
	global_load_lds_dwordx4 v148, s[0:1]
	s_add_i32 m0, m0, 0x1000
	s_waitcnt lgkmcnt(8)
	v_mfma_f32_16x16x32_bf16 v[80:83], v[170:173], v[178:181], v[80:83]
	global_load_lds_dwordx4 v146, s[0:1]
	s_add_i32 m0, m0, 0x1000
	s_waitcnt lgkmcnt(7)
	v_mfma_f32_16x16x32_bf16 v[84:87], v[170:173], v[190:193], v[84:87]
	global_load_lds_dwordx4 v144, s[0:1]
	s_add_u32 s0, s0, 64
	s_addc_u32 s1, s1, 0
	s_waitcnt lgkmcnt(6)
	v_mfma_f32_16x16x32_bf16 v[48:51], v[170:173], v[230:233], v[48:51]
	s_waitcnt lgkmcnt(5)
; __device__ __forceinline__ void h_main(f32x16 (&acc0)[2][2], f32x16 (&acc1)[2][2], const WideCtx& c, int nk, char* lds) {
;   const int h = c.h;
;   for (int kt = 0; kt < nk; ++kt) {
;     asm volatile("s_waitcnt vmcnt(0)" ::: "memory");
;     __builtin_amdgcn_s_barrier();
;     if (kt + 1 < nk) h_stage(c, kt + 1);
;     const char* st = lds + (kt & 1) * 24576;
; #pragma unroll
;     for (int ks = 0; ks < 2; ++ks) {
;       bf16x8 wf[2], a0[2], a1[2];
; #pragma unroll
;       for (int b = 0; b < 2; ++b) {
;         wf[b] = *(const bf16x8*)(st + c.wro[b] + (((ks * 2 + h) ^ c.wsw[b]) << 4));
;         a0[b] = *(const bf16x8*)(st + c.aro[0][b] + (((ks * 2 + h) ^ c.asw[0][b]) << 4));
;         a1[b] = *(const bf16x8*)(st + c.aro[1][b] + (((ks * 2 + h) ^ c.asw[1][b]) << 4));
;       }
; #pragma unroll
;       for (int nb = 0; nb < 2; ++nb)
; #pragma unroll
;         for (int tb = 0; tb < 2; ++tb) {
;           acc0[nb][tb] = __builtin_amdgcn_mfma_f32_32x32x16_bf16(wf[nb], a0[tb], acc0[nb][tb], 0, 0, 0);
;           acc1[nb][tb] = __builtin_amdgcn_mfma_f32_32x32x16_bf16(wf[nb], a1[tb], acc1[nb][tb], 0, 0, 0);
;         }
;     }
;   }
; }
	v_mfma_f32_16x16x32_bf16 v[52:55], v[170:173], v[234:237], v[52:55]
	s_waitcnt lgkmcnt(4)
	v_mfma_f32_16x16x32_bf16 v[16:19], v[170:173], v[238:241], v[16:19]
	s_waitcnt lgkmcnt(3)
	v_mfma_f32_16x16x32_bf16 v[20:23], v[170:173], v[242:245], v[20:23]
	s_waitcnt lgkmcnt(2)
	v_mfma_f32_16x16x32_bf16 v[120:123], v[182:185], v[174:177], v[120:123]
	v_mfma_f32_16x16x32_bf16 v[124:127], v[182:185], v[186:189], v[124:127]
	v_mfma_f32_16x16x32_bf16 v[88:91], v[182:185], v[178:181], v[88:91]
	v_mfma_f32_16x16x32_bf16 v[92:95], v[182:185], v[190:193], v[92:95]
	v_mfma_f32_16x16x32_bf16 v[56:59], v[182:185], v[230:233], v[56:59]
	v_mfma_f32_16x16x32_bf16 v[60:63], v[182:185], v[234:237], v[60:63]
	v_mfma_f32_16x16x32_bf16 v[24:27], v[182:185], v[238:241], v[24:27]
	v_mfma_f32_16x16x32_bf16 v[28:31], v[182:185], v[242:245], v[28:31]
	s_waitcnt lgkmcnt(1)
	v_mfma_f32_16x16x32_bf16 v[96:99], v[222:225], v[174:177], v[96:99]
	v_mfma_f32_16x16x32_bf16 v[100:103], v[222:225], v[186:189], v[100:103]
	v_mfma_f32_16x16x32_bf16 v[64:67], v[222:225], v[178:181], v[64:67]
	v_mfma_f32_16x16x32_bf16 v[68:71], v[222:225], v[190:193], v[68:71]
	v_mfma_f32_16x16x32_bf16 v[32:35], v[222:225], v[230:233], v[32:35]
	v_mfma_f32_16x16x32_bf16 v[36:39], v[222:225], v[234:237], v[36:39]
	v_mfma_f32_16x16x32_bf16 v[0:3], v[222:225], v[238:241], v[0:3]
	v_mfma_f32_16x16x32_bf16 v[4:7], v[222:225], v[242:245], v[4:7]
	s_waitcnt lgkmcnt(0)
	v_mfma_f32_16x16x32_bf16 v[104:107], v[226:229], v[174:177], v[104:107]
	v_mfma_f32_16x16x32_bf16 v[108:111], v[226:229], v[186:189], v[108:111]
	v_mfma_f32_16x16x32_bf16 v[72:75], v[226:229], v[178:181], v[72:75]
	v_mfma_f32_16x16x32_bf16 v[76:79], v[226:229], v[190:193], v[76:79]
	v_mfma_f32_16x16x32_bf16 v[40:43], v[226:229], v[230:233], v[40:43]
	v_mfma_f32_16x16x32_bf16 v[44:47], v[226:229], v[234:237], v[44:47]
	v_mfma_f32_16x16x32_bf16 v[8:11], v[226:229], v[238:241], v[8:11]
	v_mfma_f32_16x16x32_bf16 v[12:15], v[226:229], v[242:245], v[12:15]
	s_add_i32 s9, s9, 1
	s_cmp_eq_u32 s9, 32
	s_cbranch_scc0 .LBB0_111
	s_waitcnt vmcnt(6)
	s_barrier
	v_add_u32_e32 v194, s6, v248
	v_add_u32_e32 v195, s6, v249
	ds_read_b128 v[170:173], v194
	ds_read_b128 v[174:177], v195 offset:8192
	ds_read_b128 v[186:189], v195 offset:9216
	ds_read_b128 v[178:181], v195 offset:10240
	ds_read_b128 v[190:193], v195 offset:11264
	ds_read_b128 v[230:233], v195 offset:16384
	ds_read_b128 v[234:237], v195 offset:17408
	ds_read_b128 v[238:241], v195 offset:18432
	ds_read_b128 v[242:245], v195 offset:19456
	ds_read_b128 v[182:185], v194 offset:1024
	ds_read_b128 v[222:225], v194 offset:2048
	ds_read_b128 v[226:229], v194 offset:3072
	s_add_i32 s7, s6, 0x6000
	s_cmp_eq_u32 s6, 0xc000
	s_cselect_b32 s6, 0, s7
	s_waitcnt lgkmcnt(10)
	v_mfma_f32_16x16x32_bf16 v[112:115], v[170:173], v[174:177], v[112:115]
	s_waitcnt lgkmcnt(9)
	v_mfma_f32_16x16x32_bf16 v[116:119], v[170:173], v[186:189], v[116:119]
	s_waitcnt lgkmcnt(8)
	v_mfma_f32_16x16x32_bf16 v[80:83], v[170:173], v[178:181], v[80:83]
	s_waitcnt lgkmcnt(7)
	v_mfma_f32_16x16x32_bf16 v[84:87], v[170:173], v[190:193], v[84:87]
	s_waitcnt lgkmcnt(6)
	v_mfma_f32_16x16x32_bf16 v[48:51], v[170:173], v[230:233], v[48:51]
	s_waitcnt lgkmcnt(5)
	v_mfma_f32_16x16x32_bf16 v[52:55], v[170:173], v[234:237], v[52:55]
	s_waitcnt lgkmcnt(4)
	v_mfma_f32_16x16x32_bf16 v[16:19], v[170:173], v[238:241], v[16:19]
	s_waitcnt lgkmcnt(3)
	v_mfma_f32_16x16x32_bf16 v[20:23], v[170:173], v[242:245], v[20:23]
	s_waitcnt lgkmcnt(2)
	v_mfma_f32_16x16x32_bf16 v[120:123], v[182:185], v[174:177], v[120:123]
	v_mfma_f32_16x16x32_bf16 v[124:127], v[182:185], v[186:189], v[124:127]
	v_mfma_f32_16x16x32_bf16 v[88:91], v[182:185], v[178:181], v[88:91]
	v_mfma_f32_16x16x32_bf16 v[92:95], v[182:185], v[190:193], v[92:95]
	v_mfma_f32_16x16x32_bf16 v[56:59], v[182:185], v[230:233], v[56:59]
	v_mfma_f32_16x16x32_bf16 v[60:63], v[182:185], v[234:237], v[60:63]
	v_mfma_f32_16x16x32_bf16 v[24:27], v[182:185], v[238:241], v[24:27]
	v_mfma_f32_16x16x32_bf16 v[28:31], v[182:185], v[242:245], v[28:31]
	s_waitcnt lgkmcnt(1)
	v_mfma_f32_16x16x32_bf16 v[96:99], v[222:225], v[174:177], v[96:99]
	v_mfma_f32_16x16x32_bf16 v[100:103], v[222:225], v[186:189], v[100:103]
	v_mfma_f32_16x16x32_bf16 v[64:67], v[222:225], v[178:181], v[64:67]
	v_mfma_f32_16x16x32_bf16 v[68:71], v[222:225], v[190:193], v[68:71]
	v_mfma_f32_16x16x32_bf16 v[32:35], v[222:225], v[230:233], v[32:35]
	v_mfma_f32_16x16x32_bf16 v[36:39], v[222:225], v[234:237], v[36:39]
	v_mfma_f32_16x16x32_bf16 v[0:3], v[222:225], v[238:241], v[0:3]
	v_mfma_f32_16x16x32_bf16 v[4:7], v[222:225], v[242:245], v[4:7]
	s_waitcnt lgkmcnt(0)
	v_mfma_f32_16x16x32_bf16 v[104:107], v[226:229], v[174:177], v[104:107]
	v_mfma_f32_16x16x32_bf16 v[108:111], v[226:229], v[186:189], v[108:111]
	v_mfma_f32_16x16x32_bf16 v[72:75], v[226:229], v[178:181], v[72:75]
	v_mfma_f32_16x16x32_bf16 v[76:79], v[226:229], v[190:193], v[76:79]
	v_mfma_f32_16x16x32_bf16 v[40:43], v[226:229], v[230:233], v[40:43]
	v_mfma_f32_16x16x32_bf16 v[44:47], v[226:229], v[234:237], v[44:47]
	v_mfma_f32_16x16x32_bf16 v[8:11], v[226:229], v[238:241], v[8:11]
	v_mfma_f32_16x16x32_bf16 v[12:15], v[226:229], v[242:245], v[12:15]
	s_waitcnt vmcnt(0)
	s_barrier
; __device__ __forceinline__ void h_main(f32x16 (&acc0)[2][2], f32x16 (&acc1)[2][2], const WideCtx& c, int nk, char* lds) {
;     ...
;     const char* st = lds + (kt & 1) * 24576;
; #pragma unroll
;     for (int ks = 0; ks < 2; ++ks) {
;       bf16x8 wf[2], a0[2], a1[2];
; #pragma unroll
;       for (int b = 0; b < 2; ++b) {
;         wf[b] = *(const bf16x8*)(st + c.wro[b] + (((ks * 2 + h) ^ c.wsw[b]) << 4));
;         a0[b] = *(const bf16x8*)(st + c.aro[0][b] + (((ks * 2 + h) ^ c.asw[0][b]) << 4));
;         a1[b] = *(const bf16x8*)(st + c.aro[1][b] + (((ks * 2 + h) ^ c.asw[1][b]) << 4));
;       }
; #pragma unroll
;       for (int nb = 0; nb < 2; ++nb)
; #pragma unroll
;         for (int tb = 0; tb < 2; ++tb) {
;           acc0[nb][tb] = __builtin_amdgcn_mfma_f32_32x32x16_bf16(wf[nb], a0[tb], acc0[nb][tb], 0, 0, 0);
;           acc1[nb][tb] = __builtin_amdgcn_mfma_f32_32x32x16_bf16(wf[nb], a1[tb], acc1[nb][tb], 0, 0, 0);
;         }
	v_add_u32_e32 v194, s6, v248
	v_add_u32_e32 v195, s6, v249
	ds_read_b128 v[170:173], v194
	ds_read_b128 v[174:177], v195 offset:8192
	ds_read_b128 v[186:189], v195 offset:9216
	ds_read_b128 v[178:181], v195 offset:10240
	ds_read_b128 v[190:193], v195 offset:11264
	ds_read_b128 v[230:233], v195 offset:16384
	ds_read_b128 v[234:237], v195 offset:17408
	ds_read_b128 v[238:241], v195 offset:18432
	ds_read_b128 v[242:245], v195 offset:19456
	ds_read_b128 v[182:185], v194 offset:1024
	ds_read_b128 v[222:225], v194 offset:2048
	ds_read_b128 v[226:229], v194 offset:3072
	s_add_i32 s7, s6, 0x6000
	s_cmp_eq_u32 s6, 0xc000
	s_cselect_b32 s6, 0, s7
	s_waitcnt lgkmcnt(10)
	v_mfma_f32_16x16x32_bf16 v[112:115], v[170:173], v[174:177], v[112:115]
	s_waitcnt lgkmcnt(9)
	v_mfma_f32_16x16x32_bf16 v[116:119], v[170:173], v[186:189], v[116:119]
	s_waitcnt lgkmcnt(8)
	v_mfma_f32_16x16x32_bf16 v[80:83], v[170:173], v[178:181], v[80:83]
	s_waitcnt lgkmcnt(7)
	v_mfma_f32_16x16x32_bf16 v[84:87], v[170:173], v[190:193], v[84:87]
	s_waitcnt lgkmcnt(6)
	v_mfma_f32_16x16x32_bf16 v[48:51], v[170:173], v[230:233], v[48:51]
	s_waitcnt lgkmcnt(5)
	v_mfma_f32_16x16x32_bf16 v[52:55], v[170:173], v[234:237], v[52:55]
	s_waitcnt lgkmcnt(4)
	v_mfma_f32_16x16x32_bf16 v[16:19], v[170:173], v[238:241], v[16:19]
	s_waitcnt lgkmcnt(3)
	v_mfma_f32_16x16x32_bf16 v[20:23], v[170:173], v[242:245], v[20:23]
	s_waitcnt lgkmcnt(2)
	v_mfma_f32_16x16x32_bf16 v[120:123], v[182:185], v[174:177], v[120:123]
	v_mfma_f32_16x16x32_bf16 v[124:127], v[182:185], v[186:189], v[124:127]
	v_mfma_f32_16x16x32_bf16 v[88:91], v[182:185], v[178:181], v[88:91]
	v_mfma_f32_16x16x32_bf16 v[92:95], v[182:185], v[190:193], v[92:95]
	v_mfma_f32_16x16x32_bf16 v[56:59], v[182:185], v[230:233], v[56:59]
	v_mfma_f32_16x16x32_bf16 v[60:63], v[182:185], v[234:237], v[60:63]
	v_mfma_f32_16x16x32_bf16 v[24:27], v[182:185], v[238:241], v[24:27]
	v_mfma_f32_16x16x32_bf16 v[28:31], v[182:185], v[242:245], v[28:31]
	s_waitcnt lgkmcnt(1)
	v_mfma_f32_16x16x32_bf16 v[96:99], v[222:225], v[174:177], v[96:99]
	v_mfma_f32_16x16x32_bf16 v[100:103], v[222:225], v[186:189], v[100:103]
	v_mfma_f32_16x16x32_bf16 v[64:67], v[222:225], v[178:181], v[64:67]
	v_mfma_f32_16x16x32_bf16 v[68:71], v[222:225], v[190:193], v[68:71]
	v_mfma_f32_16x16x32_bf16 v[32:35], v[222:225], v[230:233], v[32:35]
	v_mfma_f32_16x16x32_bf16 v[36:39], v[222:225], v[234:237], v[36:39]
	v_mfma_f32_16x16x32_bf16 v[0:3], v[222:225], v[238:241], v[0:3]
	v_mfma_f32_16x16x32_bf16 v[4:7], v[222:225], v[242:245], v[4:7]
	s_waitcnt lgkmcnt(0)
; __device__ __forceinline__ void h_main(f32x16 (&acc0)[2][2], f32x16 (&acc1)[2][2], const WideCtx& c, int nk, char* lds) {
;     ...
;       for (int nb = 0; nb < 2; ++nb)
; #pragma unroll
;         for (int tb = 0; tb < 2; ++tb) {
;           acc0[nb][tb] = __builtin_amdgcn_mfma_f32_32x32x16_bf16(wf[nb], a0[tb], acc0[nb][tb], 0, 0, 0);
;           acc1[nb][tb] = __builtin_amdgcn_mfma_f32_32x32x16_bf16(wf[nb], a1[tb], acc1[nb][tb], 0, 0, 0);
;         }
; template <class F>
; __device__ __forceinline__ void gemm_phase_w(const u16* A, int lda, int M, const u16* W, int K, int N, char* lds, int* ctr, F&& epi) {
;     ...
;     const int ctm = tm, ctn = tn;
;     par ^= 1;
;     if (c.tid == 0) bw[2 + par] = atomicAdd(myctr, 1);
	v_mfma_f32_16x16x32_bf16 v[104:107], v[226:229], v[174:177], v[104:107]
	v_mfma_f32_16x16x32_bf16 v[108:111], v[226:229], v[186:189], v[108:111]
	v_mfma_f32_16x16x32_bf16 v[72:75], v[226:229], v[178:181], v[72:75]
	v_mfma_f32_16x16x32_bf16 v[76:79], v[226:229], v[190:193], v[76:79]
	v_mfma_f32_16x16x32_bf16 v[40:43], v[226:229], v[230:233], v[40:43]
	v_mfma_f32_16x16x32_bf16 v[44:47], v[226:229], v[234:237], v[44:47]
	v_mfma_f32_16x16x32_bf16 v[8:11], v[226:229], v[238:241], v[8:11]
	v_mfma_f32_16x16x32_bf16 v[12:15], v[226:229], v[242:245], v[12:15]
	s_xor_b32 s53, s53, 1
	s_nop 7
	s_nop 7
	v_permlane16_swap_b32_e32 v112, v116
	v_permlane16_swap_b32_e32 v113, v117
	v_permlane16_swap_b32_e32 v114, v118
	v_permlane16_swap_b32_e32 v115, v119
	v_permlane16_swap_b32_e32 v120, v124
	v_permlane16_swap_b32_e32 v121, v125
	v_permlane16_swap_b32_e32 v122, v126
	v_permlane16_swap_b32_e32 v123, v127
	v_permlane16_swap_b32_e32 v80, v84
	v_permlane16_swap_b32_e32 v81, v85
	v_permlane16_swap_b32_e32 v82, v86
	v_permlane16_swap_b32_e32 v83, v87
	v_permlane16_swap_b32_e32 v88, v92
	v_permlane16_swap_b32_e32 v89, v93
	v_permlane16_swap_b32_e32 v90, v94
	v_permlane16_swap_b32_e32 v91, v95
	v_permlane16_swap_b32_e32 v48, v52
	v_permlane16_swap_b32_e32 v49, v53
	v_permlane16_swap_b32_e32 v50, v54
	v_permlane16_swap_b32_e32 v51, v55
	v_permlane16_swap_b32_e32 v56, v60
	v_permlane16_swap_b32_e32 v57, v61
	v_permlane16_swap_b32_e32 v58, v62
	v_permlane16_swap_b32_e32 v59, v63
	v_permlane16_swap_b32_e32 v16, v20
	v_permlane16_swap_b32_e32 v17, v21
	v_permlane16_swap_b32_e32 v18, v22
	v_permlane16_swap_b32_e32 v19, v23
	v_permlane16_swap_b32_e32 v24, v28
	v_permlane16_swap_b32_e32 v25, v29
	v_permlane16_swap_b32_e32 v26, v30
	v_permlane16_swap_b32_e32 v27, v31
	v_permlane16_swap_b32_e32 v96, v100
	v_permlane16_swap_b32_e32 v97, v101
	v_permlane16_swap_b32_e32 v98, v102
	v_permlane16_swap_b32_e32 v99, v103
	v_permlane16_swap_b32_e32 v104, v108
	v_permlane16_swap_b32_e32 v105, v109
	v_permlane16_swap_b32_e32 v106, v110
	v_permlane16_swap_b32_e32 v107, v111
	v_permlane16_swap_b32_e32 v64, v68
	v_permlane16_swap_b32_e32 v65, v69
	v_permlane16_swap_b32_e32 v66, v70
	v_permlane16_swap_b32_e32 v67, v71
	v_permlane16_swap_b32_e32 v72, v76
	v_permlane16_swap_b32_e32 v73, v77
	v_permlane16_swap_b32_e32 v74, v78
	v_permlane16_swap_b32_e32 v75, v79
	v_permlane16_swap_b32_e32 v32, v36
	v_permlane16_swap_b32_e32 v33, v37
	v_permlane16_swap_b32_e32 v34, v38
	v_permlane16_swap_b32_e32 v35, v39
	v_permlane16_swap_b32_e32 v40, v44
	v_permlane16_swap_b32_e32 v41, v45
	v_permlane16_swap_b32_e32 v42, v46
	v_permlane16_swap_b32_e32 v43, v47
	v_permlane16_swap_b32_e32 v0, v4
	v_permlane16_swap_b32_e32 v1, v5
	v_permlane16_swap_b32_e32 v2, v6
	v_permlane16_swap_b32_e32 v3, v7
	v_permlane16_swap_b32_e32 v8, v12
	v_permlane16_swap_b32_e32 v9, v13
	v_permlane16_swap_b32_e32 v10, v14
	v_permlane16_swap_b32_e32 v11, v15
	v_permlane32_swap_b32_e32 v112, v116
	v_permlane32_swap_b32_e32 v113, v117
	v_permlane32_swap_b32_e32 v114, v118
	v_permlane32_swap_b32_e32 v115, v119
	v_permlane32_swap_b32_e32 v120, v124
	v_permlane32_swap_b32_e32 v121, v125
	v_permlane32_swap_b32_e32 v122, v126
	v_permlane32_swap_b32_e32 v123, v127
	v_permlane32_swap_b32_e32 v80, v84
	v_permlane32_swap_b32_e32 v81, v85
	v_permlane32_swap_b32_e32 v82, v86
	v_permlane32_swap_b32_e32 v83, v87
	v_permlane32_swap_b32_e32 v88, v92
	v_permlane32_swap_b32_e32 v89, v93
	v_permlane32_swap_b32_e32 v90, v94
	v_permlane32_swap_b32_e32 v91, v95
	v_permlane32_swap_b32_e32 v48, v52
	v_permlane32_swap_b32_e32 v49, v53
	v_permlane32_swap_b32_e32 v50, v54
	v_permlane32_swap_b32_e32 v51, v55
	v_permlane32_swap_b32_e32 v56, v60
	v_permlane32_swap_b32_e32 v57, v61
	v_permlane32_swap_b32_e32 v58, v62
	v_permlane32_swap_b32_e32 v59, v63
	v_permlane32_swap_b32_e32 v16, v20
	v_permlane32_swap_b32_e32 v17, v21
	v_permlane32_swap_b32_e32 v18, v22
	v_permlane32_swap_b32_e32 v19, v23
	v_permlane32_swap_b32_e32 v24, v28
	v_permlane32_swap_b32_e32 v25, v29
	v_permlane32_swap_b32_e32 v26, v30
	v_permlane32_swap_b32_e32 v27, v31
	v_permlane32_swap_b32_e32 v96, v100
	v_permlane32_swap_b32_e32 v97, v101
	v_permlane32_swap_b32_e32 v98, v102
	v_permlane32_swap_b32_e32 v99, v103
	v_permlane32_swap_b32_e32 v104, v108
	v_permlane32_swap_b32_e32 v105, v109
	v_permlane32_swap_b32_e32 v106, v110
	v_permlane32_swap_b32_e32 v107, v111
	v_permlane32_swap_b32_e32 v64, v68
	v_permlane32_swap_b32_e32 v65, v69
	v_permlane32_swap_b32_e32 v66, v70
	v_permlane32_swap_b32_e32 v67, v71
	v_permlane32_swap_b32_e32 v72, v76
	v_permlane32_swap_b32_e32 v73, v77
	v_permlane32_swap_b32_e32 v74, v78
	v_permlane32_swap_b32_e32 v75, v79
	v_permlane32_swap_b32_e32 v32, v36
	v_permlane32_swap_b32_e32 v33, v37
	v_permlane32_swap_b32_e32 v34, v38
	v_permlane32_swap_b32_e32 v35, v39
	v_permlane32_swap_b32_e32 v40, v44
	v_permlane32_swap_b32_e32 v41, v45
	v_permlane32_swap_b32_e32 v42, v46
	v_permlane32_swap_b32_e32 v43, v47
	v_permlane32_swap_b32_e32 v0, v4
	v_permlane32_swap_b32_e32 v1, v5
	v_permlane32_swap_b32_e32 v2, v6
	v_permlane32_swap_b32_e32 v3, v7
	v_permlane32_swap_b32_e32 v8, v12
	v_permlane32_swap_b32_e32 v9, v13
	v_permlane32_swap_b32_e32 v10, v14
	v_permlane32_swap_b32_e32 v11, v15
	s_and_saveexec_b64 s[6:7], vcc
	s_cbranch_execz .LBB0_116
	s_mov_b64 s[34:35], exec
	v_mbcnt_lo_u32_b32 v144, s34, 0
	v_mbcnt_hi_u32_b32 v144, s35, v144
	v_cmp_eq_u32_e64 s[38:39], 0, v144
	s_and_saveexec_b64 s[0:1], s[38:39]
	s_cbranch_execz .LBB0_115
	s_bcnt1_i32_b64 s9, s[34:35]
	v_mov_b32_e32 v145, s9
	global_atomic_add v145, v161, v145, s[30:31] offset:256 sc0

; __device__ __forceinline__ void h_main(f32x16 (&acc0)[2][2], f32x16 (&acc1)[2][2], const WideCtx& c, int nk, char* lds) {
;   const int h = c.h;
;   for (int kt = 0; kt < nk; ++kt) {
;     asm volatile("s_waitcnt vmcnt(0)" ::: "memory");
;     __builtin_amdgcn_s_barrier();
;     if (kt + 1 < nk) h_stage(c, kt + 1);
;     const char* st = lds + (kt & 1) * 24576;
; #pragma unroll
;     for (int ks = 0; ks < 2; ++ks) {
;       bf16x8 wf[2], a0[2], a1[2];
; #pragma unroll
;       for (int b = 0; b < 2; ++b) {
;         wf[b] = *(const bf16x8*)(st + c.wro[b] + (((ks * 2 + h) ^ c.wsw[b]) << 4));
;         a0[b] = *(const bf16x8*)(st + c.aro[0][b] + (((ks * 2 + h) ^ c.asw[0][b]) << 4));
;         a1[b] = *(const bf16x8*)(st + c.aro[1][b] + (((ks * 2 + h) ^ c.asw[1][b]) << 4));
;       }
; #pragma unroll
;       for (int nb = 0; nb < 2; ++nb)
; #pragma unroll
;         for (int tb = 0; tb < 2; ++tb) {
;           acc0[nb][tb] = __builtin_amdgcn_mfma_f32_32x32x16_bf16(wf[nb], a0[tb], acc0[nb][tb], 0, 0, 0);
;           acc1[nb][tb] = __builtin_amdgcn_mfma_f32_32x32x16_bf16(wf[nb], a1[tb], acc1[nb][tb], 0, 0, 0);
;         }
;     }
;   }
; }
; __device__ void run_phase(CP& p, int ph, char* lds) {
;     ...
;           auto epi = [&](const f32x16 (&acc)[2][2], int tbase) {
; #pragma unroll
;             for (int tb = 0; tb < 2; ++tb) {
;               const int tok = tbase + tb * 32 + l32;
;               if (tok < M) {
;                 const u16* gp = p.P + (size_t)tok * NIN + 6528 + pass * 1024 + nbase + 4 * h;
;                 u16* dst = p.MERGED + (size_t)tok * 1024 + nbase + 4 * h;
; #pragma unroll
;                 for (int nb = 0; nb < 2; ++nb)
; #pragma unroll
;                   for (int i = 0; i < 4; ++i) {
;                     const u32x2 ga = *(const u32x2*)(gp + nb * 32 + 8 * i);
;                     float o0 = sigm(bf_lo(ga.x)) * acc[nb][tb][4 * i];
;                     float o1 = sigm(bf_hi(ga.x)) * acc[nb][tb][4 * i + 1];
;                     float o2 = sigm(bf_lo(ga.y)) * acc[nb][tb][4 * i + 2];
;                     float o3 = sigm(bf_hi(ga.y)) * acc[nb][tb][4 * i + 3];
;                     if (pass) {
;                       const u32x2 pv = *(const u32x2*)(dst + nb * 32 + 8 * i);
;                       o0 += bf_lo(pv.x); o1 += bf_hi(pv.x); o2 += bf_lo(pv.y); o3 += bf_hi(pv.y);
;                     }
.LBB0_146:
	s_bitcmp1_b32 s6, 0
	s_cselect_b32 s7, 0x6000, 0
	s_waitcnt vmcnt(0)
	s_barrier
	s_cselect_b32 s9, 0, 0x6000
	s_add_i32 s7, s7, s10
	s_mov_b32 s24, m0
	s_mov_b32 m0, s7
	s_nop 0
	global_load_lds_dwordx4 v[172:173], off
	s_mov_b32 m0, s24
	s_add_i32 s24, s7, 0x1000
	s_mov_b32 s25, m0
	s_mov_b32 m0, s24
	s_nop 0
	global_load_lds_dwordx4 v[170:171], off
	s_mov_b32 m0, s25
	s_add_i32 s24, s7, 0x2000
	s_mov_b32 s25, m0
	s_mov_b32 m0, s24
	s_nop 0
	global_load_lds_dwordx4 v[168:169], off
	s_mov_b32 m0, s25
	s_add_i32 s24, s7, 0x3000
	s_mov_b32 s25, m0
	s_mov_b32 m0, s24
	s_nop 0
	global_load_lds_dwordx4 v[166:167], off
	s_mov_b32 m0, s25
	s_add_i32 s24, s7, 0x4000
	s_mov_b32 s25, m0
	s_mov_b32 m0, s24
	s_nop 0
	global_load_lds_dwordx4 v[164:165], off
	s_mov_b32 m0, s25
	v_or_b32_e32 v129, s9, v163
	s_addk_i32 s7, 0x5000
	s_mov_b32 s24, m0
	s_mov_b32 m0, s7
	s_nop 0
	global_load_lds_dwordx4 v[158:159], off
	s_mov_b32 m0, s24
	v_add_u32_e32 v196, v129, v180
	ds_read_b128 v[184:187], v196
	v_add_u32_e32 v221, s9, v174
	v_add_u32_e32 v222, v221, v180
	ds_read_b128 v[188:191], v222 offset:8192
	ds_read_b128 v[192:195], v222 offset:16384
	ds_read_b128 v[196:199], v196 offset:2048
	ds_read_b128 v[200:203], v222 offset:10240
	ds_read_b128 v[222:225], v222 offset:18432
	v_add_u32_e32 v129, v129, v181
	s_waitcnt lgkmcnt(4)
	v_mfma_f32_32x32x16_bf16 v[112:127], v[184:187], v[188:191], v[112:127]
	v_add_u32_e32 v221, v221, v181
	s_add_i32 s6, s6, 1
	v_lshl_add_u64 v[158:159], v[158:159], 0, 64
	v_lshl_add_u64 v[164:165], v[164:165], 0, 64
	v_lshl_add_u64 v[166:167], v[166:167], 0, 64
	v_lshl_add_u64 v[168:169], v[168:169], 0, 64
	v_lshl_add_u64 v[170:171], v[170:171], 0, 64
	s_waitcnt lgkmcnt(3)
	v_mfma_f32_32x32x16_bf16 v[48:63], v[184:187], v[192:195], v[48:63]
	v_lshl_add_u64 v[172:173], v[172:173], 0, 64
	s_cmp_eq_u32 s6, 32
	s_waitcnt lgkmcnt(1)
	v_mfma_f32_32x32x16_bf16 v[80:95], v[184:187], v[200:203], v[80:95]
	s_waitcnt lgkmcnt(0)
	v_mfma_f32_32x32x16_bf16 v[16:31], v[184:187], v[222:225], v[16:31]
	ds_read_b128 v[184:187], v129
	v_mfma_f32_32x32x16_bf16 v[96:111], v[196:199], v[188:191], v[96:111]
	v_mfma_f32_32x32x16_bf16 v[32:47], v[196:199], v[192:195], v[32:47]
	v_mfma_f32_32x32x16_bf16 v[64:79], v[196:199], v[200:203], v[64:79]
	v_mfma_f32_32x32x16_bf16 v[0:15], v[196:199], v[222:225], v[0:15]
	ds_read_b128 v[188:191], v221 offset:8192
	ds_read_b128 v[192:195], v221 offset:16384
	ds_read_b128 v[196:199], v129 offset:2048
	ds_read_b128 v[200:203], v221 offset:10240
	ds_read_b128 v[222:225], v221 offset:18432
	s_waitcnt lgkmcnt(4)
	v_mfma_f32_32x32x16_bf16 v[112:127], v[184:187], v[188:191], v[112:127]
	s_waitcnt lgkmcnt(3)
	v_mfma_f32_32x32x16_bf16 v[48:63], v[184:187], v[192:195], v[48:63]
	s_waitcnt lgkmcnt(1)
	v_mfma_f32_32x32x16_bf16 v[80:95], v[184:187], v[200:203], v[80:95]
	s_waitcnt lgkmcnt(0)
	v_mfma_f32_32x32x16_bf16 v[16:31], v[184:187], v[222:225], v[16:31]
	v_mfma_f32_32x32x16_bf16 v[96:111], v[196:199], v[188:191], v[96:111]
	v_mfma_f32_32x32x16_bf16 v[32:47], v[196:199], v[192:195], v[32:47]
	v_mfma_f32_32x32x16_bf16 v[64:79], v[196:199], v[200:203], v[64:79]
	v_mfma_f32_32x32x16_bf16 v[0:15], v[196:199], v[222:225], v[0:15]
	s_cbranch_scc0 .LBB0_146
	v_add_u32_e32 v129, v163, v180
	s_waitcnt vmcnt(0)
	s_barrier
	ds_read_b128 v[164:167], v129 offset:24576
	v_add_u32_e32 v158, v174, v180
	ds_read_b128 v[168:171], v158 offset:32768
	ds_read_b128 v[184:187], v158 offset:40960
	ds_read_b128 v[188:191], v158 offset:34816
	ds_read_b128 v[192:195], v158 offset:43008
	v_add_u32_e32 v158, v174, v181
	s_waitcnt lgkmcnt(3)
	v_mfma_f32_32x32x16_bf16 v[112:127], v[164:167], v[168:171], v[112:127]
	s_waitcnt lgkmcnt(2)
	v_mfma_f32_32x32x16_bf16 v[48:63], v[164:167], v[184:187], v[48:63]
	s_waitcnt lgkmcnt(1)
	v_mfma_f32_32x32x16_bf16 v[80:95], v[164:167], v[188:191], v[80:95]
	s_waitcnt lgkmcnt(0)
	v_mfma_f32_32x32x16_bf16 v[16:31], v[164:167], v[192:195], v[16:31]
	ds_read_b128 v[164:167], v129 offset:26624
	v_add_u32_e32 v129, v163, v181
	s_waitcnt lgkmcnt(0)
	v_mfma_f32_32x32x16_bf16 v[96:111], v[164:167], v[168:171], v[96:111]
	ds_read_b128 v[168:171], v158 offset:32768
	v_mfma_f32_32x32x16_bf16 v[32:47], v[164:167], v[184:187], v[32:47]
	ds_read_b128 v[184:187], v158 offset:40960
	v_mfma_f32_32x32x16_bf16 v[64:79], v[164:167], v[188:191], v[64:79]
	ds_read_b128 v[188:191], v158 offset:34816
	v_mfma_f32_32x32x16_bf16 v[0:15], v[164:167], v[192:195], v[0:15]
	ds_read_b128 v[164:167], v129 offset:24576
	ds_read_b128 v[192:195], v158 offset:43008
	s_waitcnt lgkmcnt(1)
	v_mfma_f32_32x32x16_bf16 v[112:127], v[164:167], v[168:171], v[112:127]
	v_mfma_f32_32x32x16_bf16 v[48:63], v[164:167], v[184:187], v[48:63]
	v_mfma_f32_32x32x16_bf16 v[80:95], v[164:167], v[188:191], v[80:95]
	s_waitcnt lgkmcnt(0)
	v_mfma_f32_32x32x16_bf16 v[16:31], v[164:167], v[192:195], v[16:31]
	ds_read_b128 v[164:167], v129 offset:26624
	v_cndmask_b32_e64 v129, 0, 1, s[48:49]
	v_cmp_ne_u32_e64 s[46:47], 1, v129
	s_waitcnt lgkmcnt(0)
	v_mfma_f32_32x32x16_bf16 v[96:111], v[164:167], v[168:171], v[96:111]
	v_mfma_f32_32x32x16_bf16 v[32:47], v[164:167], v[184:187], v[32:47]
	v_mfma_f32_32x32x16_bf16 v[64:79], v[164:167], v[188:191], v[64:79]
	v_mfma_f32_32x32x16_bf16 v[0:15], v[164:167], v[192:195], v[0:15]
	s_and_saveexec_b64 s[34:35], s[38:39]
	s_cbranch_execz .LBB0_183
	v_lshl_add_u64 v[158:159], s[50:51], 1, v[142:143]
	global_load_dwordx2 v[226:227], v[158:159], off
	global_load_dwordx2 v[228:229], v[158:159], off offset:16
	global_load_dwordx2 v[230:231], v[158:159], off offset:32
	global_load_dwordx2 v[232:233], v[158:159], off offset:48
	global_load_dwordx2 v[234:235], v[158:159], off offset:64
	global_load_dwordx2 v[236:237], v[158:159], off offset:80
	global_load_dwordx2 v[238:239], v[158:159], off offset:96
	global_load_dwordx2 v[240:241], v[158:159], off offset:112
	s_and_b64 vcc, exec, s[46:47]
	s_cbranch_vccnz .Lmg_skip_0
	global_load_dwordx2 v[184:185], v[144:145], off
	global_load_dwordx2 v[186:187], v[144:145], off offset:16
	global_load_dwordx2 v[188:189], v[144:145], off offset:32
	global_load_dwordx2 v[190:191], v[144:145], off offset:48
	global_load_dwordx2 v[192:193], v[144:145], off offset:64
	global_load_dwordx2 v[194:195], v[144:145], off offset:80
	global_load_dwordx2 v[168:169], v[144:145], off offset:96
	global_load_dwordx2 v[170:171], v[144:145], off offset:112
; __device__ __forceinline__ float bf_lo(unsigned u) { return __uint_as_float(u << 16); }
; __device__ __forceinline__ float bf_hi(unsigned u) { return __uint_as_float(u & 0xffff0000u); }
; __device__ __forceinline__ float sigm(float x) { return __builtin_amdgcn_rcpf(1.f + __builtin_amdgcn_exp2f(-LOG2E * x)); }
; __device__ void run_phase(CP& p, int ph, char* lds) {
;     ...
;                 const u16* gp = p.P + (size_t)tok * NIN + 6528 + pass * 1024 + nbase + 4 * h;
;                 u16* dst = p.MERGED + (size_t)tok * 1024 + nbase + 4 * h;
; #pragma unroll
;                 for (int nb = 0; nb < 2; ++nb)
; #pragma unroll
;                   for (int i = 0; i < 4; ++i) {
;                     const u32x2 ga = *(const u32x2*)(gp + nb * 32 + 8 * i);
;                     float o0 = sigm(bf_lo(ga.x)) * acc[nb][tb][4 * i];
;                     float o1 = sigm(bf_hi(ga.x)) * acc[nb][tb][4 * i + 1];
;                     float o2 = sigm(bf_lo(ga.y)) * acc[nb][tb][4 * i + 2];
;                     float o3 = sigm(bf_hi(ga.y)) * acc[nb][tb][4 * i + 3];
;                     if (pass) {
;                       const u32x2 pv = *(const u32x2*)(dst + nb * 32 + 8 * i);
;                       o0 += bf_lo(pv.x); o1 += bf_hi(pv.x); o2 += bf_lo(pv.y); o3 += bf_hi(pv.y);
;                     }
;                     *(u32x2*)(dst + nb * 32 + 8 * i) = (u32x2){pk_bf16(o0, o1), pk_bf16(o2, o3)};
.Lmg_skip_0:
	s_and_b64 vcc, exec, s[46:47]
	s_waitcnt vmcnt(7)
	v_lshlrev_b32_e32 v129, 16, v226
	v_mul_f32_e32 v129, 0xbfb8aa3b, v129
	v_exp_f32_e32 v129, v129
	s_nop 0
	v_add_f32_e32 v129, 1.0, v129
	v_rcp_f32_e32 v166, v129
	v_and_b32_e32 v129, 0xffff0000, v226
	v_mul_f32_e32 v129, 0xbfb8aa3b, v129
	v_exp_f32_e32 v129, v129
	s_nop 0
	v_add_f32_e32 v129, 1.0, v129
	v_rcp_f32_e32 v167, v129
	v_lshlrev_b32_e32 v129, 16, v227
	v_mul_f32_e32 v129, 0xbfb8aa3b, v129
	v_exp_f32_e32 v129, v129
	v_pk_mul_f32 v[112:113], v[112:113], v[166:167]
	v_add_f32_e32 v129, 1.0, v129
	v_rcp_f32_e32 v164, v129
	v_and_b32_e32 v129, 0xffff0000, v227
	v_mul_f32_e32 v129, 0xbfb8aa3b, v129
	v_exp_f32_e32 v129, v129
	s_nop 0
	v_add_f32_e32 v129, 1.0, v129
	v_rcp_f32_e32 v165, v129
	s_nop 0
	v_pk_mul_f32 v[114:115], v[114:115], v[164:165]
	s_cbranch_vccnz .LBB0_150
	s_nop 0
	s_waitcnt vmcnt(7)
	v_lshlrev_b32_e32 v166, 16, v184
	v_and_b32_e32 v167, 0xffff0000, v184
	v_lshlrev_b32_e32 v164, 16, v185
	v_and_b32_e32 v165, 0xffff0000, v185
	v_pk_add_f32 v[112:113], v[112:113], v[166:167]
	v_pk_add_f32 v[114:115], v[114:115], v[164:165]
.LBB0_150:
	v_cvt_pk_bf16_f32 v112, v112, v113
	v_cvt_pk_bf16_f32 v113, v114, v115
	global_store_dwordx2 v[144:145], v[112:113], off
	s_nop 0
	s_and_b64 vcc, exec, s[46:47]
	s_waitcnt vmcnt(7)
	v_lshlrev_b32_e32 v112, 16, v228
	v_and_b32_e32 v113, 0xffff0000, v228
	v_lshlrev_b32_e32 v114, 16, v229
	v_and_b32_e32 v115, 0xffff0000, v229
	v_mul_f32_e32 v112, 0xbfb8aa3b, v112
	v_mul_f32_e32 v113, 0xbfb8aa3b, v113
	v_mul_f32_e32 v114, 0xbfb8aa3b, v114
	v_mul_f32_e32 v115, 0xbfb8aa3b, v115
	v_exp_f32_e32 v112, v112
	v_exp_f32_e32 v113, v113
	v_exp_f32_e32 v114, v114
	v_exp_f32_e32 v115, v115
	v_add_f32_e32 v112, 1.0, v112
	v_add_f32_e32 v113, 1.0, v113
	v_add_f32_e32 v114, 1.0, v114
	v_add_f32_e32 v115, 1.0, v115
	v_rcp_f32_e32 v112, v112
	v_rcp_f32_e32 v113, v113
	v_rcp_f32_e32 v114, v114
	v_rcp_f32_e32 v115, v115
	v_pk_mul_f32 v[112:113], v[116:117], v[112:113]
	v_pk_mul_f32 v[114:115], v[118:119], v[114:115]
	s_cbranch_vccnz .LBB0_152
	s_nop 0
	s_waitcnt vmcnt(7)
	v_lshlrev_b32_e32 v118, 16, v186
	v_and_b32_e32 v119, 0xffff0000, v186
	v_lshlrev_b32_e32 v116, 16, v187
	v_and_b32_e32 v117, 0xffff0000, v187
	v_pk_add_f32 v[112:113], v[112:113], v[118:119]
	v_pk_add_f32 v[114:115], v[114:115], v[116:117]
.LBB0_152:
	v_cvt_pk_bf16_f32 v112, v112, v113
	v_cvt_pk_bf16_f32 v113, v114, v115
	global_store_dwordx2 v[144:145], v[112:113], off offset:16
	s_nop 0
	s_and_b64 vcc, exec, s[46:47]
	s_waitcnt vmcnt(7)
	v_lshlrev_b32_e32 v112, 16, v230
	v_and_b32_e32 v113, 0xffff0000, v230
	v_lshlrev_b32_e32 v114, 16, v231
	v_and_b32_e32 v115, 0xffff0000, v231
	v_mul_f32_e32 v112, 0xbfb8aa3b, v112
	v_mul_f32_e32 v113, 0xbfb8aa3b, v113
	v_mul_f32_e32 v114, 0xbfb8aa3b, v114
	v_mul_f32_e32 v115, 0xbfb8aa3b, v115
	v_exp_f32_e32 v112, v112
	v_exp_f32_e32 v113, v113
	v_exp_f32_e32 v114, v114
	v_exp_f32_e32 v115, v115
	v_add_f32_e32 v112, 1.0, v112
	v_add_f32_e32 v113, 1.0, v113
	v_add_f32_e32 v114, 1.0, v114
	v_add_f32_e32 v115, 1.0, v115
	v_rcp_f32_e32 v112, v112
	v_rcp_f32_e32 v113, v113
	v_rcp_f32_e32 v114, v114
	v_rcp_f32_e32 v115, v115
	v_pk_mul_f32 v[112:113], v[120:121], v[112:113]
	v_pk_mul_f32 v[114:115], v[122:123], v[114:115]
	s_cbranch_vccnz .LBB0_154
	s_nop 0
	s_waitcnt vmcnt(7)
	v_lshlrev_b32_e32 v118, 16, v188
	v_and_b32_e32 v119, 0xffff0000, v188
	v_lshlrev_b32_e32 v116, 16, v189
	v_and_b32_e32 v117, 0xffff0000, v189
	v_pk_add_f32 v[112:113], v[112:113], v[118:119]
	v_pk_add_f32 v[114:115], v[114:115], v[116:117]
.LBB0_154:
	v_cvt_pk_bf16_f32 v112, v112, v113
	v_cvt_pk_bf16_f32 v113, v114, v115
	global_store_dwordx2 v[144:145], v[112:113], off offset:32
	s_nop 0
	s_and_b64 vcc, exec, s[46:47]
	s_waitcnt vmcnt(7)
	v_lshlrev_b32_e32 v112, 16, v232
	v_and_b32_e32 v113, 0xffff0000, v232
	v_lshlrev_b32_e32 v114, 16, v233
	v_and_b32_e32 v115, 0xffff0000, v233
	v_mul_f32_e32 v112, 0xbfb8aa3b, v112
	v_mul_f32_e32 v113, 0xbfb8aa3b, v113
	v_mul_f32_e32 v114, 0xbfb8aa3b, v114
	v_mul_f32_e32 v115, 0xbfb8aa3b, v115
	v_exp_f32_e32 v112, v112
	v_exp_f32_e32 v113, v113
	v_exp_f32_e32 v114, v114
	v_exp_f32_e32 v115, v115
	v_add_f32_e32 v112, 1.0, v112
	v_add_f32_e32 v113, 1.0, v113
	v_add_f32_e32 v114, 1.0, v114
	v_add_f32_e32 v115, 1.0, v115
	v_rcp_f32_e32 v112, v112
	v_rcp_f32_e32 v113, v113
	v_rcp_f32_e32 v114, v114
	v_rcp_f32_e32 v115, v115
	v_pk_mul_f32 v[112:113], v[124:125], v[112:113]
	v_pk_mul_f32 v[114:115], v[126:127], v[114:115]
	s_cbranch_vccnz .LBB0_156
	s_nop 0
	s_waitcnt vmcnt(7)
	v_lshlrev_b32_e32 v118, 16, v190
	v_and_b32_e32 v119, 0xffff0000, v190
	v_lshlrev_b32_e32 v116, 16, v191
	v_and_b32_e32 v117, 0xffff0000, v191
	v_pk_add_f32 v[112:113], v[112:113], v[118:119]
	v_pk_add_f32 v[114:115], v[114:115], v[116:117]
; __device__ __forceinline__ float bf_lo(unsigned u) { return __uint_as_float(u << 16); }
; __device__ __forceinline__ float bf_hi(unsigned u) { return __uint_as_float(u & 0xffff0000u); }
; __device__ __forceinline__ float sigm(float x) { return __builtin_amdgcn_rcpf(1.f + __builtin_amdgcn_exp2f(-LOG2E * x)); }
; __device__ void run_phase(CP& p, int ph, char* lds) {
;     ...
;                 const u16* gp = p.P + (size_t)tok * NIN + 6528 + pass * 1024 + nbase + 4 * h;
;                 u16* dst = p.MERGED + (size_t)tok * 1024 + nbase + 4 * h;
; #pragma unroll
;                 for (int nb = 0; nb < 2; ++nb)
; #pragma unroll
;                   for (int i = 0; i < 4; ++i) {
;                     const u32x2 ga = *(const u32x2*)(gp + nb * 32 + 8 * i);
;                     float o0 = sigm(bf_lo(ga.x)) * acc[nb][tb][4 * i];
;                     float o1 = sigm(bf_hi(ga.x)) * acc[nb][tb][4 * i + 1];
;                     float o2 = sigm(bf_lo(ga.y)) * acc[nb][tb][4 * i + 2];
;                     float o3 = sigm(bf_hi(ga.y)) * acc[nb][tb][4 * i + 3];
;                     if (pass) {
;                       const u32x2 pv = *(const u32x2*)(dst + nb * 32 + 8 * i);
;                       o0 += bf_lo(pv.x); o1 += bf_hi(pv.x); o2 += bf_lo(pv.y); o3 += bf_hi(pv.y);
;                     }
;                     *(u32x2*)(dst + nb * 32 + 8 * i) = (u32x2){pk_bf16(o0, o1), pk_bf16(o2, o3)};
.LBB0_156:
	v_cvt_pk_bf16_f32 v112, v112, v113
	v_cvt_pk_bf16_f32 v113, v114, v115
	global_store_dwordx2 v[144:145], v[112:113], off offset:48
	s_nop 0
	s_and_b64 vcc, exec, s[46:47]
	s_waitcnt vmcnt(7)
	v_lshlrev_b32_e32 v114, 16, v234
	v_and_b32_e32 v112, 0xffff0000, v234
	v_mul_f32_e32 v112, 0xbfb8aa3b, v112
	v_exp_f32_e32 v112, v112
	v_mul_f32_e32 v114, 0xbfb8aa3b, v114
	v_exp_f32_e32 v114, v114
	v_add_f32_e32 v112, 1.0, v112
	v_rcp_f32_e32 v115, v112
	v_lshlrev_b32_e32 v112, 16, v235
	v_and_b32_e32 v113, 0xffff0000, v235
	v_mul_f32_e32 v112, 0xbfb8aa3b, v112
	v_mul_f32_e32 v113, 0xbfb8aa3b, v113
	v_exp_f32_e32 v112, v112
	v_exp_f32_e32 v113, v113
	v_add_f32_e32 v114, 1.0, v114
	v_rcp_f32_e32 v114, v114
	v_add_f32_e32 v112, 1.0, v112
	v_add_f32_e32 v113, 1.0, v113
	v_rcp_f32_e32 v112, v112
	v_rcp_f32_e32 v113, v113
	v_pk_mul_f32 v[96:97], v[96:97], v[114:115]
	v_pk_mul_f32 v[98:99], v[98:99], v[112:113]
	s_cbranch_vccnz .LBB0_158
	s_nop 0
	s_waitcnt vmcnt(7)
	v_lshlrev_b32_e32 v114, 16, v192
	v_and_b32_e32 v115, 0xffff0000, v192
	v_lshlrev_b32_e32 v112, 16, v193
	v_and_b32_e32 v113, 0xffff0000, v193
	v_pk_add_f32 v[96:97], v[96:97], v[114:115]
	v_pk_add_f32 v[98:99], v[98:99], v[112:113]
.LBB0_158:
	v_cvt_pk_bf16_f32 v96, v96, v97
	v_cvt_pk_bf16_f32 v97, v98, v99
	global_store_dwordx2 v[144:145], v[96:97], off offset:64
	s_nop 0
	s_and_b64 vcc, exec, s[46:47]
	s_waitcnt vmcnt(7)
	v_lshlrev_b32_e32 v96, 16, v236
	v_and_b32_e32 v97, 0xffff0000, v236
	v_lshlrev_b32_e32 v98, 16, v237
	v_and_b32_e32 v99, 0xffff0000, v237
	v_mul_f32_e32 v96, 0xbfb8aa3b, v96
	v_mul_f32_e32 v97, 0xbfb8aa3b, v97
	v_mul_f32_e32 v98, 0xbfb8aa3b, v98
	v_mul_f32_e32 v99, 0xbfb8aa3b, v99
	v_exp_f32_e32 v96, v96
	v_exp_f32_e32 v97, v97
	v_exp_f32_e32 v98, v98
	v_exp_f32_e32 v99, v99
	v_add_f32_e32 v96, 1.0, v96
	v_add_f32_e32 v97, 1.0, v97
	v_add_f32_e32 v98, 1.0, v98
	v_add_f32_e32 v99, 1.0, v99
	v_rcp_f32_e32 v96, v96
	v_rcp_f32_e32 v97, v97
	v_rcp_f32_e32 v98, v98
	v_rcp_f32_e32 v99, v99
	v_pk_mul_f32 v[96:97], v[100:101], v[96:97]
	v_pk_mul_f32 v[98:99], v[102:103], v[98:99]
	s_cbranch_vccnz .LBB0_160
	s_nop 0
	s_waitcnt vmcnt(7)
	v_lshlrev_b32_e32 v102, 16, v194
	v_and_b32_e32 v103, 0xffff0000, v194
	v_lshlrev_b32_e32 v100, 16, v195
	v_and_b32_e32 v101, 0xffff0000, v195
	v_pk_add_f32 v[96:97], v[96:97], v[102:103]
	v_pk_add_f32 v[98:99], v[98:99], v[100:101]
.LBB0_160:
	v_cvt_pk_bf16_f32 v96, v96, v97
	v_cvt_pk_bf16_f32 v97, v98, v99
	global_store_dwordx2 v[144:145], v[96:97], off offset:80
	s_nop 0
	s_and_b64 vcc, exec, s[46:47]
	s_waitcnt vmcnt(7)
	v_lshlrev_b32_e32 v96, 16, v238
	v_and_b32_e32 v97, 0xffff0000, v238
	v_lshlrev_b32_e32 v98, 16, v239
	v_and_b32_e32 v99, 0xffff0000, v239
	v_mul_f32_e32 v96, 0xbfb8aa3b, v96
	v_mul_f32_e32 v97, 0xbfb8aa3b, v97
	v_mul_f32_e32 v98, 0xbfb8aa3b, v98
	v_mul_f32_e32 v99, 0xbfb8aa3b, v99
	v_exp_f32_e32 v96, v96
	v_exp_f32_e32 v97, v97
	v_exp_f32_e32 v98, v98
	v_exp_f32_e32 v99, v99
	v_add_f32_e32 v96, 1.0, v96
	v_add_f32_e32 v97, 1.0, v97
	v_add_f32_e32 v98, 1.0, v98
	v_add_f32_e32 v99, 1.0, v99
	v_rcp_f32_e32 v96, v96
	v_rcp_f32_e32 v97, v97
	v_rcp_f32_e32 v98, v98
	v_rcp_f32_e32 v99, v99
	v_pk_mul_f32 v[96:97], v[104:105], v[96:97]
	v_pk_mul_f32 v[98:99], v[106:107], v[98:99]
	s_cbranch_vccnz .LBB0_162
	s_nop 0
	s_waitcnt vmcnt(7)
	v_lshlrev_b32_e32 v102, 16, v168
	v_and_b32_e32 v103, 0xffff0000, v168
	v_lshlrev_b32_e32 v100, 16, v169
	v_and_b32_e32 v101, 0xffff0000, v169
	v_pk_add_f32 v[96:97], v[96:97], v[102:103]
	v_pk_add_f32 v[98:99], v[98:99], v[100:101]
.LBB0_162:
	v_cvt_pk_bf16_f32 v96, v96, v97
	v_cvt_pk_bf16_f32 v97, v98, v99
	global_store_dwordx2 v[144:145], v[96:97], off offset:96
	s_nop 0
	s_and_b64 vcc, exec, s[46:47]
	s_waitcnt vmcnt(7)
	v_lshlrev_b32_e32 v98, 16, v240
	v_and_b32_e32 v96, 0xffff0000, v240
	v_lshlrev_b32_e32 v99, 16, v241
	v_and_b32_e32 v97, 0xffff0000, v241
	v_mul_f32_e32 v98, 0xbfb8aa3b, v98
	v_mul_f32_e32 v96, 0xbfb8aa3b, v96
	v_mul_f32_e32 v99, 0xbfb8aa3b, v99
	v_mul_f32_e32 v97, 0xbfb8aa3b, v97
	v_exp_f32_e32 v98, v98
	v_exp_f32_e32 v96, v96
	v_exp_f32_e32 v99, v99
	v_exp_f32_e32 v97, v97
	v_add_f32_e32 v98, 1.0, v98
	v_add_f32_e32 v100, 1.0, v96
	v_add_f32_e32 v99, 1.0, v99
	v_add_f32_e32 v101, 1.0, v97
	v_rcp_f32_e32 v96, v98
	v_rcp_f32_e32 v97, v100
	v_rcp_f32_e32 v100, v99
	v_rcp_f32_e32 v101, v101
	v_pk_mul_f32 v[98:99], v[108:109], v[96:97]
	v_pk_mul_f32 v[96:97], v[110:111], v[100:101]
	s_cbranch_vccnz .LBB0_164
	s_nop 0
	s_waitcnt vmcnt(7)
	v_lshlrev_b32_e32 v102, 16, v170
	v_and_b32_e32 v103, 0xffff0000, v170
	v_lshlrev_b32_e32 v100, 16, v171
	v_and_b32_e32 v101, 0xffff0000, v171
	v_pk_add_f32 v[98:99], v[98:99], v[102:103]
	v_pk_add_f32 v[96:97], v[96:97], v[100:101]

; __device__ __forceinline__ float bf_lo(unsigned u) { return __uint_as_float(u << 16); }
; __device__ __forceinline__ float bf_hi(unsigned u) { return __uint_as_float(u & 0xffff0000u); }
; __device__ __forceinline__ float sigm(float x) { return __builtin_amdgcn_rcpf(1.f + __builtin_amdgcn_exp2f(-LOG2E * x)); }
; __device__ void run_phase(CP& p, int ph, char* lds) {
;     ...
;                 const u16* gp = p.P + (size_t)tok * NIN + 6528 + pass * 1024 + nbase + 4 * h;
;                 u16* dst = p.MERGED + (size_t)tok * 1024 + nbase + 4 * h;
; #pragma unroll
;                 for (int nb = 0; nb < 2; ++nb)
; #pragma unroll
;                   for (int i = 0; i < 4; ++i) {
;                     const u32x2 ga = *(const u32x2*)(gp + nb * 32 + 8 * i);
;                     float o0 = sigm(bf_lo(ga.x)) * acc[nb][tb][4 * i];
;                     float o1 = sigm(bf_hi(ga.x)) * acc[nb][tb][4 * i + 1];
;                     float o2 = sigm(bf_lo(ga.y)) * acc[nb][tb][4 * i + 2];
;                     float o3 = sigm(bf_hi(ga.y)) * acc[nb][tb][4 * i + 3];
;                     if (pass) {
;                       const u32x2 pv = *(const u32x2*)(dst + nb * 32 + 8 * i);
;                       o0 += bf_lo(pv.x); o1 += bf_hi(pv.x); o2 += bf_lo(pv.y); o3 += bf_hi(pv.y);
;                     }
;                     *(u32x2*)(dst + nb * 32 + 8 * i) = (u32x2){pk_bf16(o0, o1), pk_bf16(o2, o3)};
.LBB0_166:
	s_nop 2
	v_lshl_add_u64 v[64:65], s[50:51], 1, v[150:151]
	global_load_dwordx2 v[226:227], v[64:65], off
	global_load_dwordx2 v[228:229], v[64:65], off offset:16
	global_load_dwordx2 v[230:231], v[64:65], off offset:32
	global_load_dwordx2 v[232:233], v[64:65], off offset:48
	global_load_dwordx2 v[234:235], v[64:65], off offset:64
	global_load_dwordx2 v[236:237], v[64:65], off offset:80
	global_load_dwordx2 v[238:239], v[64:65], off offset:96
	global_load_dwordx2 v[240:241], v[64:65], off offset:112
	s_and_b64 vcc, exec, s[46:47]
	s_cbranch_vccnz .Lmg_skip_1
	global_load_dwordx2 v[184:185], v[152:153], off
	global_load_dwordx2 v[186:187], v[152:153], off offset:16
	global_load_dwordx2 v[188:189], v[152:153], off offset:32
	global_load_dwordx2 v[190:191], v[152:153], off offset:48
	global_load_dwordx2 v[192:193], v[152:153], off offset:64
	global_load_dwordx2 v[194:195], v[152:153], off offset:80
	global_load_dwordx2 v[168:169], v[152:153], off offset:96
	global_load_dwordx2 v[170:171], v[152:153], off offset:112
.Lmg_skip_1:
	s_and_b64 vcc, exec, s[46:47]
	s_waitcnt vmcnt(7)
	v_lshlrev_b32_e32 v68, 16, v226
	v_and_b32_e32 v66, 0xffff0000, v226
	v_mul_f32_e32 v66, 0xbfb8aa3b, v66
	v_exp_f32_e32 v66, v66
	v_mul_f32_e32 v68, 0xbfb8aa3b, v68
	v_exp_f32_e32 v68, v68
	v_add_f32_e32 v66, 1.0, v66
	v_rcp_f32_e32 v69, v66
	v_lshlrev_b32_e32 v66, 16, v227
	v_and_b32_e32 v67, 0xffff0000, v227
	v_mul_f32_e32 v66, 0xbfb8aa3b, v66
	v_mul_f32_e32 v67, 0xbfb8aa3b, v67
	v_exp_f32_e32 v66, v66
	v_exp_f32_e32 v67, v67
	v_add_f32_e32 v68, 1.0, v68
	v_rcp_f32_e32 v68, v68
	v_add_f32_e32 v66, 1.0, v66
	v_add_f32_e32 v67, 1.0, v67
	v_rcp_f32_e32 v66, v66
	v_rcp_f32_e32 v67, v67
	v_pk_mul_f32 v[48:49], v[48:49], v[68:69]
	v_pk_mul_f32 v[50:51], v[50:51], v[66:67]
	s_cbranch_vccnz .LBB0_168
	s_nop 0
	s_waitcnt vmcnt(7)
	v_lshlrev_b32_e32 v68, 16, v184
	v_and_b32_e32 v69, 0xffff0000, v184
	v_lshlrev_b32_e32 v66, 16, v185
	v_and_b32_e32 v67, 0xffff0000, v185
	v_pk_add_f32 v[48:49], v[48:49], v[68:69]
	v_pk_add_f32 v[50:51], v[50:51], v[66:67]
.LBB0_168:
	v_cvt_pk_bf16_f32 v48, v48, v49
	v_cvt_pk_bf16_f32 v49, v50, v51
	global_store_dwordx2 v[152:153], v[48:49], off
	s_nop 0
	s_and_b64 vcc, exec, s[46:47]
	s_waitcnt vmcnt(7)
	v_lshlrev_b32_e32 v48, 16, v228
	v_and_b32_e32 v49, 0xffff0000, v228
	v_lshlrev_b32_e32 v50, 16, v229
	v_and_b32_e32 v51, 0xffff0000, v229
	v_mul_f32_e32 v48, 0xbfb8aa3b, v48
	v_mul_f32_e32 v49, 0xbfb8aa3b, v49
	v_mul_f32_e32 v50, 0xbfb8aa3b, v50
	v_mul_f32_e32 v51, 0xbfb8aa3b, v51
	v_exp_f32_e32 v48, v48
	v_exp_f32_e32 v49, v49
	v_exp_f32_e32 v50, v50
	v_exp_f32_e32 v51, v51
	v_add_f32_e32 v48, 1.0, v48
	v_add_f32_e32 v49, 1.0, v49
	v_add_f32_e32 v50, 1.0, v50
	v_add_f32_e32 v51, 1.0, v51
	v_rcp_f32_e32 v48, v48
	v_rcp_f32_e32 v49, v49
	v_rcp_f32_e32 v50, v50
	v_rcp_f32_e32 v51, v51
	v_pk_mul_f32 v[48:49], v[52:53], v[48:49]
	v_pk_mul_f32 v[50:51], v[54:55], v[50:51]
	s_cbranch_vccnz .LBB0_170
	s_nop 0
	s_waitcnt vmcnt(7)
	v_lshlrev_b32_e32 v54, 16, v186
	v_and_b32_e32 v55, 0xffff0000, v186
	v_lshlrev_b32_e32 v52, 16, v187
	v_and_b32_e32 v53, 0xffff0000, v187
	v_pk_add_f32 v[48:49], v[48:49], v[54:55]
	v_pk_add_f32 v[50:51], v[50:51], v[52:53]
.LBB0_170:
	v_cvt_pk_bf16_f32 v48, v48, v49
	v_cvt_pk_bf16_f32 v49, v50, v51
	global_store_dwordx2 v[152:153], v[48:49], off offset:16
	s_nop 0
	s_and_b64 vcc, exec, s[46:47]
	s_waitcnt vmcnt(7)
	v_lshlrev_b32_e32 v48, 16, v230
	v_and_b32_e32 v49, 0xffff0000, v230
	v_lshlrev_b32_e32 v50, 16, v231
	v_and_b32_e32 v51, 0xffff0000, v231
	v_mul_f32_e32 v48, 0xbfb8aa3b, v48
	v_mul_f32_e32 v49, 0xbfb8aa3b, v49
	v_mul_f32_e32 v50, 0xbfb8aa3b, v50
	v_mul_f32_e32 v51, 0xbfb8aa3b, v51
	v_exp_f32_e32 v48, v48
	v_exp_f32_e32 v49, v49
	v_exp_f32_e32 v50, v50
	v_exp_f32_e32 v51, v51
	v_add_f32_e32 v48, 1.0, v48
	v_add_f32_e32 v49, 1.0, v49
	v_add_f32_e32 v50, 1.0, v50
	v_add_f32_e32 v51, 1.0, v51
	v_rcp_f32_e32 v48, v48
	v_rcp_f32_e32 v49, v49
	v_rcp_f32_e32 v50, v50
	v_rcp_f32_e32 v51, v51
	v_pk_mul_f32 v[48:49], v[56:57], v[48:49]
	v_pk_mul_f32 v[50:51], v[58:59], v[50:51]
	s_cbranch_vccnz .LBB0_172
	s_nop 0
	s_waitcnt vmcnt(7)
	v_lshlrev_b32_e32 v54, 16, v188
	v_and_b32_e32 v55, 0xffff0000, v188
	v_lshlrev_b32_e32 v52, 16, v189
	v_and_b32_e32 v53, 0xffff0000, v189
	v_pk_add_f32 v[48:49], v[48:49], v[54:55]
	v_pk_add_f32 v[50:51], v[50:51], v[52:53]
.LBB0_172:
	v_cvt_pk_bf16_f32 v48, v48, v49
	v_cvt_pk_bf16_f32 v49, v50, v51
	global_store_dwordx2 v[152:153], v[48:49], off offset:32
	s_nop 0
	s_and_b64 vcc, exec, s[46:47]
	s_waitcnt vmcnt(7)
	v_lshlrev_b32_e32 v48, 16, v232
	v_and_b32_e32 v49, 0xffff0000, v232
	v_lshlrev_b32_e32 v50, 16, v233
	v_and_b32_e32 v51, 0xffff0000, v233
	v_mul_f32_e32 v48, 0xbfb8aa3b, v48
	v_mul_f32_e32 v49, 0xbfb8aa3b, v49
	v_mul_f32_e32 v50, 0xbfb8aa3b, v50
	v_mul_f32_e32 v51, 0xbfb8aa3b, v51
	v_exp_f32_e32 v48, v48
	v_exp_f32_e32 v49, v49
	v_exp_f32_e32 v50, v50
	v_exp_f32_e32 v51, v51
	v_add_f32_e32 v48, 1.0, v48
	v_add_f32_e32 v49, 1.0, v49
	v_add_f32_e32 v50, 1.0, v50
	v_add_f32_e32 v51, 1.0, v51
	v_rcp_f32_e32 v48, v48
	v_rcp_f32_e32 v49, v49
	v_rcp_f32_e32 v50, v50
	v_rcp_f32_e32 v51, v51
	v_pk_mul_f32 v[48:49], v[60:61], v[48:49]
	v_pk_mul_f32 v[50:51], v[62:63], v[50:51]
	s_cbranch_vccnz .LBB0_174
	s_nop 0
	s_waitcnt vmcnt(7)
	v_lshlrev_b32_e32 v54, 16, v190
	v_and_b32_e32 v55, 0xffff0000, v190
	v_lshlrev_b32_e32 v52, 16, v191
	v_and_b32_e32 v53, 0xffff0000, v191
	v_pk_add_f32 v[48:49], v[48:49], v[54:55]
	v_pk_add_f32 v[50:51], v[50:51], v[52:53]
; __device__ __forceinline__ float bf_lo(unsigned u) { return __uint_as_float(u << 16); }
; __device__ __forceinline__ float bf_hi(unsigned u) { return __uint_as_float(u & 0xffff0000u); }
; __device__ __forceinline__ float sigm(float x) { return __builtin_amdgcn_rcpf(1.f + __builtin_amdgcn_exp2f(-LOG2E * x)); }
; __device__ void run_phase(CP& p, int ph, char* lds) {
;     ...
;                 const u16* gp = p.P + (size_t)tok * NIN + 6528 + pass * 1024 + nbase + 4 * h;
;                 u16* dst = p.MERGED + (size_t)tok * 1024 + nbase + 4 * h;
; #pragma unroll
;                 for (int nb = 0; nb < 2; ++nb)
; #pragma unroll
;                   for (int i = 0; i < 4; ++i) {
;                     const u32x2 ga = *(const u32x2*)(gp + nb * 32 + 8 * i);
;                     float o0 = sigm(bf_lo(ga.x)) * acc[nb][tb][4 * i];
;                     float o1 = sigm(bf_hi(ga.x)) * acc[nb][tb][4 * i + 1];
;                     float o2 = sigm(bf_lo(ga.y)) * acc[nb][tb][4 * i + 2];
;                     float o3 = sigm(bf_hi(ga.y)) * acc[nb][tb][4 * i + 3];
;                     if (pass) {
;                       const u32x2 pv = *(const u32x2*)(dst + nb * 32 + 8 * i);
;                       o0 += bf_lo(pv.x); o1 += bf_hi(pv.x); o2 += bf_lo(pv.y); o3 += bf_hi(pv.y);
;                     }
;                     *(u32x2*)(dst + nb * 32 + 8 * i) = (u32x2){pk_bf16(o0, o1), pk_bf16(o2, o3)};
.LBB0_174:
	v_cvt_pk_bf16_f32 v48, v48, v49
	v_cvt_pk_bf16_f32 v49, v50, v51
	global_store_dwordx2 v[152:153], v[48:49], off offset:48
	s_nop 0
	s_and_b64 vcc, exec, s[46:47]
	s_waitcnt vmcnt(7)
	v_lshlrev_b32_e32 v50, 16, v234
	v_and_b32_e32 v48, 0xffff0000, v234
	v_mul_f32_e32 v48, 0xbfb8aa3b, v48
	v_exp_f32_e32 v48, v48
	v_mul_f32_e32 v50, 0xbfb8aa3b, v50
	v_exp_f32_e32 v50, v50
	v_add_f32_e32 v48, 1.0, v48
	v_rcp_f32_e32 v51, v48
	v_lshlrev_b32_e32 v48, 16, v235
	v_and_b32_e32 v49, 0xffff0000, v235
	v_mul_f32_e32 v48, 0xbfb8aa3b, v48
	v_mul_f32_e32 v49, 0xbfb8aa3b, v49
	v_exp_f32_e32 v48, v48
	v_exp_f32_e32 v49, v49
	v_add_f32_e32 v50, 1.0, v50
	v_rcp_f32_e32 v50, v50
	v_add_f32_e32 v48, 1.0, v48
	v_add_f32_e32 v49, 1.0, v49
	v_rcp_f32_e32 v48, v48
	v_rcp_f32_e32 v49, v49
	v_pk_mul_f32 v[32:33], v[32:33], v[50:51]
	v_pk_mul_f32 v[34:35], v[34:35], v[48:49]
	s_cbranch_vccnz .LBB0_176
	s_nop 0
	s_waitcnt vmcnt(7)
	v_lshlrev_b32_e32 v50, 16, v192
	v_and_b32_e32 v51, 0xffff0000, v192
	v_lshlrev_b32_e32 v48, 16, v193
	v_and_b32_e32 v49, 0xffff0000, v193
	v_pk_add_f32 v[32:33], v[32:33], v[50:51]
	v_pk_add_f32 v[34:35], v[34:35], v[48:49]
.LBB0_176:
	v_cvt_pk_bf16_f32 v32, v32, v33
	v_cvt_pk_bf16_f32 v33, v34, v35
	global_store_dwordx2 v[152:153], v[32:33], off offset:64
	s_nop 0
	s_and_b64 vcc, exec, s[46:47]
	s_waitcnt vmcnt(7)
	v_lshlrev_b32_e32 v32, 16, v236
	v_and_b32_e32 v33, 0xffff0000, v236
	v_lshlrev_b32_e32 v34, 16, v237
	v_and_b32_e32 v35, 0xffff0000, v237
	v_mul_f32_e32 v32, 0xbfb8aa3b, v32
	v_mul_f32_e32 v33, 0xbfb8aa3b, v33
	v_mul_f32_e32 v34, 0xbfb8aa3b, v34
	v_mul_f32_e32 v35, 0xbfb8aa3b, v35
	v_exp_f32_e32 v32, v32
	v_exp_f32_e32 v33, v33
	v_exp_f32_e32 v34, v34
	v_exp_f32_e32 v35, v35
	v_add_f32_e32 v32, 1.0, v32
	v_add_f32_e32 v33, 1.0, v33
	v_add_f32_e32 v34, 1.0, v34
	v_add_f32_e32 v35, 1.0, v35
	v_rcp_f32_e32 v32, v32
	v_rcp_f32_e32 v33, v33
	v_rcp_f32_e32 v34, v34
	v_rcp_f32_e32 v35, v35
	v_pk_mul_f32 v[32:33], v[36:37], v[32:33]
	v_pk_mul_f32 v[34:35], v[38:39], v[34:35]
	s_cbranch_vccnz .LBB0_178
	s_nop 0
	s_waitcnt vmcnt(7)
	v_lshlrev_b32_e32 v38, 16, v194
	v_and_b32_e32 v39, 0xffff0000, v194
	v_lshlrev_b32_e32 v36, 16, v195
	v_and_b32_e32 v37, 0xffff0000, v195
	v_pk_add_f32 v[32:33], v[32:33], v[38:39]
	v_pk_add_f32 v[34:35], v[34:35], v[36:37]
.LBB0_178:
	v_cvt_pk_bf16_f32 v32, v32, v33
	v_cvt_pk_bf16_f32 v33, v34, v35
	global_store_dwordx2 v[152:153], v[32:33], off offset:80
	s_nop 0
	s_and_b64 vcc, exec, s[46:47]
	s_waitcnt vmcnt(7)
	v_lshlrev_b32_e32 v32, 16, v238
	v_and_b32_e32 v33, 0xffff0000, v238
	v_lshlrev_b32_e32 v34, 16, v239
	v_and_b32_e32 v35, 0xffff0000, v239
	v_mul_f32_e32 v32, 0xbfb8aa3b, v32
	v_mul_f32_e32 v33, 0xbfb8aa3b, v33
	v_mul_f32_e32 v34, 0xbfb8aa3b, v34
	v_mul_f32_e32 v35, 0xbfb8aa3b, v35
	v_exp_f32_e32 v32, v32
	v_exp_f32_e32 v33, v33
	v_exp_f32_e32 v34, v34
	v_exp_f32_e32 v35, v35
	v_add_f32_e32 v32, 1.0, v32
	v_add_f32_e32 v33, 1.0, v33
	v_add_f32_e32 v34, 1.0, v34
	v_add_f32_e32 v35, 1.0, v35
	v_rcp_f32_e32 v32, v32
	v_rcp_f32_e32 v33, v33
	v_rcp_f32_e32 v34, v34
	v_rcp_f32_e32 v35, v35
	v_pk_mul_f32 v[32:33], v[40:41], v[32:33]
	v_pk_mul_f32 v[34:35], v[42:43], v[34:35]
	s_cbranch_vccnz .LBB0_180
	s_nop 0
	s_waitcnt vmcnt(7)
	v_lshlrev_b32_e32 v38, 16, v168
	v_and_b32_e32 v39, 0xffff0000, v168
	v_lshlrev_b32_e32 v36, 16, v169
	v_and_b32_e32 v37, 0xffff0000, v169
	v_pk_add_f32 v[32:33], v[32:33], v[38:39]
	v_pk_add_f32 v[34:35], v[34:35], v[36:37]
.LBB0_180:
	v_cvt_pk_bf16_f32 v32, v32, v33
	v_cvt_pk_bf16_f32 v33, v34, v35
	global_store_dwordx2 v[152:153], v[32:33], off offset:96
	s_nop 0
	s_and_b64 vcc, exec, s[46:47]
	s_waitcnt vmcnt(7)
	v_lshlrev_b32_e32 v34, 16, v240
	v_and_b32_e32 v32, 0xffff0000, v240
	v_lshlrev_b32_e32 v35, 16, v241
	v_and_b32_e32 v33, 0xffff0000, v241
	v_mul_f32_e32 v34, 0xbfb8aa3b, v34
	v_mul_f32_e32 v32, 0xbfb8aa3b, v32
	v_mul_f32_e32 v35, 0xbfb8aa3b, v35
	v_mul_f32_e32 v33, 0xbfb8aa3b, v33
	v_exp_f32_e32 v34, v34
	v_exp_f32_e32 v32, v32
	v_exp_f32_e32 v35, v35
	v_exp_f32_e32 v33, v33
	v_add_f32_e32 v34, 1.0, v34
	v_add_f32_e32 v36, 1.0, v32
	v_add_f32_e32 v35, 1.0, v35
	v_add_f32_e32 v37, 1.0, v33
	v_rcp_f32_e32 v32, v34
	v_rcp_f32_e32 v33, v36
	v_rcp_f32_e32 v36, v35
	v_rcp_f32_e32 v37, v37
	v_pk_mul_f32 v[34:35], v[44:45], v[32:33]
	v_pk_mul_f32 v[32:33], v[46:47], v[36:37]
	s_cbranch_vccnz .LBB0_182
	s_nop 0
	s_waitcnt vmcnt(7)
	v_lshlrev_b32_e32 v38, 16, v170
	v_and_b32_e32 v39, 0xffff0000, v170
	v_lshlrev_b32_e32 v36, 16, v171
	v_and_b32_e32 v37, 0xffff0000, v171
	v_pk_add_f32 v[34:35], v[34:35], v[38:39]
	v_pk_add_f32 v[32:33], v[32:33], v[36:37]

; __device__ __forceinline__ float bf_lo(unsigned u) { return __uint_as_float(u << 16); }
; __device__ __forceinline__ float bf_hi(unsigned u) { return __uint_as_float(u & 0xffff0000u); }
; __device__ __forceinline__ float sigm(float x) { return __builtin_amdgcn_rcpf(1.f + __builtin_amdgcn_exp2f(-LOG2E * x)); }
; __device__ void run_phase(CP& p, int ph, char* lds) {
;     ...
;           auto epi = [&](const f32x16 (&acc)[2][2], int tbase) {
; #pragma unroll
;             for (int tb = 0; tb < 2; ++tb) {
;               const int tok = tbase + tb * 32 + l32;
;               if (tok < M) {
;                 const u16* gp = p.P + (size_t)tok * NIN + 6528 + pass * 1024 + nbase + 4 * h;
;                 u16* dst = p.MERGED + (size_t)tok * 1024 + nbase + 4 * h;
; #pragma unroll
;                 for (int nb = 0; nb < 2; ++nb)
; #pragma unroll
;                   for (int i = 0; i < 4; ++i) {
;                     const u32x2 ga = *(const u32x2*)(gp + nb * 32 + 8 * i);
;                     float o0 = sigm(bf_lo(ga.x)) * acc[nb][tb][4 * i];
;                     float o1 = sigm(bf_hi(ga.x)) * acc[nb][tb][4 * i + 1];
;                     float o2 = sigm(bf_lo(ga.y)) * acc[nb][tb][4 * i + 2];
;                     float o3 = sigm(bf_hi(ga.y)) * acc[nb][tb][4 * i + 3];
;                     if (pass) {
;                       const u32x2 pv = *(const u32x2*)(dst + nb * 32 + 8 * i);
;                       o0 += bf_lo(pv.x); o1 += bf_hi(pv.x); o2 += bf_lo(pv.y); o3 += bf_hi(pv.y);
;                     }
;                     *(u32x2*)(dst + nb * 32 + 8 * i) = (u32x2){pk_bf16(o0, o1), pk_bf16(o2, o3)};
;                   }
.LBB0_184:
	s_nop 3
	v_lshl_add_u64 v[96:97], s[50:51], 1, v[146:147]
	global_load_dwordx2 v[226:227], v[96:97], off
	global_load_dwordx2 v[228:229], v[96:97], off offset:16
	global_load_dwordx2 v[230:231], v[96:97], off offset:32
	global_load_dwordx2 v[232:233], v[96:97], off offset:48
	global_load_dwordx2 v[234:235], v[96:97], off offset:64
	global_load_dwordx2 v[236:237], v[96:97], off offset:80
	global_load_dwordx2 v[238:239], v[96:97], off offset:96
	global_load_dwordx2 v[240:241], v[96:97], off offset:112
	s_and_b64 vcc, exec, s[46:47]
	s_cbranch_vccnz .Lmg_skip_2
	global_load_dwordx2 v[184:185], v[148:149], off
	global_load_dwordx2 v[186:187], v[148:149], off offset:16
	global_load_dwordx2 v[188:189], v[148:149], off offset:32
	global_load_dwordx2 v[190:191], v[148:149], off offset:48
	global_load_dwordx2 v[192:193], v[148:149], off offset:64
	global_load_dwordx2 v[194:195], v[148:149], off offset:80
	global_load_dwordx2 v[168:169], v[148:149], off offset:96
	global_load_dwordx2 v[170:171], v[148:149], off offset:112
.Lmg_skip_2:
	s_and_b64 vcc, exec, s[46:47]
	s_waitcnt vmcnt(7)
	v_lshlrev_b32_e32 v100, 16, v226
	v_and_b32_e32 v98, 0xffff0000, v226
	v_mul_f32_e32 v98, 0xbfb8aa3b, v98
	v_exp_f32_e32 v98, v98
	v_mul_f32_e32 v100, 0xbfb8aa3b, v100
	v_exp_f32_e32 v100, v100
	v_add_f32_e32 v98, 1.0, v98
	v_rcp_f32_e32 v101, v98
	v_lshlrev_b32_e32 v98, 16, v227
	v_and_b32_e32 v99, 0xffff0000, v227
	v_mul_f32_e32 v98, 0xbfb8aa3b, v98
	v_mul_f32_e32 v99, 0xbfb8aa3b, v99
	v_exp_f32_e32 v98, v98
	v_exp_f32_e32 v99, v99
	v_add_f32_e32 v100, 1.0, v100
	v_rcp_f32_e32 v100, v100
	v_add_f32_e32 v98, 1.0, v98
	v_add_f32_e32 v99, 1.0, v99
	v_rcp_f32_e32 v98, v98
	v_rcp_f32_e32 v99, v99
	v_pk_mul_f32 v[80:81], v[80:81], v[100:101]
	v_pk_mul_f32 v[82:83], v[82:83], v[98:99]
	s_cbranch_vccnz .LBB0_186
	s_nop 0
	s_waitcnt vmcnt(7)
	v_lshlrev_b32_e32 v100, 16, v184
	v_and_b32_e32 v101, 0xffff0000, v184
	v_lshlrev_b32_e32 v98, 16, v185
	v_and_b32_e32 v99, 0xffff0000, v185
	v_pk_add_f32 v[80:81], v[80:81], v[100:101]
	v_pk_add_f32 v[82:83], v[82:83], v[98:99]
.LBB0_186:
	v_cvt_pk_bf16_f32 v80, v80, v81
	v_cvt_pk_bf16_f32 v81, v82, v83
	global_store_dwordx2 v[148:149], v[80:81], off
	s_nop 0
	s_and_b64 vcc, exec, s[46:47]
	s_waitcnt vmcnt(7)
	v_lshlrev_b32_e32 v80, 16, v228
	v_and_b32_e32 v81, 0xffff0000, v228
	v_lshlrev_b32_e32 v82, 16, v229
	v_and_b32_e32 v83, 0xffff0000, v229
	v_mul_f32_e32 v80, 0xbfb8aa3b, v80
	v_mul_f32_e32 v81, 0xbfb8aa3b, v81
	v_mul_f32_e32 v82, 0xbfb8aa3b, v82
	v_mul_f32_e32 v83, 0xbfb8aa3b, v83
	v_exp_f32_e32 v80, v80
	v_exp_f32_e32 v81, v81
	v_exp_f32_e32 v82, v82
	v_exp_f32_e32 v83, v83
	v_add_f32_e32 v80, 1.0, v80
	v_add_f32_e32 v81, 1.0, v81
	v_add_f32_e32 v82, 1.0, v82
	v_add_f32_e32 v83, 1.0, v83
	v_rcp_f32_e32 v80, v80
	v_rcp_f32_e32 v81, v81
	v_rcp_f32_e32 v82, v82
	v_rcp_f32_e32 v83, v83
	v_pk_mul_f32 v[80:81], v[84:85], v[80:81]
	v_pk_mul_f32 v[82:83], v[86:87], v[82:83]
	s_cbranch_vccnz .LBB0_188
	s_nop 0
	s_waitcnt vmcnt(7)
	v_lshlrev_b32_e32 v86, 16, v186
	v_and_b32_e32 v87, 0xffff0000, v186
	v_lshlrev_b32_e32 v84, 16, v187
	v_and_b32_e32 v85, 0xffff0000, v187
	v_pk_add_f32 v[80:81], v[80:81], v[86:87]
	v_pk_add_f32 v[82:83], v[82:83], v[84:85]
.LBB0_188:
	v_cvt_pk_bf16_f32 v80, v80, v81
	v_cvt_pk_bf16_f32 v81, v82, v83
	global_store_dwordx2 v[148:149], v[80:81], off offset:16
	s_nop 0
	s_and_b64 vcc, exec, s[46:47]
	s_waitcnt vmcnt(7)
	v_lshlrev_b32_e32 v80, 16, v230
	v_and_b32_e32 v81, 0xffff0000, v230
	v_lshlrev_b32_e32 v82, 16, v231
	v_and_b32_e32 v83, 0xffff0000, v231
	v_mul_f32_e32 v80, 0xbfb8aa3b, v80
	v_mul_f32_e32 v81, 0xbfb8aa3b, v81
	v_mul_f32_e32 v82, 0xbfb8aa3b, v82
	v_mul_f32_e32 v83, 0xbfb8aa3b, v83
	v_exp_f32_e32 v80, v80
	v_exp_f32_e32 v81, v81
	v_exp_f32_e32 v82, v82
	v_exp_f32_e32 v83, v83
	v_add_f32_e32 v80, 1.0, v80
	v_add_f32_e32 v81, 1.0, v81
	v_add_f32_e32 v82, 1.0, v82
	v_add_f32_e32 v83, 1.0, v83
	v_rcp_f32_e32 v80, v80
	v_rcp_f32_e32 v81, v81
	v_rcp_f32_e32 v82, v82
	v_rcp_f32_e32 v83, v83
	v_pk_mul_f32 v[80:81], v[88:89], v[80:81]
	v_pk_mul_f32 v[82:83], v[90:91], v[82:83]
	s_cbranch_vccnz .LBB0_190
	s_nop 0
	s_waitcnt vmcnt(7)
	v_lshlrev_b32_e32 v86, 16, v188
	v_and_b32_e32 v87, 0xffff0000, v188
	v_lshlrev_b32_e32 v84, 16, v189
	v_and_b32_e32 v85, 0xffff0000, v189
	v_pk_add_f32 v[80:81], v[80:81], v[86:87]
	v_pk_add_f32 v[82:83], v[82:83], v[84:85]
.LBB0_190:
	v_cvt_pk_bf16_f32 v80, v80, v81
	v_cvt_pk_bf16_f32 v81, v82, v83
	global_store_dwordx2 v[148:149], v[80:81], off offset:32
	s_nop 0
	s_and_b64 vcc, exec, s[46:47]
	s_waitcnt vmcnt(7)
	v_lshlrev_b32_e32 v80, 16, v232
	v_and_b32_e32 v81, 0xffff0000, v232
	v_lshlrev_b32_e32 v82, 16, v233
	v_and_b32_e32 v83, 0xffff0000, v233
	v_mul_f32_e32 v80, 0xbfb8aa3b, v80
	v_mul_f32_e32 v81, 0xbfb8aa3b, v81
	v_mul_f32_e32 v82, 0xbfb8aa3b, v82
	v_mul_f32_e32 v83, 0xbfb8aa3b, v83
	v_exp_f32_e32 v80, v80
	v_exp_f32_e32 v81, v81
	v_exp_f32_e32 v82, v82
	v_exp_f32_e32 v83, v83
	v_add_f32_e32 v80, 1.0, v80
	v_add_f32_e32 v81, 1.0, v81
	v_add_f32_e32 v82, 1.0, v82
	v_add_f32_e32 v83, 1.0, v83
	v_rcp_f32_e32 v80, v80
	v_rcp_f32_e32 v81, v81
	v_rcp_f32_e32 v82, v82
	v_rcp_f32_e32 v83, v83
	v_pk_mul_f32 v[80:81], v[92:93], v[80:81]
	v_pk_mul_f32 v[82:83], v[94:95], v[82:83]
	s_cbranch_vccnz .LBB0_192
	s_nop 0
	s_waitcnt vmcnt(7)
	v_lshlrev_b32_e32 v86, 16, v190
	v_and_b32_e32 v87, 0xffff0000, v190
	v_lshlrev_b32_e32 v84, 16, v191
	v_and_b32_e32 v85, 0xffff0000, v191
	v_pk_add_f32 v[80:81], v[80:81], v[86:87]
	v_pk_add_f32 v[82:83], v[82:83], v[84:85]
; __device__ __forceinline__ float bf_lo(unsigned u) { return __uint_as_float(u << 16); }
; __device__ __forceinline__ float bf_hi(unsigned u) { return __uint_as_float(u & 0xffff0000u); }
; __device__ __forceinline__ float sigm(float x) { return __builtin_amdgcn_rcpf(1.f + __builtin_amdgcn_exp2f(-LOG2E * x)); }
; __device__ void run_phase(CP& p, int ph, char* lds) {
;     ...
;           auto epi = [&](const f32x16 (&acc)[2][2], int tbase) {
; #pragma unroll
;             for (int tb = 0; tb < 2; ++tb) {
;               const int tok = tbase + tb * 32 + l32;
;               if (tok < M) {
;                 const u16* gp = p.P + (size_t)tok * NIN + 6528 + pass * 1024 + nbase + 4 * h;
;                 u16* dst = p.MERGED + (size_t)tok * 1024 + nbase + 4 * h;
; #pragma unroll
;                 for (int nb = 0; nb < 2; ++nb)
; #pragma unroll
;                   for (int i = 0; i < 4; ++i) {
;                     const u32x2 ga = *(const u32x2*)(gp + nb * 32 + 8 * i);
;                     float o0 = sigm(bf_lo(ga.x)) * acc[nb][tb][4 * i];
;                     float o1 = sigm(bf_hi(ga.x)) * acc[nb][tb][4 * i + 1];
;                     float o2 = sigm(bf_lo(ga.y)) * acc[nb][tb][4 * i + 2];
;                     float o3 = sigm(bf_hi(ga.y)) * acc[nb][tb][4 * i + 3];
;                     if (pass) {
;                       const u32x2 pv = *(const u32x2*)(dst + nb * 32 + 8 * i);
;                       o0 += bf_lo(pv.x); o1 += bf_hi(pv.x); o2 += bf_lo(pv.y); o3 += bf_hi(pv.y);
;                     }
;                     *(u32x2*)(dst + nb * 32 + 8 * i) = (u32x2){pk_bf16(o0, o1), pk_bf16(o2, o3)};
;                   }
.LBB0_192:
	v_cvt_pk_bf16_f32 v80, v80, v81
	v_cvt_pk_bf16_f32 v81, v82, v83
	global_store_dwordx2 v[148:149], v[80:81], off offset:48
	s_nop 0
	s_and_b64 vcc, exec, s[46:47]
	s_waitcnt vmcnt(7)
	v_lshlrev_b32_e32 v82, 16, v234
	v_and_b32_e32 v80, 0xffff0000, v234
	v_mul_f32_e32 v80, 0xbfb8aa3b, v80
	v_exp_f32_e32 v80, v80
	v_mul_f32_e32 v82, 0xbfb8aa3b, v82
	v_exp_f32_e32 v82, v82
	v_add_f32_e32 v80, 1.0, v80
	v_rcp_f32_e32 v83, v80
	v_lshlrev_b32_e32 v80, 16, v235
	v_and_b32_e32 v81, 0xffff0000, v235
	v_mul_f32_e32 v80, 0xbfb8aa3b, v80
	v_mul_f32_e32 v81, 0xbfb8aa3b, v81
	v_exp_f32_e32 v80, v80
	v_exp_f32_e32 v81, v81
	v_add_f32_e32 v82, 1.0, v82
	v_rcp_f32_e32 v82, v82
	v_add_f32_e32 v80, 1.0, v80
	v_add_f32_e32 v81, 1.0, v81
	v_rcp_f32_e32 v80, v80
	v_rcp_f32_e32 v81, v81
	v_pk_mul_f32 v[64:65], v[64:65], v[82:83]
	v_pk_mul_f32 v[66:67], v[66:67], v[80:81]
	s_cbranch_vccnz .LBB0_194
	s_nop 0
	s_waitcnt vmcnt(7)
	v_lshlrev_b32_e32 v82, 16, v192
	v_and_b32_e32 v83, 0xffff0000, v192
	v_lshlrev_b32_e32 v80, 16, v193
	v_and_b32_e32 v81, 0xffff0000, v193
	v_pk_add_f32 v[64:65], v[64:65], v[82:83]
	v_pk_add_f32 v[66:67], v[66:67], v[80:81]
.LBB0_194:
	v_cvt_pk_bf16_f32 v64, v64, v65
	v_cvt_pk_bf16_f32 v65, v66, v67
	global_store_dwordx2 v[148:149], v[64:65], off offset:64
	s_nop 0
	s_and_b64 vcc, exec, s[46:47]
	s_waitcnt vmcnt(7)
	v_lshlrev_b32_e32 v64, 16, v236
	v_and_b32_e32 v65, 0xffff0000, v236
	v_lshlrev_b32_e32 v66, 16, v237
	v_and_b32_e32 v67, 0xffff0000, v237
	v_mul_f32_e32 v64, 0xbfb8aa3b, v64
	v_mul_f32_e32 v65, 0xbfb8aa3b, v65
	v_mul_f32_e32 v66, 0xbfb8aa3b, v66
	v_mul_f32_e32 v67, 0xbfb8aa3b, v67
	v_exp_f32_e32 v64, v64
	v_exp_f32_e32 v65, v65
	v_exp_f32_e32 v66, v66
	v_exp_f32_e32 v67, v67
	v_add_f32_e32 v64, 1.0, v64
	v_add_f32_e32 v65, 1.0, v65
	v_add_f32_e32 v66, 1.0, v66
	v_add_f32_e32 v67, 1.0, v67
	v_rcp_f32_e32 v64, v64
	v_rcp_f32_e32 v65, v65
	v_rcp_f32_e32 v66, v66
	v_rcp_f32_e32 v67, v67
	v_pk_mul_f32 v[64:65], v[68:69], v[64:65]
	v_pk_mul_f32 v[66:67], v[70:71], v[66:67]
	s_cbranch_vccnz .LBB0_196
	s_nop 0
	s_waitcnt vmcnt(7)
	v_lshlrev_b32_e32 v70, 16, v194
	v_and_b32_e32 v71, 0xffff0000, v194
	v_lshlrev_b32_e32 v68, 16, v195
	v_and_b32_e32 v69, 0xffff0000, v195
	v_pk_add_f32 v[64:65], v[64:65], v[70:71]
	v_pk_add_f32 v[66:67], v[66:67], v[68:69]
.LBB0_196:
	v_cvt_pk_bf16_f32 v64, v64, v65
	v_cvt_pk_bf16_f32 v65, v66, v67
	global_store_dwordx2 v[148:149], v[64:65], off offset:80
	s_nop 0
	s_and_b64 vcc, exec, s[46:47]
	s_waitcnt vmcnt(7)
	v_lshlrev_b32_e32 v64, 16, v238
	v_and_b32_e32 v65, 0xffff0000, v238
	v_lshlrev_b32_e32 v66, 16, v239
	v_and_b32_e32 v67, 0xffff0000, v239
	v_mul_f32_e32 v64, 0xbfb8aa3b, v64
	v_mul_f32_e32 v65, 0xbfb8aa3b, v65
	v_mul_f32_e32 v66, 0xbfb8aa3b, v66
	v_mul_f32_e32 v67, 0xbfb8aa3b, v67
	v_exp_f32_e32 v64, v64
	v_exp_f32_e32 v65, v65
	v_exp_f32_e32 v66, v66
	v_exp_f32_e32 v67, v67
	v_add_f32_e32 v64, 1.0, v64
	v_add_f32_e32 v65, 1.0, v65
	v_add_f32_e32 v66, 1.0, v66
	v_add_f32_e32 v67, 1.0, v67
	v_rcp_f32_e32 v64, v64
	v_rcp_f32_e32 v65, v65
	v_rcp_f32_e32 v66, v66
	v_rcp_f32_e32 v67, v67
	v_pk_mul_f32 v[64:65], v[72:73], v[64:65]
	v_pk_mul_f32 v[66:67], v[74:75], v[66:67]
	s_cbranch_vccnz .LBB0_198
	s_nop 0
	s_waitcnt vmcnt(7)
	v_lshlrev_b32_e32 v70, 16, v168
	v_and_b32_e32 v71, 0xffff0000, v168
	v_lshlrev_b32_e32 v68, 16, v169
	v_and_b32_e32 v69, 0xffff0000, v169
	v_pk_add_f32 v[64:65], v[64:65], v[70:71]
	v_pk_add_f32 v[66:67], v[66:67], v[68:69]
.LBB0_198:
	v_cvt_pk_bf16_f32 v64, v64, v65
	v_cvt_pk_bf16_f32 v65, v66, v67
	global_store_dwordx2 v[148:149], v[64:65], off offset:96
	s_nop 0
	s_and_b64 vcc, exec, s[46:47]
	s_waitcnt vmcnt(7)
	v_lshlrev_b32_e32 v66, 16, v240
	v_and_b32_e32 v64, 0xffff0000, v240
	v_lshlrev_b32_e32 v67, 16, v241
	v_and_b32_e32 v65, 0xffff0000, v241
	v_mul_f32_e32 v66, 0xbfb8aa3b, v66
	v_mul_f32_e32 v64, 0xbfb8aa3b, v64
	v_mul_f32_e32 v67, 0xbfb8aa3b, v67
	v_mul_f32_e32 v65, 0xbfb8aa3b, v65
	v_exp_f32_e32 v66, v66
	v_exp_f32_e32 v64, v64
	v_exp_f32_e32 v67, v67
	v_exp_f32_e32 v65, v65
	v_add_f32_e32 v66, 1.0, v66
	v_add_f32_e32 v68, 1.0, v64
	v_add_f32_e32 v67, 1.0, v67
	v_add_f32_e32 v69, 1.0, v65
	v_rcp_f32_e32 v64, v66
	v_rcp_f32_e32 v65, v68
	v_rcp_f32_e32 v68, v67
	v_rcp_f32_e32 v69, v69
	v_pk_mul_f32 v[66:67], v[76:77], v[64:65]
	v_pk_mul_f32 v[64:65], v[78:79], v[68:69]
	s_cbranch_vccnz .LBB0_200
	s_nop 0
	s_waitcnt vmcnt(7)
	v_lshlrev_b32_e32 v70, 16, v170
	v_and_b32_e32 v71, 0xffff0000, v170
	v_lshlrev_b32_e32 v68, 16, v171
	v_and_b32_e32 v69, 0xffff0000, v171
	v_pk_add_f32 v[66:67], v[66:67], v[70:71]
	v_pk_add_f32 v[64:65], v[64:65], v[68:69]

; __device__ __forceinline__ float bf_lo(unsigned u) { return __uint_as_float(u << 16); }
; __device__ __forceinline__ float bf_hi(unsigned u) { return __uint_as_float(u & 0xffff0000u); }
; __device__ __forceinline__ float sigm(float x) { return __builtin_amdgcn_rcpf(1.f + __builtin_amdgcn_exp2f(-LOG2E * x)); }
; __device__ void run_phase(CP& p, int ph, char* lds) {
;     ...
;           auto epi = [&](const f32x16 (&acc)[2][2], int tbase) {
; #pragma unroll
;             for (int tb = 0; tb < 2; ++tb) {
;               const int tok = tbase + tb * 32 + l32;
;               if (tok < M) {
;                 const u16* gp = p.P + (size_t)tok * NIN + 6528 + pass * 1024 + nbase + 4 * h;
;                 u16* dst = p.MERGED + (size_t)tok * 1024 + nbase + 4 * h;
; #pragma unroll
;                 for (int nb = 0; nb < 2; ++nb)
; #pragma unroll
;                   for (int i = 0; i < 4; ++i) {
;                     const u32x2 ga = *(const u32x2*)(gp + nb * 32 + 8 * i);
;                     float o0 = sigm(bf_lo(ga.x)) * acc[nb][tb][4 * i];
;                     float o1 = sigm(bf_hi(ga.x)) * acc[nb][tb][4 * i + 1];
;                     float o2 = sigm(bf_lo(ga.y)) * acc[nb][tb][4 * i + 2];
;                     float o3 = sigm(bf_hi(ga.y)) * acc[nb][tb][4 * i + 3];
;                     if (pass) {
;                       const u32x2 pv = *(const u32x2*)(dst + nb * 32 + 8 * i);
;                       o0 += bf_lo(pv.x); o1 += bf_hi(pv.x); o2 += bf_lo(pv.y); o3 += bf_hi(pv.y);
;                     }
;                     *(u32x2*)(dst + nb * 32 + 8 * i) = (u32x2){pk_bf16(o0, o1), pk_bf16(o2, o3)};
;                   }
.LBB0_202:
	v_lshl_add_u64 v[32:33], s[50:51], 1, v[154:155]
	global_load_dwordx2 v[226:227], v[32:33], off
	global_load_dwordx2 v[228:229], v[32:33], off offset:16
	global_load_dwordx2 v[230:231], v[32:33], off offset:32
	global_load_dwordx2 v[232:233], v[32:33], off offset:48
	global_load_dwordx2 v[234:235], v[32:33], off offset:64
	global_load_dwordx2 v[236:237], v[32:33], off offset:80
	global_load_dwordx2 v[238:239], v[32:33], off offset:96
	global_load_dwordx2 v[240:241], v[32:33], off offset:112
	s_and_b64 vcc, exec, s[46:47]
	s_cbranch_vccnz .Lmg_skip_3
	global_load_dwordx2 v[184:185], v[156:157], off
	global_load_dwordx2 v[186:187], v[156:157], off offset:16
	global_load_dwordx2 v[188:189], v[156:157], off offset:32
	global_load_dwordx2 v[190:191], v[156:157], off offset:48
	global_load_dwordx2 v[192:193], v[156:157], off offset:64
	global_load_dwordx2 v[194:195], v[156:157], off offset:80
	global_load_dwordx2 v[168:169], v[156:157], off offset:96
	global_load_dwordx2 v[170:171], v[156:157], off offset:112
.Lmg_skip_3:
	s_and_b64 vcc, exec, s[46:47]
	s_waitcnt vmcnt(7)
	v_lshlrev_b32_e32 v36, 16, v226
	v_and_b32_e32 v34, 0xffff0000, v226
	v_mul_f32_e32 v34, 0xbfb8aa3b, v34
	v_exp_f32_e32 v34, v34
	v_mul_f32_e32 v36, 0xbfb8aa3b, v36
	v_exp_f32_e32 v36, v36
	v_add_f32_e32 v34, 1.0, v34
	v_rcp_f32_e32 v37, v34
	v_lshlrev_b32_e32 v34, 16, v227
	v_and_b32_e32 v35, 0xffff0000, v227
	v_mul_f32_e32 v34, 0xbfb8aa3b, v34
	v_mul_f32_e32 v35, 0xbfb8aa3b, v35
	v_exp_f32_e32 v34, v34
	v_exp_f32_e32 v35, v35
	v_add_f32_e32 v36, 1.0, v36
	v_rcp_f32_e32 v36, v36
	v_add_f32_e32 v34, 1.0, v34
	v_add_f32_e32 v35, 1.0, v35
	v_rcp_f32_e32 v34, v34
	v_rcp_f32_e32 v35, v35
	v_pk_mul_f32 v[16:17], v[16:17], v[36:37]
	v_pk_mul_f32 v[18:19], v[18:19], v[34:35]
	s_cbranch_vccnz .LBB0_204
	s_nop 0
	s_waitcnt vmcnt(7)
	v_lshlrev_b32_e32 v36, 16, v184
	v_and_b32_e32 v37, 0xffff0000, v184
	v_lshlrev_b32_e32 v34, 16, v185
	v_and_b32_e32 v35, 0xffff0000, v185
	v_pk_add_f32 v[16:17], v[16:17], v[36:37]
	v_pk_add_f32 v[18:19], v[18:19], v[34:35]
.LBB0_204:
	v_cvt_pk_bf16_f32 v16, v16, v17
	v_cvt_pk_bf16_f32 v17, v18, v19
	global_store_dwordx2 v[156:157], v[16:17], off
	s_nop 0
	s_and_b64 vcc, exec, s[46:47]
	s_waitcnt vmcnt(7)
	v_lshlrev_b32_e32 v16, 16, v228
	v_and_b32_e32 v17, 0xffff0000, v228
	v_lshlrev_b32_e32 v18, 16, v229
	v_and_b32_e32 v19, 0xffff0000, v229
	v_mul_f32_e32 v16, 0xbfb8aa3b, v16
	v_mul_f32_e32 v17, 0xbfb8aa3b, v17
	v_mul_f32_e32 v18, 0xbfb8aa3b, v18
	v_mul_f32_e32 v19, 0xbfb8aa3b, v19
	v_exp_f32_e32 v16, v16
	v_exp_f32_e32 v17, v17
	v_exp_f32_e32 v18, v18
	v_exp_f32_e32 v19, v19
	v_add_f32_e32 v16, 1.0, v16
	v_add_f32_e32 v17, 1.0, v17
	v_add_f32_e32 v18, 1.0, v18
	v_add_f32_e32 v19, 1.0, v19
	v_rcp_f32_e32 v16, v16
	v_rcp_f32_e32 v17, v17
	v_rcp_f32_e32 v18, v18
	v_rcp_f32_e32 v19, v19
	v_pk_mul_f32 v[16:17], v[20:21], v[16:17]
	v_pk_mul_f32 v[18:19], v[22:23], v[18:19]
	s_cbranch_vccnz .LBB0_206
	s_nop 0
	s_waitcnt vmcnt(7)
	v_lshlrev_b32_e32 v22, 16, v186
	v_and_b32_e32 v23, 0xffff0000, v186
	v_lshlrev_b32_e32 v20, 16, v187
	v_and_b32_e32 v21, 0xffff0000, v187
	v_pk_add_f32 v[16:17], v[16:17], v[22:23]
	v_pk_add_f32 v[18:19], v[18:19], v[20:21]
.LBB0_206:
	v_cvt_pk_bf16_f32 v16, v16, v17
	v_cvt_pk_bf16_f32 v17, v18, v19
	global_store_dwordx2 v[156:157], v[16:17], off offset:16
	s_nop 0
	s_and_b64 vcc, exec, s[46:47]
	s_waitcnt vmcnt(7)
	v_lshlrev_b32_e32 v16, 16, v230
	v_and_b32_e32 v17, 0xffff0000, v230
	v_lshlrev_b32_e32 v18, 16, v231
	v_and_b32_e32 v19, 0xffff0000, v231
	v_mul_f32_e32 v16, 0xbfb8aa3b, v16
	v_mul_f32_e32 v17, 0xbfb8aa3b, v17
	v_mul_f32_e32 v18, 0xbfb8aa3b, v18
	v_mul_f32_e32 v19, 0xbfb8aa3b, v19
	v_exp_f32_e32 v16, v16
	v_exp_f32_e32 v17, v17
	v_exp_f32_e32 v18, v18
	v_exp_f32_e32 v19, v19
	v_add_f32_e32 v16, 1.0, v16
	v_add_f32_e32 v17, 1.0, v17
	v_add_f32_e32 v18, 1.0, v18
	v_add_f32_e32 v19, 1.0, v19
	v_rcp_f32_e32 v16, v16
	v_rcp_f32_e32 v17, v17
	v_rcp_f32_e32 v18, v18
	v_rcp_f32_e32 v19, v19
	v_pk_mul_f32 v[16:17], v[24:25], v[16:17]
	v_pk_mul_f32 v[18:19], v[26:27], v[18:19]
	s_cbranch_vccnz .LBB0_208
	s_nop 0
	s_waitcnt vmcnt(7)
	v_lshlrev_b32_e32 v22, 16, v188
	v_and_b32_e32 v23, 0xffff0000, v188
	v_lshlrev_b32_e32 v20, 16, v189
	v_and_b32_e32 v21, 0xffff0000, v189
	v_pk_add_f32 v[16:17], v[16:17], v[22:23]
	v_pk_add_f32 v[18:19], v[18:19], v[20:21]
.LBB0_208:
	v_cvt_pk_bf16_f32 v16, v16, v17
	v_cvt_pk_bf16_f32 v17, v18, v19
	global_store_dwordx2 v[156:157], v[16:17], off offset:32
	s_nop 0
	s_and_b64 vcc, exec, s[46:47]
	s_waitcnt vmcnt(7)
	v_lshlrev_b32_e32 v16, 16, v232
	v_and_b32_e32 v17, 0xffff0000, v232
	v_lshlrev_b32_e32 v18, 16, v233
	v_and_b32_e32 v19, 0xffff0000, v233
	v_mul_f32_e32 v16, 0xbfb8aa3b, v16
	v_mul_f32_e32 v17, 0xbfb8aa3b, v17
	v_mul_f32_e32 v18, 0xbfb8aa3b, v18
	v_mul_f32_e32 v19, 0xbfb8aa3b, v19
	v_exp_f32_e32 v16, v16
	v_exp_f32_e32 v17, v17
	v_exp_f32_e32 v18, v18
	v_exp_f32_e32 v19, v19
	v_add_f32_e32 v16, 1.0, v16
	v_add_f32_e32 v17, 1.0, v17
	v_add_f32_e32 v18, 1.0, v18
	v_add_f32_e32 v19, 1.0, v19
	v_rcp_f32_e32 v16, v16
	v_rcp_f32_e32 v17, v17
	v_rcp_f32_e32 v18, v18
	v_rcp_f32_e32 v19, v19
	v_pk_mul_f32 v[16:17], v[28:29], v[16:17]
	v_pk_mul_f32 v[18:19], v[30:31], v[18:19]
	s_cbranch_vccnz .LBB0_210
	s_nop 0
	s_waitcnt vmcnt(7)
	v_lshlrev_b32_e32 v22, 16, v190
	v_and_b32_e32 v23, 0xffff0000, v190
	v_lshlrev_b32_e32 v20, 16, v191
	v_and_b32_e32 v21, 0xffff0000, v191
	v_pk_add_f32 v[16:17], v[16:17], v[22:23]
	v_pk_add_f32 v[18:19], v[18:19], v[20:21]
; __device__ __forceinline__ float bf_lo(unsigned u) { return __uint_as_float(u << 16); }
; __device__ __forceinline__ float bf_hi(unsigned u) { return __uint_as_float(u & 0xffff0000u); }
; __device__ __forceinline__ float sigm(float x) { return __builtin_amdgcn_rcpf(1.f + __builtin_amdgcn_exp2f(-LOG2E * x)); }
; __device__ void run_phase(CP& p, int ph, char* lds) {
;     ...
;           auto epi = [&](const f32x16 (&acc)[2][2], int tbase) {
; #pragma unroll
;             for (int tb = 0; tb < 2; ++tb) {
;               const int tok = tbase + tb * 32 + l32;
;               if (tok < M) {
;                 const u16* gp = p.P + (size_t)tok * NIN + 6528 + pass * 1024 + nbase + 4 * h;
;                 u16* dst = p.MERGED + (size_t)tok * 1024 + nbase + 4 * h;
; #pragma unroll
;                 for (int nb = 0; nb < 2; ++nb)
; #pragma unroll
;                   for (int i = 0; i < 4; ++i) {
;                     const u32x2 ga = *(const u32x2*)(gp + nb * 32 + 8 * i);
;                     float o0 = sigm(bf_lo(ga.x)) * acc[nb][tb][4 * i];
;                     float o1 = sigm(bf_hi(ga.x)) * acc[nb][tb][4 * i + 1];
;                     float o2 = sigm(bf_lo(ga.y)) * acc[nb][tb][4 * i + 2];
;                     float o3 = sigm(bf_hi(ga.y)) * acc[nb][tb][4 * i + 3];
;                     if (pass) {
;                       const u32x2 pv = *(const u32x2*)(dst + nb * 32 + 8 * i);
;                       o0 += bf_lo(pv.x); o1 += bf_hi(pv.x); o2 += bf_lo(pv.y); o3 += bf_hi(pv.y);
;                     }
;                     *(u32x2*)(dst + nb * 32 + 8 * i) = (u32x2){pk_bf16(o0, o1), pk_bf16(o2, o3)};
;                   }
.LBB0_210:
	v_cvt_pk_bf16_f32 v16, v16, v17
	v_cvt_pk_bf16_f32 v17, v18, v19
	global_store_dwordx2 v[156:157], v[16:17], off offset:48
	s_nop 0
	s_and_b64 vcc, exec, s[46:47]
	s_waitcnt vmcnt(7)
	v_lshlrev_b32_e32 v18, 16, v234
	v_and_b32_e32 v16, 0xffff0000, v234
	v_mul_f32_e32 v16, 0xbfb8aa3b, v16
	v_exp_f32_e32 v16, v16
	v_mul_f32_e32 v18, 0xbfb8aa3b, v18
	v_exp_f32_e32 v18, v18
	v_add_f32_e32 v16, 1.0, v16
	v_rcp_f32_e32 v19, v16
	v_lshlrev_b32_e32 v16, 16, v235
	v_and_b32_e32 v17, 0xffff0000, v235
	v_mul_f32_e32 v16, 0xbfb8aa3b, v16
	v_mul_f32_e32 v17, 0xbfb8aa3b, v17
	v_exp_f32_e32 v16, v16
	v_exp_f32_e32 v17, v17
	v_add_f32_e32 v18, 1.0, v18
	v_rcp_f32_e32 v18, v18
	v_add_f32_e32 v16, 1.0, v16
	v_add_f32_e32 v17, 1.0, v17
	v_rcp_f32_e32 v16, v16
	v_rcp_f32_e32 v17, v17
	v_pk_mul_f32 v[0:1], v[0:1], v[18:19]
	v_pk_mul_f32 v[2:3], v[2:3], v[16:17]
	s_cbranch_vccnz .LBB0_212
	s_nop 0
	s_waitcnt vmcnt(7)
	v_lshlrev_b32_e32 v18, 16, v192
	v_and_b32_e32 v19, 0xffff0000, v192
	v_lshlrev_b32_e32 v16, 16, v193
	v_and_b32_e32 v17, 0xffff0000, v193
	v_pk_add_f32 v[0:1], v[0:1], v[18:19]
	v_pk_add_f32 v[2:3], v[2:3], v[16:17]
.LBB0_212:
	v_cvt_pk_bf16_f32 v0, v0, v1
	v_cvt_pk_bf16_f32 v1, v2, v3
	global_store_dwordx2 v[156:157], v[0:1], off offset:64
	s_nop 0
	s_and_b64 vcc, exec, s[46:47]
	s_waitcnt vmcnt(7)
	v_lshlrev_b32_e32 v0, 16, v236
	v_and_b32_e32 v1, 0xffff0000, v236
	v_lshlrev_b32_e32 v2, 16, v237
	v_and_b32_e32 v3, 0xffff0000, v237
	v_mul_f32_e32 v0, 0xbfb8aa3b, v0
	v_mul_f32_e32 v1, 0xbfb8aa3b, v1
	v_mul_f32_e32 v2, 0xbfb8aa3b, v2
	v_mul_f32_e32 v3, 0xbfb8aa3b, v3
	v_exp_f32_e32 v0, v0
	v_exp_f32_e32 v1, v1
	v_exp_f32_e32 v2, v2
	v_exp_f32_e32 v3, v3
	v_add_f32_e32 v0, 1.0, v0
	v_add_f32_e32 v1, 1.0, v1
	v_add_f32_e32 v2, 1.0, v2
	v_add_f32_e32 v3, 1.0, v3
	v_rcp_f32_e32 v0, v0
	v_rcp_f32_e32 v1, v1
	v_rcp_f32_e32 v2, v2
	v_rcp_f32_e32 v3, v3
	v_pk_mul_f32 v[0:1], v[4:5], v[0:1]
	v_pk_mul_f32 v[2:3], v[6:7], v[2:3]
	s_cbranch_vccnz .LBB0_214
	s_nop 0
	s_waitcnt vmcnt(7)
	v_lshlrev_b32_e32 v6, 16, v194
	v_and_b32_e32 v7, 0xffff0000, v194
	v_lshlrev_b32_e32 v4, 16, v195
	v_and_b32_e32 v5, 0xffff0000, v195
	v_pk_add_f32 v[0:1], v[0:1], v[6:7]
	v_pk_add_f32 v[2:3], v[2:3], v[4:5]
.LBB0_214:
	v_cvt_pk_bf16_f32 v0, v0, v1
	v_cvt_pk_bf16_f32 v1, v2, v3
	global_store_dwordx2 v[156:157], v[0:1], off offset:80
	s_nop 0
	s_and_b64 vcc, exec, s[46:47]
	s_waitcnt vmcnt(7)
	v_lshlrev_b32_e32 v0, 16, v238
	v_and_b32_e32 v1, 0xffff0000, v238
	v_lshlrev_b32_e32 v2, 16, v239
	v_and_b32_e32 v3, 0xffff0000, v239
	v_mul_f32_e32 v0, 0xbfb8aa3b, v0
	v_mul_f32_e32 v1, 0xbfb8aa3b, v1
	v_mul_f32_e32 v2, 0xbfb8aa3b, v2
	v_mul_f32_e32 v3, 0xbfb8aa3b, v3
	v_exp_f32_e32 v0, v0
	v_exp_f32_e32 v1, v1
	v_exp_f32_e32 v2, v2
	v_exp_f32_e32 v3, v3
	v_add_f32_e32 v0, 1.0, v0
	v_add_f32_e32 v1, 1.0, v1
	v_add_f32_e32 v2, 1.0, v2
	v_add_f32_e32 v3, 1.0, v3
	v_rcp_f32_e32 v0, v0
	v_rcp_f32_e32 v1, v1
	v_rcp_f32_e32 v2, v2
	v_rcp_f32_e32 v3, v3
	v_pk_mul_f32 v[0:1], v[8:9], v[0:1]
	v_pk_mul_f32 v[2:3], v[10:11], v[2:3]
	s_cbranch_vccnz .LBB0_216
	s_nop 0
	s_waitcnt vmcnt(7)
	v_lshlrev_b32_e32 v6, 16, v168
	v_and_b32_e32 v7, 0xffff0000, v168
	v_lshlrev_b32_e32 v4, 16, v169
	v_and_b32_e32 v5, 0xffff0000, v169
	v_pk_add_f32 v[0:1], v[0:1], v[6:7]
	v_pk_add_f32 v[2:3], v[2:3], v[4:5]
.LBB0_216:
	v_cvt_pk_bf16_f32 v0, v0, v1
	v_cvt_pk_bf16_f32 v1, v2, v3
	global_store_dwordx2 v[156:157], v[0:1], off offset:96
	s_nop 0
	s_and_b64 vcc, exec, s[46:47]
	s_waitcnt vmcnt(7)
	v_lshlrev_b32_e32 v2, 16, v240
	v_and_b32_e32 v0, 0xffff0000, v240
	v_lshlrev_b32_e32 v3, 16, v241
	v_and_b32_e32 v1, 0xffff0000, v241
	v_mul_f32_e32 v2, 0xbfb8aa3b, v2
	v_mul_f32_e32 v0, 0xbfb8aa3b, v0
	v_mul_f32_e32 v3, 0xbfb8aa3b, v3
	v_mul_f32_e32 v1, 0xbfb8aa3b, v1
	v_exp_f32_e32 v2, v2
	v_exp_f32_e32 v0, v0
	v_exp_f32_e32 v3, v3
	v_exp_f32_e32 v1, v1
	v_add_f32_e32 v2, 1.0, v2
	v_add_f32_e32 v4, 1.0, v0
	v_add_f32_e32 v3, 1.0, v3
	v_add_f32_e32 v5, 1.0, v1
	v_rcp_f32_e32 v0, v2
	v_rcp_f32_e32 v1, v4
	v_rcp_f32_e32 v4, v3
	v_rcp_f32_e32 v5, v5
	v_pk_mul_f32 v[2:3], v[12:13], v[0:1]
	v_pk_mul_f32 v[0:1], v[14:15], v[4:5]
	s_cbranch_vccnz .LBB0_143
	s_nop 0
	s_waitcnt vmcnt(7)
	v_lshlrev_b32_e32 v6, 16, v170
	v_and_b32_e32 v7, 0xffff0000, v170
	v_lshlrev_b32_e32 v4, 16, v171
	v_and_b32_e32 v5, 0xffff0000, v171
	v_pk_add_f32 v[2:3], v[2:3], v[6:7]
	v_pk_add_f32 v[0:1], v[0:1], v[4:5]
	s_branch .LBB0_143

; __device__ __forceinline__ unsigned xb_xcc_id() { return (unsigned)__builtin_amdgcn_s_getreg((3 << 11) | 20) & 0xFu; }
; __device__ __forceinline__ void h_tile(WideCtx& c, const u16* __restrict__ A, int lda, int M, int m0, const u16* __restrict__ W, int ldw, int n0) {
; #pragma unroll
;   for (int i = 0; i < 2; ++i) {
;     const int q = c.tid + 256 * i, row = q >> 2, ch = (q & 3) ^ ((row >> 2) & 3);
;     c.wp[i] = W + (size_t)(n0 + row) * ldw + ch * 8;
;   }
; #pragma unroll
;   for (int i = 0; i < 4; ++i) {
;     const int q = c.tid + 256 * i, row = q >> 2, ch = (q & 3) ^ ((row >> 2) & 3);
;     int ar = m0 + row; ar = ar < M ? ar : M - 1;
;     c.ap[i] = A + (size_t)ar * lda + ch * 8;
;   }
; }
; __device__ __forceinline__ void h_stage(const WideCtx& c, int kt) {
;   const unsigned sb = c.lds0 + (kt & 1) * 24576;
; #pragma unroll
;   for (int i = 0; i < 2; ++i) glds16(c.wp[i] + kt * 32, sb + i * 4096);
; #pragma unroll
;   for (int i = 0; i < 4; ++i) glds16(c.ap[i] + kt * 32, sb + 8192 + i * 4096);
; }
; template <class F>
; __device__ __forceinline__ void gemm_phase_w(const u16* A, int lda, int M, const u16* W, int K, int N, char* lds, int* ctr, F&& epi) {
;   const int nN = N >> 7, nM = (M + 255) >> 8, nt = nN * nM, nk = K >> 5;
;   const int xcd = (int)xb_xcc_id() & 7;
;   const int tq = nt >> 3, trm = nt & 7;
;   const int tstart = xcd < trm ? xcd * (tq + 1) : trm * (tq + 1) + (xcd - trm) * tq;
;   const int tcnt = tq + (xcd < trm ? 1 : 0);
;   auto decode = [&](int off, int& tm, int& tn) {
;     const int id = tstart + off, nig = 4 * nN, grp = id / nig, fm = grp * 4;
;     const int gsz = (nM - fm) < 4 ? (nM - fm) : 4, idl = id - grp * nig;
;     tm = fm + idl % gsz; tn = idl / gsz;
;   };
;   WideCtx c;
;   h_init(c, lds);
;   const int wave = c.tid >> 6;
;   volatile int* bw = (volatile int*)(lds + 65536);
;   int* myctr = ctr + xcd;
;   int par = 0;
;   if (c.tid == 0) bw[2] = atomicAdd(myctr, 1);
;   asm volatile("s_waitcnt vmcnt(0) lgkmcnt(0)" ::: "memory");
;   __builtin_amdgcn_s_barrier();
;   int off = bw[2];
;   int tm = 0, tn = 0;
;   if (off < tcnt) { decode(off, tm, tn); h_tile(c, A, lda, M, tm * 256, W, K, tn * 128); h_stage(c, 0); }
.LBB0_612:
	s_or_b64 exec, exec, s[34:35]
	s_mov_b64 s[0:1], src_shared_base
	v_cndmask_b32_e64 v1, 0, 1, s[6:7]
	s_waitcnt vmcnt(0)
	v_mov_b32_e32 v163, s1
	v_add_u32_e32 v156, s24, v1
	s_waitcnt vmcnt(0) lgkmcnt(0)
	s_barrier
	flat_load_dword v1, v[162:163] sc0 sc1
	s_waitcnt vmcnt(0) lgkmcnt(0)
	v_cmp_lt_i32_e64 s[38:39], v1, v156
	s_and_saveexec_b64 s[44:45], s[38:39]
	s_cbranch_execz .LBB0_643
	v_and_b32_e32 v2, 31, v0
	v_lshrrev_b32_e32 v3, 1, v0
	s_mov_b32 s0, 0x3ffffc0
	v_and_or_b32 v2, v3, s0, v2
	s_lshl_b32 s0, s9, 4
	s_and_b32 s24, s0, 0xfffffc00
	s_and_b64 s[0:1], exec, s[86:87]
	v_add_u32_e32 v1, s11, v1
	s_mov_b32 s0, 0x7a44c6b
	v_lshlrev_b32_e32 v3, 6, v0
	v_lshlrev_b32_e32 v158, 6, v2
	v_mul_hi_i32 v2, v1, s0
	v_and_b32_e32 v157, 0x17c0, v3
	v_lshrrev_b32_e32 v3, 31, v2
	v_ashrrev_i32_e32 v2, 3, v2
	v_add_u32_e32 v2, v2, v3
	v_lshlrev_b32_e32 v3, 2, v2
	v_sub_u32_e32 v7, s10, v3
	v_min_i32_e32 v7, 4, v7
	v_sub_u32_e32 v8, 0, v7
	v_max_i32_e32 v8, v7, v8
	v_cvt_f32_u32_e32 v9, v8
	s_movk_i32 s0, 0xfef4
	v_mad_i32_i24 v1, v2, s0, v1
	v_sub_u32_e32 v11, 0, v8
	v_rcp_iflag_f32_e32 v2, v9
	v_sub_u32_e32 v10, 0, v1
	v_max_i32_e32 v10, v1, v10
	v_xor_b32_e32 v9, v1, v7
	v_mul_f32_e32 v2, 0x4f7ffffe, v2
	v_cvt_u32_f32_e32 v2, v2
	v_ashrrev_i32_e32 v9, 31, v9
	s_load_dwordx2 s[0:1], s[64:65], 0x130
	v_ashrrev_i32_e32 v159, 2, v0
	v_mul_lo_u32 v11, v11, v2
	v_mul_hi_u32 v11, v2, v11
	v_add_u32_e32 v2, v2, v11
	v_mul_hi_u32 v2, v10, v2
	v_mul_lo_u32 v11, v2, v8
	v_sub_u32_e32 v10, v10, v11
	v_add_u32_e32 v11, 1, v2
	v_cmp_ge_u32_e64 s[38:39], v10, v8
	s_cselect_b32 s47, s27, s93
	s_cselect_b32 s46, s26, s92
	v_cndmask_b32_e64 v2, v2, v11, s[38:39]
	v_sub_u32_e32 v11, v10, v8
	v_cndmask_b32_e64 v10, v10, v11, s[38:39]
	v_add_u32_e32 v11, 1, v2
	v_cmp_ge_u32_e64 s[38:39], v10, v8
	s_add_i32 s25, s62, -1
	s_add_i32 s52, s24, 0x1000
	v_cndmask_b32_e64 v2, v2, v11, s[38:39]
	v_xor_b32_e32 v2, v2, v9
	v_sub_u32_e32 v149, v2, v9
	v_mul_lo_u32 v2, v149, v7
	v_sub_u32_e32 v1, v1, v2
	v_lshrrev_b32_e32 v2, 4, v0
	v_and_b32_e32 v250, 1, v2
	v_lshlrev_b32_e32 v250, 1, v250
	v_xor_b32_e32 v2, v2, v250
	v_xor_b32_e32 v2, v2, v0
	v_lshlrev_b32_e32 v7, 7, v149
	v_lshlrev_b32_e32 v2, 4, v2
	v_and_b32_e32 v160, 48, v2
	v_add_u32_e32 v2, v7, v159
	v_add_u32_e32 v152, v1, v3
	v_ashrrev_i32_e32 v3, 31, v2
	s_waitcnt lgkmcnt(0)
	v_lshl_add_u64 v[128:129], s[0:1], 0, v[160:161]
	v_lshlrev_b64 v[2:3], 11, v[2:3]
	v_lshl_add_u64 v[132:133], v[128:129], 0, v[2:3]
	v_add_u32_e32 v2, 0x100, v0
	v_ashrrev_i32_e32 v163, 2, v2
	v_add_u32_e32 v2, v7, v163
	v_ashrrev_i32_e32 v3, 31, v2
	s_load_dwordx2 s[0:1], s[64:65], 0x1c0
	v_lshlrev_b32_e32 v1, 8, v152
	v_lshlrev_b64 v[2:3], 11, v[2:3]
	v_lshl_add_u64 v[134:135], v[128:129], 0, v[2:3]
	v_add_u32_e32 v2, v1, v159
	v_min_i32_e32 v2, s25, v2
	v_ashrrev_i32_e32 v3, 31, v2
	s_waitcnt lgkmcnt(0)
	v_lshl_add_u64 v[130:131], s[0:1], 0, v[160:161]
	v_lshlrev_b64 v[2:3], 11, v[2:3]
	v_lshl_add_u64 v[136:137], v[130:131], 0, v[2:3]
	v_add_u32_e32 v2, v1, v163
	v_min_i32_e32 v2, s25, v2
	v_ashrrev_i32_e32 v3, 31, v2
	v_lshlrev_b64 v[2:3], 11, v[2:3]
	v_lshl_add_u64 v[138:139], v[130:131], 0, v[2:3]
	v_add_u32_e32 v2, 0x200, v0
	v_ashrrev_i32_e32 v164, 2, v2
	v_add_u32_e32 v2, v1, v164
	v_min_i32_e32 v2, s25, v2
	v_ashrrev_i32_e32 v3, 31, v2
	v_lshlrev_b64 v[2:3], 11, v[2:3]
	v_lshl_add_u64 v[140:141], v[130:131], 0, v[2:3]
	v_add_u32_e32 v2, 0x300, v0
	v_ashrrev_i32_e32 v165, 2, v2
	s_mov_b32 s0, m0
	s_mov_b32 m0, s24
	s_nop 0
	global_load_lds_dwordx4 v[132:133], off
	s_mov_b32 m0, s0
	v_add_u32_e32 v1, v1, v165
	s_mov_b32 s0, m0
	s_mov_b32 m0, s52
	s_nop 0
	global_load_lds_dwordx4 v[134:135], off
	s_mov_b32 m0, s0
	v_min_i32_e32 v2, s25, v1
	s_add_i32 s53, s24, 0x2000
	s_mov_b32 s0, m0
	s_mov_b32 m0, s53
	s_nop 0
	global_load_lds_dwordx4 v[136:137], off
	s_mov_b32 m0, s0
	v_ashrrev_i32_e32 v3, 31, v2
	s_add_i32 s57, s24, 0x3000
	s_mov_b32 s0, m0
	s_mov_b32 m0, s57
	s_nop 0
	global_load_lds_dwordx4 v[138:139], off
	s_mov_b32 m0, s0
	v_lshlrev_b64 v[2:3], 11, v[2:3]
	s_add_i32 s58, s24, 0x4000
	s_mov_b32 s0, m0
	s_mov_b32 m0, s58
	s_nop 0
	global_load_lds_dwordx4 v[140:141], off
	s_mov_b32 m0, s0
	v_lshl_add_u64 v[142:143], v[130:131], 0, v[2:3]
	s_add_i32 s59, s24, 0x5000
	s_mov_b32 s0, m0
	s_mov_b32 m0, s59
	s_nop 0
	global_load_lds_dwordx4 v[142:143], off
	s_mov_b32 m0, s0
	s_add_i32 m0, s24, 0x5fc0
	s_nop 0
	global_load_lds_dwordx4 v[132:133], off offset:64
	s_add_i32 m0, s52, 0x5fc0
	s_nop 0
	global_load_lds_dwordx4 v[134:135], off offset:64
	s_add_i32 m0, s53, 0x5fc0
	s_nop 0
	global_load_lds_dwordx4 v[136:137], off offset:64
	s_add_i32 m0, s57, 0x5fc0
	s_nop 0
	global_load_lds_dwordx4 v[138:139], off offset:64
	s_add_i32 m0, s58, 0x5fc0
	s_nop 0
	global_load_lds_dwordx4 v[140:141], off offset:64
	s_add_i32 m0, s59, 0x5fc0
	s_nop 0
	global_load_lds_dwordx4 v[142:143], off offset:64
	s_load_dwordx2 s[48:49], s[64:65], 0x228
	s_load_dwordx2 s[50:51], s[64:65], 0x1a8
	v_bfe_u32 v4, v0, 5, 1
	v_lshrrev_b32_e32 v5, 2, v0
	v_bfe_u32 v6, v0, 2, 2
	v_bitop3_b32 v1, v5, v4, 3 bitop3:0x6c
	v_lshlrev_b32_e32 v166, 4, v1
	v_bitop3_b32 v1, v4, v6, 2 bitop3:0x36
	v_and_b32_e32 v168, 64, v0
	v_ashrrev_i32_e32 v0, 1, v0
	s_add_i32 s0, s77, 63
	s_mov_b32 s9, 0
	v_lshlrev_b32_e32 v167, 4, v1
	v_and_b32_e32 v169, 0xffffffc0, v0
	s_add_i32 s33, s33, -1
	s_and_b32 s63, s0, 0x3fc0
	s_mov_b64 s[54:55], 0
	s_branch .LBB0_615

; __device__ __forceinline__ void zero_acc(f32x16 (&acc)[2][2]) {
; #pragma unroll
;   for (int a = 0; a < 2; ++a)
; #pragma unroll
;     for (int b = 0; b < 2; ++b)
; #pragma unroll
;       for (int r = 0; r < 16; ++r) acc[a][b][r] = 0.f;
; }
; __device__ __forceinline__ void h_main(f32x16 (&acc0)[2][2], f32x16 (&acc1)[2][2], const WideCtx& c, int nk, char* lds) {
;   const int h = c.h;
;   for (int kt = 0; kt < nk; ++kt) {
;     asm volatile("s_waitcnt vmcnt(0)" ::: "memory");
;     __builtin_amdgcn_s_barrier();
;     if (kt + 1 < nk) h_stage(c, kt + 1);
;     const char* st = lds + (kt & 1) * 24576;
; #pragma unroll
;     for (int ks = 0; ks < 2; ++ks) {
;       bf16x8 wf[2], a0[2], a1[2];
; #pragma unroll
;       for (int b = 0; b < 2; ++b) {
;         wf[b] = *(const bf16x8*)(st + c.wro[b] + (((ks * 2 + h) ^ c.wsw[b]) << 4));
;         a0[b] = *(const bf16x8*)(st + c.aro[0][b] + (((ks * 2 + h) ^ c.asw[0][b]) << 4));
;         a1[b] = *(const bf16x8*)(st + c.aro[1][b] + (((ks * 2 + h) ^ c.asw[1][b]) << 4));
;       }
; #pragma unroll
;       for (int nb = 0; nb < 2; ++nb)
; #pragma unroll
;         for (int tb = 0; tb < 2; ++tb) {
;           acc0[nb][tb] = __builtin_amdgcn_mfma_f32_32x32x16_bf16(wf[nb], a0[tb], acc0[nb][tb], 0, 0, 0);
;           acc1[nb][tb] = __builtin_amdgcn_mfma_f32_32x32x16_bf16(wf[nb], a1[tb], acc1[nb][tb], 0, 0, 0);
;         }
.LBB0_615:
	v_mov_b32_e32 v64, 0
	v_mov_b32_e32 v170, v152
	v_mov_b32_e32 v160, v149
	s_load_dwordx2 s[0:1], s[64:65], 0x120
	s_waitcnt lgkmcnt(0)
	v_subrev_u32_e32 v144, s0, v142
	v_subrev_u32_e32 v146, s0, v140
	v_subrev_u32_e32 v148, s0, v138
	v_subrev_u32_e32 v150, s0, v136
	v_subrev_u32_e32 v152, s0, v134
	v_subrev_u32_e32 v154, s0, v132
	s_add_u32 s0, s0, 0x80
	s_addc_u32 s1, s1, 0
	s_mov_b32 s9, 2
	s_mov_b32 s6, 0
	v_and_b32_e32 v250, 15, v204
	v_lshlrev_b32_e32 v250, 6, v250
	v_bfe_u32 v251, v204, 2, 2
	v_and_b32_e32 v247, 1, v251
	v_lshlrev_b32_e32 v247, 1, v247
	v_xor_b32_e32 v251, v251, v247
	v_bfe_u32 v247, v204, 4, 2
	v_xor_b32_e32 v251, v251, v247
	v_lshl_or_b32 v250, v251, 4, v250
	v_bfe_u32 v247, v204, 6, 1
	v_lshl_or_b32 v248, v247, 12, v250
	v_lshrrev_b32_e32 v247, 7, v204
	v_lshl_or_b32 v249, v247, 12, v250
	v_mov_b32_e32 v65, v64
	v_mov_b32_e32 v66, v64
	v_mov_b32_e32 v67, v64
	v_mov_b32_e32 v68, v64
	v_mov_b32_e32 v69, v64
	v_mov_b32_e32 v70, v64
	v_mov_b32_e32 v71, v64
	v_mov_b32_e32 v72, v64
	v_mov_b32_e32 v73, v64
	v_mov_b32_e32 v74, v64
	v_mov_b32_e32 v75, v64
	v_mov_b32_e32 v76, v64
	v_mov_b32_e32 v77, v64
	v_mov_b32_e32 v78, v64
	v_mov_b32_e32 v79, v64
	v_mov_b32_e32 v96, v64
	v_mov_b32_e32 v97, v64
	v_mov_b32_e32 v98, v64
	v_mov_b32_e32 v99, v64
	v_mov_b32_e32 v100, v64
	v_mov_b32_e32 v101, v64
	v_mov_b32_e32 v102, v64
	v_mov_b32_e32 v103, v64
	v_mov_b32_e32 v104, v64
	v_mov_b32_e32 v105, v64
	v_mov_b32_e32 v106, v64
	v_mov_b32_e32 v107, v64
	v_mov_b32_e32 v108, v64
	v_mov_b32_e32 v109, v64
	v_mov_b32_e32 v110, v64
	v_mov_b32_e32 v111, v64
	v_mov_b32_e32 v80, v64
	v_mov_b32_e32 v81, v64
	v_mov_b32_e32 v82, v64
	v_mov_b32_e32 v83, v64
	v_mov_b32_e32 v84, v64
	v_mov_b32_e32 v85, v64
	v_mov_b32_e32 v86, v64
	v_mov_b32_e32 v87, v64
	v_mov_b32_e32 v88, v64
	v_mov_b32_e32 v89, v64
	v_mov_b32_e32 v90, v64
	v_mov_b32_e32 v91, v64
	v_mov_b32_e32 v92, v64
	v_mov_b32_e32 v93, v64
	v_mov_b32_e32 v94, v64
	v_mov_b32_e32 v95, v64
	v_mov_b32_e32 v112, v64
	v_mov_b32_e32 v113, v64
	v_mov_b32_e32 v114, v64
	v_mov_b32_e32 v115, v64
	v_mov_b32_e32 v116, v64
	v_mov_b32_e32 v117, v64
	v_mov_b32_e32 v118, v64
	v_mov_b32_e32 v119, v64
	v_mov_b32_e32 v120, v64
	v_mov_b32_e32 v121, v64
	v_mov_b32_e32 v122, v64
	v_mov_b32_e32 v123, v64
	v_mov_b32_e32 v124, v64
	v_mov_b32_e32 v125, v64
	v_mov_b32_e32 v126, v64
	v_mov_b32_e32 v127, v64
	v_mov_b32_e32 v0, v64
	v_mov_b32_e32 v1, v64
	v_mov_b32_e32 v2, v64
	v_mov_b32_e32 v3, v64
	v_mov_b32_e32 v4, v64
	v_mov_b32_e32 v5, v64
	v_mov_b32_e32 v6, v64
	v_mov_b32_e32 v7, v64
	v_mov_b32_e32 v8, v64
	v_mov_b32_e32 v9, v64
	v_mov_b32_e32 v10, v64
	v_mov_b32_e32 v11, v64
	v_mov_b32_e32 v12, v64
	v_mov_b32_e32 v13, v64
	v_mov_b32_e32 v14, v64
	v_mov_b32_e32 v15, v64
	v_mov_b32_e32 v32, v64
	v_mov_b32_e32 v33, v64
	v_mov_b32_e32 v34, v64
	v_mov_b32_e32 v35, v64
	v_mov_b32_e32 v36, v64
	v_mov_b32_e32 v37, v64
	v_mov_b32_e32 v38, v64
	v_mov_b32_e32 v39, v64
	v_mov_b32_e32 v40, v64
	v_mov_b32_e32 v41, v64
	v_mov_b32_e32 v42, v64
	v_mov_b32_e32 v43, v64
	v_mov_b32_e32 v44, v64
	v_mov_b32_e32 v45, v64
	v_mov_b32_e32 v46, v64
	v_mov_b32_e32 v47, v64
	v_mov_b32_e32 v16, v64
	v_mov_b32_e32 v17, v64
	v_mov_b32_e32 v18, v64
	v_mov_b32_e32 v19, v64
	v_mov_b32_e32 v20, v64
	v_mov_b32_e32 v21, v64
	v_mov_b32_e32 v22, v64
	v_mov_b32_e32 v23, v64
	v_mov_b32_e32 v24, v64
	v_mov_b32_e32 v25, v64
	v_mov_b32_e32 v26, v64
	v_mov_b32_e32 v27, v64
	v_mov_b32_e32 v28, v64
	v_mov_b32_e32 v29, v64
	v_mov_b32_e32 v30, v64
	v_mov_b32_e32 v31, v64
	v_mov_b32_e32 v48, v64
	v_mov_b32_e32 v49, v64
	v_mov_b32_e32 v50, v64
	v_mov_b32_e32 v51, v64
	v_mov_b32_e32 v52, v64
	v_mov_b32_e32 v53, v64
	v_mov_b32_e32 v54, v64
	v_mov_b32_e32 v55, v64
	v_mov_b32_e32 v56, v64
	v_mov_b32_e32 v57, v64
	v_mov_b32_e32 v58, v64
	v_mov_b32_e32 v59, v64
	v_mov_b32_e32 v60, v64
	v_mov_b32_e32 v61, v64
	v_mov_b32_e32 v62, v64
	v_mov_b32_e32 v63, v64
.LBB0_616:
	s_waitcnt vmcnt(6)
	s_barrier
	v_add_u32_e32 v171, s6, v248
	v_add_u32_e32 v196, s6, v249
	ds_read_b128 v[172:175], v171
	ds_read_b128 v[176:179], v196 offset:8192
	ds_read_b128 v[188:191], v196 offset:9216
	ds_read_b128 v[180:183], v196 offset:10240
	ds_read_b128 v[192:195], v196 offset:11264
	ds_read_b128 v[230:233], v196 offset:16384
	ds_read_b128 v[234:237], v196 offset:17408
	ds_read_b128 v[238:241], v196 offset:18432
	ds_read_b128 v[242:245], v196 offset:19456
	ds_read_b128 v[184:187], v171 offset:1024
	ds_read_b128 v[222:225], v171 offset:2048
	ds_read_b128 v[226:229], v171 offset:3072
	s_add_i32 s7, s6, 0xffffa000
	s_cmp_eq_u32 s6, 0
	s_cselect_b32 s7, 0xc000, s7
	s_add_i32 m0, s7, s24
	s_add_i32 s7, s6, 0x6000
	global_load_lds_dwordx4 v154, s[0:1]
	s_add_i32 m0, m0, 0x1000
	s_cmp_eq_u32 s6, 0xc000
	global_load_lds_dwordx4 v152, s[0:1]
	s_cselect_b32 s6, 0, s7
	s_add_i32 m0, m0, 0x1000
	s_waitcnt lgkmcnt(10)
	v_mfma_f32_16x16x32_bf16 v[112:115], v[172:175], v[176:179], v[112:115]
	global_load_lds_dwordx4 v150, s[0:1]
	s_add_i32 m0, m0, 0x1000
	s_waitcnt lgkmcnt(9)
	v_mfma_f32_16x16x32_bf16 v[116:119], v[172:175], v[188:191], v[116:119]
	global_load_lds_dwordx4 v148, s[0:1]
	s_add_i32 m0, m0, 0x1000
	s_waitcnt lgkmcnt(8)
	v_mfma_f32_16x16x32_bf16 v[80:83], v[172:175], v[180:183], v[80:83]
	global_load_lds_dwordx4 v146, s[0:1]
	s_add_i32 m0, m0, 0x1000
	s_waitcnt lgkmcnt(7)
	v_mfma_f32_16x16x32_bf16 v[84:87], v[172:175], v[192:195], v[84:87]
	global_load_lds_dwordx4 v144, s[0:1]
	s_add_u32 s0, s0, 64
	s_addc_u32 s1, s1, 0
	s_waitcnt lgkmcnt(6)
	v_mfma_f32_16x16x32_bf16 v[48:51], v[172:175], v[230:233], v[48:51]
	s_waitcnt lgkmcnt(5)
	v_mfma_f32_16x16x32_bf16 v[52:55], v[172:175], v[234:237], v[52:55]
	s_waitcnt lgkmcnt(4)
; __device__ __forceinline__ void h_main(f32x16 (&acc0)[2][2], f32x16 (&acc1)[2][2], const WideCtx& c, int nk, char* lds) {
;   const int h = c.h;
;   for (int kt = 0; kt < nk; ++kt) {
;     asm volatile("s_waitcnt vmcnt(0)" ::: "memory");
;     __builtin_amdgcn_s_barrier();
;     if (kt + 1 < nk) h_stage(c, kt + 1);
;     const char* st = lds + (kt & 1) * 24576;
; #pragma unroll
;     for (int ks = 0; ks < 2; ++ks) {
;       bf16x8 wf[2], a0[2], a1[2];
; #pragma unroll
;       for (int b = 0; b < 2; ++b) {
;         wf[b] = *(const bf16x8*)(st + c.wro[b] + (((ks * 2 + h) ^ c.wsw[b]) << 4));
;         a0[b] = *(const bf16x8*)(st + c.aro[0][b] + (((ks * 2 + h) ^ c.asw[0][b]) << 4));
;         a1[b] = *(const bf16x8*)(st + c.aro[1][b] + (((ks * 2 + h) ^ c.asw[1][b]) << 4));
;       }
; #pragma unroll
;       for (int nb = 0; nb < 2; ++nb)
; #pragma unroll
;         for (int tb = 0; tb < 2; ++tb) {
;           acc0[nb][tb] = __builtin_amdgcn_mfma_f32_32x32x16_bf16(wf[nb], a0[tb], acc0[nb][tb], 0, 0, 0);
;           acc1[nb][tb] = __builtin_amdgcn_mfma_f32_32x32x16_bf16(wf[nb], a1[tb], acc1[nb][tb], 0, 0, 0);
;         }
;     }
;   }
	v_mfma_f32_16x16x32_bf16 v[16:19], v[172:175], v[238:241], v[16:19]
	s_waitcnt lgkmcnt(3)
	v_mfma_f32_16x16x32_bf16 v[20:23], v[172:175], v[242:245], v[20:23]
	s_waitcnt lgkmcnt(2)
	v_mfma_f32_16x16x32_bf16 v[120:123], v[184:187], v[176:179], v[120:123]
	v_mfma_f32_16x16x32_bf16 v[124:127], v[184:187], v[188:191], v[124:127]
	v_mfma_f32_16x16x32_bf16 v[88:91], v[184:187], v[180:183], v[88:91]
	v_mfma_f32_16x16x32_bf16 v[92:95], v[184:187], v[192:195], v[92:95]
	v_mfma_f32_16x16x32_bf16 v[56:59], v[184:187], v[230:233], v[56:59]
	v_mfma_f32_16x16x32_bf16 v[60:63], v[184:187], v[234:237], v[60:63]
	v_mfma_f32_16x16x32_bf16 v[24:27], v[184:187], v[238:241], v[24:27]
	v_mfma_f32_16x16x32_bf16 v[28:31], v[184:187], v[242:245], v[28:31]
	s_waitcnt lgkmcnt(1)
	v_mfma_f32_16x16x32_bf16 v[96:99], v[222:225], v[176:179], v[96:99]
	v_mfma_f32_16x16x32_bf16 v[100:103], v[222:225], v[188:191], v[100:103]
	v_mfma_f32_16x16x32_bf16 v[64:67], v[222:225], v[180:183], v[64:67]
	v_mfma_f32_16x16x32_bf16 v[68:71], v[222:225], v[192:195], v[68:71]
	v_mfma_f32_16x16x32_bf16 v[32:35], v[222:225], v[230:233], v[32:35]
	v_mfma_f32_16x16x32_bf16 v[36:39], v[222:225], v[234:237], v[36:39]
	v_mfma_f32_16x16x32_bf16 v[0:3], v[222:225], v[238:241], v[0:3]
	v_mfma_f32_16x16x32_bf16 v[4:7], v[222:225], v[242:245], v[4:7]
	s_waitcnt lgkmcnt(0)
	v_mfma_f32_16x16x32_bf16 v[104:107], v[226:229], v[176:179], v[104:107]
	v_mfma_f32_16x16x32_bf16 v[108:111], v[226:229], v[188:191], v[108:111]
	v_mfma_f32_16x16x32_bf16 v[72:75], v[226:229], v[180:183], v[72:75]
	v_mfma_f32_16x16x32_bf16 v[76:79], v[226:229], v[192:195], v[76:79]
	v_mfma_f32_16x16x32_bf16 v[40:43], v[226:229], v[230:233], v[40:43]
	v_mfma_f32_16x16x32_bf16 v[44:47], v[226:229], v[234:237], v[44:47]
	v_mfma_f32_16x16x32_bf16 v[8:11], v[226:229], v[238:241], v[8:11]
	v_mfma_f32_16x16x32_bf16 v[12:15], v[226:229], v[242:245], v[12:15]
	s_add_i32 s9, s9, 1
	s_cmp_eq_u32 s9, 32
	s_cbranch_scc0 .LBB0_616
	s_waitcnt vmcnt(6)
	s_barrier
	v_add_u32_e32 v171, s6, v248
	v_add_u32_e32 v196, s6, v249
	ds_read_b128 v[172:175], v171
	ds_read_b128 v[176:179], v196 offset:8192
	ds_read_b128 v[188:191], v196 offset:9216
	ds_read_b128 v[180:183], v196 offset:10240
	ds_read_b128 v[192:195], v196 offset:11264
	ds_read_b128 v[230:233], v196 offset:16384
	ds_read_b128 v[234:237], v196 offset:17408
	ds_read_b128 v[238:241], v196 offset:18432
	ds_read_b128 v[242:245], v196 offset:19456
	ds_read_b128 v[184:187], v171 offset:1024
	ds_read_b128 v[222:225], v171 offset:2048
	ds_read_b128 v[226:229], v171 offset:3072
	s_add_i32 s7, s6, 0x6000
	s_cmp_eq_u32 s6, 0xc000
	s_cselect_b32 s6, 0, s7
	s_waitcnt lgkmcnt(10)
	v_mfma_f32_16x16x32_bf16 v[112:115], v[172:175], v[176:179], v[112:115]
	s_waitcnt lgkmcnt(9)
	v_mfma_f32_16x16x32_bf16 v[116:119], v[172:175], v[188:191], v[116:119]
	s_waitcnt lgkmcnt(8)
	v_mfma_f32_16x16x32_bf16 v[80:83], v[172:175], v[180:183], v[80:83]
	s_waitcnt lgkmcnt(7)
	v_mfma_f32_16x16x32_bf16 v[84:87], v[172:175], v[192:195], v[84:87]
	s_waitcnt lgkmcnt(6)
	v_mfma_f32_16x16x32_bf16 v[48:51], v[172:175], v[230:233], v[48:51]
	s_waitcnt lgkmcnt(5)
	v_mfma_f32_16x16x32_bf16 v[52:55], v[172:175], v[234:237], v[52:55]
	s_waitcnt lgkmcnt(4)
	v_mfma_f32_16x16x32_bf16 v[16:19], v[172:175], v[238:241], v[16:19]
	s_waitcnt lgkmcnt(3)
	v_mfma_f32_16x16x32_bf16 v[20:23], v[172:175], v[242:245], v[20:23]
	s_waitcnt lgkmcnt(2)
	v_mfma_f32_16x16x32_bf16 v[120:123], v[184:187], v[176:179], v[120:123]
	v_mfma_f32_16x16x32_bf16 v[124:127], v[184:187], v[188:191], v[124:127]
	v_mfma_f32_16x16x32_bf16 v[88:91], v[184:187], v[180:183], v[88:91]
	v_mfma_f32_16x16x32_bf16 v[92:95], v[184:187], v[192:195], v[92:95]
	v_mfma_f32_16x16x32_bf16 v[56:59], v[184:187], v[230:233], v[56:59]
	v_mfma_f32_16x16x32_bf16 v[60:63], v[184:187], v[234:237], v[60:63]
	v_mfma_f32_16x16x32_bf16 v[24:27], v[184:187], v[238:241], v[24:27]
	v_mfma_f32_16x16x32_bf16 v[28:31], v[184:187], v[242:245], v[28:31]
	s_waitcnt lgkmcnt(1)
	v_mfma_f32_16x16x32_bf16 v[96:99], v[222:225], v[176:179], v[96:99]
	v_mfma_f32_16x16x32_bf16 v[100:103], v[222:225], v[188:191], v[100:103]
	v_mfma_f32_16x16x32_bf16 v[64:67], v[222:225], v[180:183], v[64:67]
	v_mfma_f32_16x16x32_bf16 v[68:71], v[222:225], v[192:195], v[68:71]
	v_mfma_f32_16x16x32_bf16 v[32:35], v[222:225], v[230:233], v[32:35]
	v_mfma_f32_16x16x32_bf16 v[36:39], v[222:225], v[234:237], v[36:39]
	v_mfma_f32_16x16x32_bf16 v[0:3], v[222:225], v[238:241], v[0:3]
	v_mfma_f32_16x16x32_bf16 v[4:7], v[222:225], v[242:245], v[4:7]
	s_waitcnt lgkmcnt(0)
	v_mfma_f32_16x16x32_bf16 v[104:107], v[226:229], v[176:179], v[104:107]
	v_mfma_f32_16x16x32_bf16 v[108:111], v[226:229], v[188:191], v[108:111]
	v_mfma_f32_16x16x32_bf16 v[72:75], v[226:229], v[180:183], v[72:75]
	v_mfma_f32_16x16x32_bf16 v[76:79], v[226:229], v[192:195], v[76:79]
	v_mfma_f32_16x16x32_bf16 v[40:43], v[226:229], v[230:233], v[40:43]
	v_mfma_f32_16x16x32_bf16 v[44:47], v[226:229], v[234:237], v[44:47]
	v_mfma_f32_16x16x32_bf16 v[8:11], v[226:229], v[238:241], v[8:11]
	v_mfma_f32_16x16x32_bf16 v[12:15], v[226:229], v[242:245], v[12:15]
	s_waitcnt vmcnt(0)
	s_barrier
; __device__ __forceinline__ void h_main(f32x16 (&acc0)[2][2], f32x16 (&acc1)[2][2], const WideCtx& c, int nk, char* lds) {
;   const int h = c.h;
;   for (int kt = 0; kt < nk; ++kt) {
;     asm volatile("s_waitcnt vmcnt(0)" ::: "memory");
;     __builtin_amdgcn_s_barrier();
;     if (kt + 1 < nk) h_stage(c, kt + 1);
;     const char* st = lds + (kt & 1) * 24576;
; #pragma unroll
;     for (int ks = 0; ks < 2; ++ks) {
;       bf16x8 wf[2], a0[2], a1[2];
; #pragma unroll
;       for (int b = 0; b < 2; ++b) {
;         wf[b] = *(const bf16x8*)(st + c.wro[b] + (((ks * 2 + h) ^ c.wsw[b]) << 4));
;         a0[b] = *(const bf16x8*)(st + c.aro[0][b] + (((ks * 2 + h) ^ c.asw[0][b]) << 4));
;         a1[b] = *(const bf16x8*)(st + c.aro[1][b] + (((ks * 2 + h) ^ c.asw[1][b]) << 4));
;       }
; #pragma unroll
;       for (int nb = 0; nb < 2; ++nb)
; #pragma unroll
;         for (int tb = 0; tb < 2; ++tb) {
;           acc0[nb][tb] = __builtin_amdgcn_mfma_f32_32x32x16_bf16(wf[nb], a0[tb], acc0[nb][tb], 0, 0, 0);
;           acc1[nb][tb] = __builtin_amdgcn_mfma_f32_32x32x16_bf16(wf[nb], a1[tb], acc1[nb][tb], 0, 0, 0);
;         }
	v_add_u32_e32 v171, s6, v248
	v_add_u32_e32 v196, s6, v249
	ds_read_b128 v[172:175], v171
	ds_read_b128 v[176:179], v196 offset:8192
	ds_read_b128 v[188:191], v196 offset:9216
	ds_read_b128 v[180:183], v196 offset:10240
	ds_read_b128 v[192:195], v196 offset:11264
	ds_read_b128 v[230:233], v196 offset:16384
	ds_read_b128 v[234:237], v196 offset:17408
	ds_read_b128 v[238:241], v196 offset:18432
	ds_read_b128 v[242:245], v196 offset:19456
	ds_read_b128 v[184:187], v171 offset:1024
	ds_read_b128 v[222:225], v171 offset:2048
	ds_read_b128 v[226:229], v171 offset:3072
	s_add_i32 s7, s6, 0x6000
	s_cmp_eq_u32 s6, 0xc000
	s_cselect_b32 s6, 0, s7
	s_waitcnt lgkmcnt(10)
	v_mfma_f32_16x16x32_bf16 v[112:115], v[172:175], v[176:179], v[112:115]
	s_waitcnt lgkmcnt(9)
	v_mfma_f32_16x16x32_bf16 v[116:119], v[172:175], v[188:191], v[116:119]
	s_waitcnt lgkmcnt(8)
	v_mfma_f32_16x16x32_bf16 v[80:83], v[172:175], v[180:183], v[80:83]
	s_waitcnt lgkmcnt(7)
	v_mfma_f32_16x16x32_bf16 v[84:87], v[172:175], v[192:195], v[84:87]
	s_waitcnt lgkmcnt(6)
	v_mfma_f32_16x16x32_bf16 v[48:51], v[172:175], v[230:233], v[48:51]
	s_waitcnt lgkmcnt(5)
	v_mfma_f32_16x16x32_bf16 v[52:55], v[172:175], v[234:237], v[52:55]
	s_waitcnt lgkmcnt(4)
	v_mfma_f32_16x16x32_bf16 v[16:19], v[172:175], v[238:241], v[16:19]
	s_waitcnt lgkmcnt(3)
	v_mfma_f32_16x16x32_bf16 v[20:23], v[172:175], v[242:245], v[20:23]
	s_waitcnt lgkmcnt(2)
	v_mfma_f32_16x16x32_bf16 v[120:123], v[184:187], v[176:179], v[120:123]
	v_mfma_f32_16x16x32_bf16 v[124:127], v[184:187], v[188:191], v[124:127]
	v_mfma_f32_16x16x32_bf16 v[88:91], v[184:187], v[180:183], v[88:91]
	v_mfma_f32_16x16x32_bf16 v[92:95], v[184:187], v[192:195], v[92:95]
	v_mfma_f32_16x16x32_bf16 v[56:59], v[184:187], v[230:233], v[56:59]
	v_mfma_f32_16x16x32_bf16 v[60:63], v[184:187], v[234:237], v[60:63]
	v_mfma_f32_16x16x32_bf16 v[24:27], v[184:187], v[238:241], v[24:27]
	v_mfma_f32_16x16x32_bf16 v[28:31], v[184:187], v[242:245], v[28:31]
	s_waitcnt lgkmcnt(1)
	v_mfma_f32_16x16x32_bf16 v[96:99], v[222:225], v[176:179], v[96:99]
	v_mfma_f32_16x16x32_bf16 v[100:103], v[222:225], v[188:191], v[100:103]
	v_mfma_f32_16x16x32_bf16 v[64:67], v[222:225], v[180:183], v[64:67]
	v_mfma_f32_16x16x32_bf16 v[68:71], v[222:225], v[192:195], v[68:71]
	v_mfma_f32_16x16x32_bf16 v[32:35], v[222:225], v[230:233], v[32:35]
	v_mfma_f32_16x16x32_bf16 v[36:39], v[222:225], v[234:237], v[36:39]
	v_mfma_f32_16x16x32_bf16 v[0:3], v[222:225], v[238:241], v[0:3]
	v_mfma_f32_16x16x32_bf16 v[4:7], v[222:225], v[242:245], v[4:7]
	s_waitcnt lgkmcnt(0)
; __device__ __forceinline__ void h_main(f32x16 (&acc0)[2][2], f32x16 (&acc1)[2][2], const WideCtx& c, int nk, char* lds) {
;   const int h = c.h;
;   for (int kt = 0; kt < nk; ++kt) {
;     asm volatile("s_waitcnt vmcnt(0)" ::: "memory");
;     __builtin_amdgcn_s_barrier();
;     if (kt + 1 < nk) h_stage(c, kt + 1);
;     const char* st = lds + (kt & 1) * 24576;
; #pragma unroll
;     for (int ks = 0; ks < 2; ++ks) {
;       bf16x8 wf[2], a0[2], a1[2];
; #pragma unroll
;       for (int b = 0; b < 2; ++b) {
;         wf[b] = *(const bf16x8*)(st + c.wro[b] + (((ks * 2 + h) ^ c.wsw[b]) << 4));
;         a0[b] = *(const bf16x8*)(st + c.aro[0][b] + (((ks * 2 + h) ^ c.asw[0][b]) << 4));
;         a1[b] = *(const bf16x8*)(st + c.aro[1][b] + (((ks * 2 + h) ^ c.asw[1][b]) << 4));
;       }
; #pragma unroll
;       for (int nb = 0; nb < 2; ++nb)
; #pragma unroll
;         for (int tb = 0; tb < 2; ++tb) {
;           acc0[nb][tb] = __builtin_amdgcn_mfma_f32_32x32x16_bf16(wf[nb], a0[tb], acc0[nb][tb], 0, 0, 0);
;           acc1[nb][tb] = __builtin_amdgcn_mfma_f32_32x32x16_bf16(wf[nb], a1[tb], acc1[nb][tb], 0, 0, 0);
;         }
;     }
;   }
; template <class F>
; __device__ __forceinline__ void gemm_phase_w(const u16* A, int lda, int M, const u16* W, int K, int N, char* lds, int* ctr, F&& epi) {
;     ...
;     const int ctm = tm, ctn = tn;
;     par ^= 1;
;     if (c.tid == 0) bw[2 + par] = atomicAdd(myctr, 1);
	v_mfma_f32_16x16x32_bf16 v[104:107], v[226:229], v[176:179], v[104:107]
	v_mfma_f32_16x16x32_bf16 v[108:111], v[226:229], v[188:191], v[108:111]
	v_mfma_f32_16x16x32_bf16 v[72:75], v[226:229], v[180:183], v[72:75]
	v_mfma_f32_16x16x32_bf16 v[76:79], v[226:229], v[192:195], v[76:79]
	v_mfma_f32_16x16x32_bf16 v[40:43], v[226:229], v[230:233], v[40:43]
	v_mfma_f32_16x16x32_bf16 v[44:47], v[226:229], v[234:237], v[44:47]
	v_mfma_f32_16x16x32_bf16 v[8:11], v[226:229], v[238:241], v[8:11]
	v_mfma_f32_16x16x32_bf16 v[12:15], v[226:229], v[242:245], v[12:15]
	s_xor_b32 s9, s9, 1
	s_nop 7
	s_nop 7
	v_permlane16_swap_b32_e32 v112, v116
	v_permlane16_swap_b32_e32 v113, v117
	v_permlane16_swap_b32_e32 v114, v118
	v_permlane16_swap_b32_e32 v115, v119
	v_permlane16_swap_b32_e32 v120, v124
	v_permlane16_swap_b32_e32 v121, v125
	v_permlane16_swap_b32_e32 v122, v126
	v_permlane16_swap_b32_e32 v123, v127
	v_permlane16_swap_b32_e32 v80, v84
	v_permlane16_swap_b32_e32 v81, v85
	v_permlane16_swap_b32_e32 v82, v86
	v_permlane16_swap_b32_e32 v83, v87
	v_permlane16_swap_b32_e32 v88, v92
	v_permlane16_swap_b32_e32 v89, v93
	v_permlane16_swap_b32_e32 v90, v94
	v_permlane16_swap_b32_e32 v91, v95
	v_permlane16_swap_b32_e32 v48, v52
	v_permlane16_swap_b32_e32 v49, v53
	v_permlane16_swap_b32_e32 v50, v54
	v_permlane16_swap_b32_e32 v51, v55
	v_permlane16_swap_b32_e32 v56, v60
	v_permlane16_swap_b32_e32 v57, v61
	v_permlane16_swap_b32_e32 v58, v62
	v_permlane16_swap_b32_e32 v59, v63
	v_permlane16_swap_b32_e32 v16, v20
	v_permlane16_swap_b32_e32 v17, v21
	v_permlane16_swap_b32_e32 v18, v22
	v_permlane16_swap_b32_e32 v19, v23
	v_permlane16_swap_b32_e32 v24, v28
	v_permlane16_swap_b32_e32 v25, v29
	v_permlane16_swap_b32_e32 v26, v30
	v_permlane16_swap_b32_e32 v27, v31
	v_permlane16_swap_b32_e32 v96, v100
	v_permlane16_swap_b32_e32 v97, v101
	v_permlane16_swap_b32_e32 v98, v102
	v_permlane16_swap_b32_e32 v99, v103
	v_permlane16_swap_b32_e32 v104, v108
	v_permlane16_swap_b32_e32 v105, v109
	v_permlane16_swap_b32_e32 v106, v110
	v_permlane16_swap_b32_e32 v107, v111
	v_permlane16_swap_b32_e32 v64, v68
	v_permlane16_swap_b32_e32 v65, v69
	v_permlane16_swap_b32_e32 v66, v70
	v_permlane16_swap_b32_e32 v67, v71
	v_permlane16_swap_b32_e32 v72, v76
	v_permlane16_swap_b32_e32 v73, v77
	v_permlane16_swap_b32_e32 v74, v78
	v_permlane16_swap_b32_e32 v75, v79
	v_permlane16_swap_b32_e32 v32, v36
	v_permlane16_swap_b32_e32 v33, v37
	v_permlane16_swap_b32_e32 v34, v38
	v_permlane16_swap_b32_e32 v35, v39
	v_permlane16_swap_b32_e32 v40, v44
	v_permlane16_swap_b32_e32 v41, v45
	v_permlane16_swap_b32_e32 v42, v46
	v_permlane16_swap_b32_e32 v43, v47
	v_permlane16_swap_b32_e32 v0, v4
	v_permlane16_swap_b32_e32 v1, v5
	v_permlane16_swap_b32_e32 v2, v6
	v_permlane16_swap_b32_e32 v3, v7
	v_permlane16_swap_b32_e32 v8, v12
	v_permlane16_swap_b32_e32 v9, v13
	v_permlane16_swap_b32_e32 v10, v14
	v_permlane16_swap_b32_e32 v11, v15
	v_permlane32_swap_b32_e32 v112, v116
	v_permlane32_swap_b32_e32 v113, v117
	v_permlane32_swap_b32_e32 v114, v118
	v_permlane32_swap_b32_e32 v115, v119
	v_permlane32_swap_b32_e32 v120, v124
	v_permlane32_swap_b32_e32 v121, v125
	v_permlane32_swap_b32_e32 v122, v126
	v_permlane32_swap_b32_e32 v123, v127
	v_permlane32_swap_b32_e32 v80, v84
	v_permlane32_swap_b32_e32 v81, v85
	v_permlane32_swap_b32_e32 v82, v86
	v_permlane32_swap_b32_e32 v83, v87
	v_permlane32_swap_b32_e32 v88, v92
	v_permlane32_swap_b32_e32 v89, v93
	v_permlane32_swap_b32_e32 v90, v94
	v_permlane32_swap_b32_e32 v91, v95
	v_permlane32_swap_b32_e32 v48, v52
	v_permlane32_swap_b32_e32 v49, v53
	v_permlane32_swap_b32_e32 v50, v54
	v_permlane32_swap_b32_e32 v51, v55
	v_permlane32_swap_b32_e32 v56, v60
	v_permlane32_swap_b32_e32 v57, v61
	v_permlane32_swap_b32_e32 v58, v62
	v_permlane32_swap_b32_e32 v59, v63
	v_permlane32_swap_b32_e32 v16, v20
	v_permlane32_swap_b32_e32 v17, v21
	v_permlane32_swap_b32_e32 v18, v22
	v_permlane32_swap_b32_e32 v19, v23
	v_permlane32_swap_b32_e32 v24, v28
	v_permlane32_swap_b32_e32 v25, v29
	v_permlane32_swap_b32_e32 v26, v30
	v_permlane32_swap_b32_e32 v27, v31
	v_permlane32_swap_b32_e32 v96, v100
	v_permlane32_swap_b32_e32 v97, v101
	v_permlane32_swap_b32_e32 v98, v102
	v_permlane32_swap_b32_e32 v99, v103
	v_permlane32_swap_b32_e32 v104, v108
	v_permlane32_swap_b32_e32 v105, v109
	v_permlane32_swap_b32_e32 v106, v110
	v_permlane32_swap_b32_e32 v107, v111
	v_permlane32_swap_b32_e32 v64, v68
	v_permlane32_swap_b32_e32 v65, v69
	v_permlane32_swap_b32_e32 v66, v70
	v_permlane32_swap_b32_e32 v67, v71
	v_permlane32_swap_b32_e32 v72, v76
	v_permlane32_swap_b32_e32 v73, v77
	v_permlane32_swap_b32_e32 v74, v78
	v_permlane32_swap_b32_e32 v75, v79
	v_permlane32_swap_b32_e32 v32, v36
	v_permlane32_swap_b32_e32 v33, v37
	v_permlane32_swap_b32_e32 v34, v38
	v_permlane32_swap_b32_e32 v35, v39
	v_permlane32_swap_b32_e32 v40, v44
	v_permlane32_swap_b32_e32 v41, v45
	v_permlane32_swap_b32_e32 v42, v46
	v_permlane32_swap_b32_e32 v43, v47
	v_permlane32_swap_b32_e32 v0, v4
	v_permlane32_swap_b32_e32 v1, v5
	v_permlane32_swap_b32_e32 v2, v6
	v_permlane32_swap_b32_e32 v3, v7
	v_permlane32_swap_b32_e32 v8, v12
	v_permlane32_swap_b32_e32 v9, v13
	v_permlane32_swap_b32_e32 v10, v14
	v_permlane32_swap_b32_e32 v11, v15
	s_and_saveexec_b64 s[6:7], vcc
	s_cbranch_execz .LBB0_621
	s_mov_b64 s[34:35], exec
	v_mbcnt_lo_u32_b32 v144, s34, 0
	v_mbcnt_hi_u32_b32 v144, s35, v144
	v_cmp_eq_u32_e64 s[38:39], 0, v144
	s_and_saveexec_b64 s[0:1], s[38:39]
	s_cbranch_execz .LBB0_620
	s_bcnt1_i32_b64 s34, s[34:35]
	v_mov_b32_e32 v145, s34
	global_atomic_add v145, v161, v145, s[30:31] offset:256 sc0

; __device__ __forceinline__ unsigned xb_xcc_id() { return (unsigned)__builtin_amdgcn_s_getreg((3 << 11) | 20) & 0xFu; }
; __device__ __forceinline__ void h_tile(WideCtx& c, const u16* __restrict__ A, int lda, int M, int m0, const u16* __restrict__ W, int ldw, int n0) {
; #pragma unroll
;   for (int i = 0; i < 2; ++i) {
;     const int q = c.tid + 256 * i, row = q >> 2, ch = (q & 3) ^ ((row >> 2) & 3);
;     c.wp[i] = W + (size_t)(n0 + row) * ldw + ch * 8;
;   }
; #pragma unroll
;   for (int i = 0; i < 4; ++i) {
;     const int q = c.tid + 256 * i, row = q >> 2, ch = (q & 3) ^ ((row >> 2) & 3);
;     int ar = m0 + row; ar = ar < M ? ar : M - 1;
;     c.ap[i] = A + (size_t)ar * lda + ch * 8;
;   }
; }
; __device__ __forceinline__ void h_stage(const WideCtx& c, int kt) {
;   const unsigned sb = c.lds0 + (kt & 1) * 24576;
; #pragma unroll
;   for (int i = 0; i < 2; ++i) glds16(c.wp[i] + kt * 32, sb + i * 4096);
; #pragma unroll
;   for (int i = 0; i < 4; ++i) glds16(c.ap[i] + kt * 32, sb + 8192 + i * 4096);
; }
; template <class F>
; __device__ __forceinline__ void gemm_phase_w(const u16* A, int lda, int M, const u16* W, int K, int N, char* lds, int* ctr, F&& epi) {
;   const int nN = N >> 7, nM = (M + 255) >> 8, nt = nN * nM, nk = K >> 5;
;   const int xcd = (int)xb_xcc_id() & 7;
;   const int tq = nt >> 3, trm = nt & 7;
;   const int tstart = xcd < trm ? xcd * (tq + 1) : trm * (tq + 1) + (xcd - trm) * tq;
;   const int tcnt = tq + (xcd < trm ? 1 : 0);
;   auto decode = [&](int off, int& tm, int& tn) {
;     const int id = tstart + off, nig = 4 * nN, grp = id / nig, fm = grp * 4;
;     const int gsz = (nM - fm) < 4 ? (nM - fm) : 4, idl = id - grp * nig;
;     tm = fm + idl % gsz; tn = idl / gsz;
;   };
;   WideCtx c;
;   h_init(c, lds);
;   const int wave = c.tid >> 6;
;   volatile int* bw = (volatile int*)(lds + 65536);
;   int* myctr = ctr + xcd;
;   int par = 0;
;   if (c.tid == 0) bw[2] = atomicAdd(myctr, 1);
;   asm volatile("s_waitcnt vmcnt(0) lgkmcnt(0)" ::: "memory");
;   __builtin_amdgcn_s_barrier();
;   int off = bw[2];
;   int tm = 0, tn = 0;
;   if (off < tcnt) { decode(off, tm, tn); h_tile(c, A, lda, M, tm * 256, W, K, tn * 128); h_stage(c, 0); }
.LBB0_652:
	s_or_b64 exec, exec, s[6:7]
	s_mov_b64 s[0:1], src_shared_base
	s_waitcnt vmcnt(0)
	v_mov_b32_e32 v163, s1
	s_waitcnt vmcnt(0) lgkmcnt(0)
	s_barrier
	flat_load_dword v1, v[162:163] sc0 sc1
	s_waitcnt vmcnt(0)
	s_add_i32 s0, s62, 0xff
	s_lshr_b32 s10, s0, 8
	s_waitcnt lgkmcnt(0)
	v_cmp_gt_i32_e64 s[38:39], s10, v1
	s_and_saveexec_b64 s[44:45], s[38:39]
	s_cbranch_execz .LBB0_679
	s_mul_i32 s11, s11, s10
	v_and_b32_e32 v2, 31, v0
	v_lshrrev_b32_e32 v6, 1, v0
	s_mov_b32 s0, 0x3ffffc0
	v_and_or_b32 v2, v6, s0, v2
	v_add_u32_e32 v1, s11, v1
	v_lshlrev_b32_e32 v157, 6, v2
	v_ashrrev_i32_e32 v2, 31, v1
	v_lshrrev_b32_e32 v2, 27, v2
	v_lshlrev_b32_e32 v6, 6, v0
	v_add_u32_e32 v2, v1, v2
	v_and_b32_e32 v156, 0x17c0, v6
	v_ashrrev_i32_e32 v6, 5, v2
	v_lshlrev_b32_e32 v6, 2, v6
	v_sub_u32_e32 v7, s10, v6
	v_min_i32_e32 v7, 4, v7
	v_sub_u32_e32 v8, 0, v7
	v_max_i32_e32 v8, v7, v8
	v_cvt_f32_u32_e32 v9, v8
	v_and_b32_e32 v2, 0xffffffe0, v2
	v_sub_u32_e32 v1, v1, v2
	v_sub_u32_e32 v11, 0, v8
	v_rcp_iflag_f32_e32 v2, v9
	v_sub_u32_e32 v10, 0, v1
	v_max_i32_e32 v10, v1, v10
	v_xor_b32_e32 v9, v1, v7
	v_mul_f32_e32 v2, 0x4f7ffffe, v2
	v_cvt_u32_f32_e32 v2, v2
	v_ashrrev_i32_e32 v9, 31, v9
	s_lshl_b32 s0, s9, 4
	s_and_b32 s24, s0, 0xfffffc00
	v_mul_lo_u32 v11, v11, v2
	v_mul_hi_u32 v11, v2, v11
	v_add_u32_e32 v2, v2, v11
	v_mul_hi_u32 v2, v10, v2
	v_mul_lo_u32 v11, v2, v8
	v_sub_u32_e32 v10, v10, v11
	v_add_u32_e32 v11, 1, v2
	v_cmp_ge_u32_e64 s[38:39], v10, v8
	s_load_dwordx2 s[0:1], s[64:65], 0x128
	v_ashrrev_i32_e32 v158, 2, v0
	v_cndmask_b32_e64 v2, v2, v11, s[38:39]
	v_sub_u32_e32 v11, v10, v8
	v_cndmask_b32_e64 v10, v10, v11, s[38:39]
	v_add_u32_e32 v11, 1, v2
	v_cmp_ge_u32_e64 s[38:39], v10, v8
	s_add_i32 s33, s62, -1
	s_add_i32 s52, s24, 0x1000
	v_cndmask_b32_e64 v2, v2, v11, s[38:39]
	v_xor_b32_e32 v2, v2, v9
	v_sub_u32_e32 v152, v2, v9
	v_mul_lo_u32 v2, v152, v7
	v_sub_u32_e32 v1, v1, v2
	v_add_u32_e32 v153, v1, v6
	v_lshrrev_b32_e32 v6, 4, v0
	v_and_b32_e32 v250, 1, v6
	v_lshlrev_b32_e32 v250, 1, v250
	v_xor_b32_e32 v6, v6, v250
	v_xor_b32_e32 v6, v6, v0
	v_lshlrev_b32_e32 v6, 4, v6
	v_lshlrev_b32_e32 v2, 7, v152
	v_and_b32_e32 v160, 48, v6
	s_waitcnt lgkmcnt(0)
	v_lshl_add_u64 v[128:129], s[0:1], 0, v[160:161]
	v_add_u32_e32 v6, v2, v158
	v_mad_i64_i32 v[132:133], s[0:1], v6, s56, v[128:129]
	v_add_u32_e32 v6, 0x100, v0
	v_ashrrev_i32_e32 v159, 2, v6
	v_add_u32_e32 v2, v2, v159
	v_mad_i64_i32 v[134:135], s[0:1], v2, s56, v[128:129]
	s_load_dwordx2 s[0:1], s[64:65], 0x1c8
	v_lshlrev_b32_e32 v1, 8, v153
	v_add_u32_e32 v2, v1, v158
	v_min_i32_e32 v2, s33, v2
	s_add_i32 s53, s24, 0x2000
	s_waitcnt lgkmcnt(0)
	v_lshl_add_u64 v[130:131], s[0:1], 0, v[160:161]
	v_mad_i64_i32 v[136:137], s[0:1], v2, s56, v[130:131]
	v_add_u32_e32 v2, v1, v159
	v_min_i32_e32 v2, s33, v2
	v_mad_i64_i32 v[138:139], s[0:1], v2, s56, v[130:131]
	v_add_u32_e32 v2, 0x200, v0
	v_ashrrev_i32_e32 v160, 2, v2
	v_add_u32_e32 v2, v1, v160
	v_min_i32_e32 v2, s33, v2
	s_mov_b32 s0, m0
	s_mov_b32 m0, s24
	s_nop 0
	global_load_lds_dwordx4 v[132:133], off
	s_mov_b32 m0, s0
	s_add_i32 s54, s24, 0x3000
	v_mad_i64_i32 v[140:141], s[0:1], v2, s56, v[130:131]
	v_add_u32_e32 v2, 0x300, v0
	s_mov_b32 s0, m0
	s_mov_b32 m0, s52
	s_nop 0
	global_load_lds_dwordx4 v[134:135], off
	s_mov_b32 m0, s0
	v_ashrrev_i32_e32 v163, 2, v2
	s_mov_b32 s0, m0
	s_mov_b32 m0, s53
	s_nop 0
	global_load_lds_dwordx4 v[136:137], off
	s_mov_b32 m0, s0
	v_add_u32_e32 v1, v1, v163
	s_mov_b32 s0, m0
	s_mov_b32 m0, s54
	s_nop 0
	global_load_lds_dwordx4 v[138:139], off
	s_mov_b32 m0, s0
	v_min_i32_e32 v1, s33, v1
	s_add_i32 s55, s24, 0x4000
	s_mov_b32 s0, m0
	s_mov_b32 m0, s55
	s_nop 0
	global_load_lds_dwordx4 v[140:141], off
	s_mov_b32 m0, s0
	s_add_i32 s57, s24, 0x5000
	v_mad_i64_i32 v[142:143], s[0:1], v1, s56, v[130:131]
	s_mov_b32 s0, m0
	s_mov_b32 m0, s57
	s_nop 0
	global_load_lds_dwordx4 v[142:143], off
	s_mov_b32 m0, s0
	s_add_i32 m0, s24, 0x5fc0
	s_nop 0
	global_load_lds_dwordx4 v[132:133], off offset:64
	s_add_i32 m0, s52, 0x5fc0
	s_nop 0
	global_load_lds_dwordx4 v[134:135], off offset:64
	s_add_i32 m0, s53, 0x5fc0
	s_nop 0
	global_load_lds_dwordx4 v[136:137], off offset:64
	s_add_i32 m0, s54, 0x5fc0
	s_nop 0
	global_load_lds_dwordx4 v[138:139], off offset:64
	s_add_i32 m0, s55, 0x5fc0
	s_nop 0
	global_load_lds_dwordx4 v[140:141], off offset:64
	s_add_i32 m0, s57, 0x5fc0
	s_nop 0
	global_load_lds_dwordx4 v[142:143], off offset:64
	s_load_dwordx2 s[46:47], s[64:65], 0x1c0
	s_load_dwordx2 s[48:49], s[64:65], 0x228
	v_bfe_u32 v3, v0, 5, 1
	v_lshrrev_b32_e32 v4, 2, v0
	v_bfe_u32 v5, v0, 2, 2
	v_bitop3_b32 v1, v4, v3, 3 bitop3:0x6c
	v_lshlrev_b32_e32 v164, 4, v1
	v_bitop3_b32 v1, v3, v5, 2 bitop3:0x36
	v_and_b32_e32 v166, 64, v0
	v_ashrrev_i32_e32 v0, 1, v0
	s_mov_b32 s25, 0
	v_lshlrev_b32_e32 v165, 4, v1
	v_and_b32_e32 v167, 0xffffffc0, v0
	s_mov_b64 s[50:51], 0
	s_branch .LBB0_655

; __device__ __forceinline__ void h_main(f32x16 (&acc0)[2][2], f32x16 (&acc1)[2][2], const WideCtx& c, int nk, char* lds) {
;   const int h = c.h;
;   for (int kt = 0; kt < nk; ++kt) {
;     asm volatile("s_waitcnt vmcnt(0)" ::: "memory");
;     __builtin_amdgcn_s_barrier();
;     if (kt + 1 < nk) h_stage(c, kt + 1);
;     const char* st = lds + (kt & 1) * 24576;
; #pragma unroll
;     for (int ks = 0; ks < 2; ++ks) {
;       bf16x8 wf[2], a0[2], a1[2];
; #pragma unroll
;       for (int b = 0; b < 2; ++b) {
;         wf[b] = *(const bf16x8*)(st + c.wro[b] + (((ks * 2 + h) ^ c.wsw[b]) << 4));
;         a0[b] = *(const bf16x8*)(st + c.aro[0][b] + (((ks * 2 + h) ^ c.asw[0][b]) << 4));
;         a1[b] = *(const bf16x8*)(st + c.aro[1][b] + (((ks * 2 + h) ^ c.asw[1][b]) << 4));
;       }
; #pragma unroll
;       for (int nb = 0; nb < 2; ++nb)
; #pragma unroll
;         for (int tb = 0; tb < 2; ++tb) {
;           acc0[nb][tb] = __builtin_amdgcn_mfma_f32_32x32x16_bf16(wf[nb], a0[tb], acc0[nb][tb], 0, 0, 0);
;           acc1[nb][tb] = __builtin_amdgcn_mfma_f32_32x32x16_bf16(wf[nb], a1[tb], acc1[nb][tb], 0, 0, 0);
;         }
;     }
;   }
.LBB0_656:
	s_waitcnt vmcnt(6)
	s_barrier
	v_add_u32_e32 v194, s6, v248
	v_add_u32_e32 v195, s6, v249
	ds_read_b128 v[170:173], v194
	ds_read_b128 v[174:177], v195 offset:8192
	ds_read_b128 v[186:189], v195 offset:9216
	ds_read_b128 v[178:181], v195 offset:10240
	ds_read_b128 v[190:193], v195 offset:11264
	ds_read_b128 v[230:233], v195 offset:16384
	ds_read_b128 v[234:237], v195 offset:17408
	ds_read_b128 v[238:241], v195 offset:18432
	ds_read_b128 v[242:245], v195 offset:19456
	ds_read_b128 v[182:185], v194 offset:1024
	ds_read_b128 v[222:225], v194 offset:2048
	ds_read_b128 v[226:229], v194 offset:3072
	s_add_i32 s7, s6, 0xffffa000
	s_cmp_eq_u32 s6, 0
	s_cselect_b32 s7, 0xc000, s7
	s_add_i32 m0, s7, s24
	s_add_i32 s7, s6, 0x6000
	global_load_lds_dwordx4 v154, s[0:1]
	s_add_i32 m0, m0, 0x1000
	s_cmp_eq_u32 s6, 0xc000
	global_load_lds_dwordx4 v152, s[0:1]
	s_cselect_b32 s6, 0, s7
	s_add_i32 m0, m0, 0x1000
	s_waitcnt lgkmcnt(10)
	v_mfma_f32_16x16x32_bf16 v[112:115], v[170:173], v[174:177], v[112:115]
	global_load_lds_dwordx4 v150, s[0:1]
	s_add_i32 m0, m0, 0x1000
	s_waitcnt lgkmcnt(9)
	v_mfma_f32_16x16x32_bf16 v[116:119], v[170:173], v[186:189], v[116:119]
	global_load_lds_dwordx4 v148, s[0:1]
	s_add_i32 m0, m0, 0x1000
	s_waitcnt lgkmcnt(8)
	v_mfma_f32_16x16x32_bf16 v[80:83], v[170:173], v[178:181], v[80:83]
	global_load_lds_dwordx4 v146, s[0:1]
	s_add_i32 m0, m0, 0x1000
	s_waitcnt lgkmcnt(7)
	v_mfma_f32_16x16x32_bf16 v[84:87], v[170:173], v[190:193], v[84:87]
	global_load_lds_dwordx4 v144, s[0:1]
	s_add_u32 s0, s0, 64
	s_addc_u32 s1, s1, 0
	s_waitcnt lgkmcnt(6)
	v_mfma_f32_16x16x32_bf16 v[48:51], v[170:173], v[230:233], v[48:51]
	s_waitcnt lgkmcnt(5)
	v_mfma_f32_16x16x32_bf16 v[52:55], v[170:173], v[234:237], v[52:55]
	s_waitcnt lgkmcnt(4)
	v_mfma_f32_16x16x32_bf16 v[16:19], v[170:173], v[238:241], v[16:19]
	s_waitcnt lgkmcnt(3)
	v_mfma_f32_16x16x32_bf16 v[20:23], v[170:173], v[242:245], v[20:23]
	s_waitcnt lgkmcnt(2)
	v_mfma_f32_16x16x32_bf16 v[120:123], v[182:185], v[174:177], v[120:123]
	v_mfma_f32_16x16x32_bf16 v[124:127], v[182:185], v[186:189], v[124:127]
	v_mfma_f32_16x16x32_bf16 v[88:91], v[182:185], v[178:181], v[88:91]
	v_mfma_f32_16x16x32_bf16 v[92:95], v[182:185], v[190:193], v[92:95]
	v_mfma_f32_16x16x32_bf16 v[56:59], v[182:185], v[230:233], v[56:59]
	v_mfma_f32_16x16x32_bf16 v[60:63], v[182:185], v[234:237], v[60:63]
	v_mfma_f32_16x16x32_bf16 v[24:27], v[182:185], v[238:241], v[24:27]
	v_mfma_f32_16x16x32_bf16 v[28:31], v[182:185], v[242:245], v[28:31]
	s_waitcnt lgkmcnt(1)
	v_mfma_f32_16x16x32_bf16 v[96:99], v[222:225], v[174:177], v[96:99]
	v_mfma_f32_16x16x32_bf16 v[100:103], v[222:225], v[186:189], v[100:103]
	v_mfma_f32_16x16x32_bf16 v[64:67], v[222:225], v[178:181], v[64:67]
	v_mfma_f32_16x16x32_bf16 v[68:71], v[222:225], v[190:193], v[68:71]
	v_mfma_f32_16x16x32_bf16 v[32:35], v[222:225], v[230:233], v[32:35]
	v_mfma_f32_16x16x32_bf16 v[36:39], v[222:225], v[234:237], v[36:39]
	v_mfma_f32_16x16x32_bf16 v[0:3], v[222:225], v[238:241], v[0:3]
	v_mfma_f32_16x16x32_bf16 v[4:7], v[222:225], v[242:245], v[4:7]
	s_waitcnt lgkmcnt(0)
	v_mfma_f32_16x16x32_bf16 v[104:107], v[226:229], v[174:177], v[104:107]
	v_mfma_f32_16x16x32_bf16 v[108:111], v[226:229], v[186:189], v[108:111]
	v_mfma_f32_16x16x32_bf16 v[72:75], v[226:229], v[178:181], v[72:75]
	v_mfma_f32_16x16x32_bf16 v[76:79], v[226:229], v[190:193], v[76:79]
	v_mfma_f32_16x16x32_bf16 v[40:43], v[226:229], v[230:233], v[40:43]
	v_mfma_f32_16x16x32_bf16 v[44:47], v[226:229], v[234:237], v[44:47]
	v_mfma_f32_16x16x32_bf16 v[8:11], v[226:229], v[238:241], v[8:11]
	v_mfma_f32_16x16x32_bf16 v[12:15], v[226:229], v[242:245], v[12:15]
	s_add_i32 s9, s9, 1
	s_cmp_eq_u32 s9, 88
	s_cbranch_scc0 .LBB0_656
	s_waitcnt vmcnt(6)
	s_barrier
	v_add_u32_e32 v194, s6, v248
	v_add_u32_e32 v195, s6, v249
	ds_read_b128 v[170:173], v194
	ds_read_b128 v[174:177], v195 offset:8192
	ds_read_b128 v[186:189], v195 offset:9216
	ds_read_b128 v[178:181], v195 offset:10240
	ds_read_b128 v[190:193], v195 offset:11264
	ds_read_b128 v[230:233], v195 offset:16384
	ds_read_b128 v[234:237], v195 offset:17408
	ds_read_b128 v[238:241], v195 offset:18432
	ds_read_b128 v[242:245], v195 offset:19456
	ds_read_b128 v[182:185], v194 offset:1024
	ds_read_b128 v[222:225], v194 offset:2048
	ds_read_b128 v[226:229], v194 offset:3072
	s_add_i32 s7, s6, 0x6000
	s_cmp_eq_u32 s6, 0xc000
	s_cselect_b32 s6, 0, s7
	s_waitcnt lgkmcnt(10)
	v_mfma_f32_16x16x32_bf16 v[112:115], v[170:173], v[174:177], v[112:115]
	s_waitcnt lgkmcnt(9)
	v_mfma_f32_16x16x32_bf16 v[116:119], v[170:173], v[186:189], v[116:119]
	s_waitcnt lgkmcnt(8)
	v_mfma_f32_16x16x32_bf16 v[80:83], v[170:173], v[178:181], v[80:83]
	s_waitcnt lgkmcnt(7)
	v_mfma_f32_16x16x32_bf16 v[84:87], v[170:173], v[190:193], v[84:87]
	s_waitcnt lgkmcnt(6)
	v_mfma_f32_16x16x32_bf16 v[48:51], v[170:173], v[230:233], v[48:51]
	s_waitcnt lgkmcnt(5)
	v_mfma_f32_16x16x32_bf16 v[52:55], v[170:173], v[234:237], v[52:55]
	s_waitcnt lgkmcnt(4)
	v_mfma_f32_16x16x32_bf16 v[16:19], v[170:173], v[238:241], v[16:19]
	s_waitcnt lgkmcnt(3)
	v_mfma_f32_16x16x32_bf16 v[20:23], v[170:173], v[242:245], v[20:23]
	s_waitcnt lgkmcnt(2)
	v_mfma_f32_16x16x32_bf16 v[120:123], v[182:185], v[174:177], v[120:123]
	v_mfma_f32_16x16x32_bf16 v[124:127], v[182:185], v[186:189], v[124:127]
	v_mfma_f32_16x16x32_bf16 v[88:91], v[182:185], v[178:181], v[88:91]
	v_mfma_f32_16x16x32_bf16 v[92:95], v[182:185], v[190:193], v[92:95]
	v_mfma_f32_16x16x32_bf16 v[56:59], v[182:185], v[230:233], v[56:59]
	v_mfma_f32_16x16x32_bf16 v[60:63], v[182:185], v[234:237], v[60:63]
	v_mfma_f32_16x16x32_bf16 v[24:27], v[182:185], v[238:241], v[24:27]
	v_mfma_f32_16x16x32_bf16 v[28:31], v[182:185], v[242:245], v[28:31]
	s_waitcnt lgkmcnt(1)
	v_mfma_f32_16x16x32_bf16 v[96:99], v[222:225], v[174:177], v[96:99]
	v_mfma_f32_16x16x32_bf16 v[100:103], v[222:225], v[186:189], v[100:103]
	v_mfma_f32_16x16x32_bf16 v[64:67], v[222:225], v[178:181], v[64:67]
	v_mfma_f32_16x16x32_bf16 v[68:71], v[222:225], v[190:193], v[68:71]
	v_mfma_f32_16x16x32_bf16 v[32:35], v[222:225], v[230:233], v[32:35]
	v_mfma_f32_16x16x32_bf16 v[36:39], v[222:225], v[234:237], v[36:39]
	v_mfma_f32_16x16x32_bf16 v[0:3], v[222:225], v[238:241], v[0:3]
	v_mfma_f32_16x16x32_bf16 v[4:7], v[222:225], v[242:245], v[4:7]
	s_waitcnt lgkmcnt(0)
	v_mfma_f32_16x16x32_bf16 v[104:107], v[226:229], v[174:177], v[104:107]
	v_mfma_f32_16x16x32_bf16 v[108:111], v[226:229], v[186:189], v[108:111]
	v_mfma_f32_16x16x32_bf16 v[72:75], v[226:229], v[178:181], v[72:75]
	v_mfma_f32_16x16x32_bf16 v[76:79], v[226:229], v[190:193], v[76:79]
	v_mfma_f32_16x16x32_bf16 v[40:43], v[226:229], v[230:233], v[40:43]
	v_mfma_f32_16x16x32_bf16 v[44:47], v[226:229], v[234:237], v[44:47]
	v_mfma_f32_16x16x32_bf16 v[8:11], v[226:229], v[238:241], v[8:11]
	v_mfma_f32_16x16x32_bf16 v[12:15], v[226:229], v[242:245], v[12:15]
	s_waitcnt vmcnt(0)
	s_barrier
; __device__ __forceinline__ void h_main(f32x16 (&acc0)[2][2], f32x16 (&acc1)[2][2], const WideCtx& c, int nk, char* lds) {
;   const int h = c.h;
;   for (int kt = 0; kt < nk; ++kt) {
;     asm volatile("s_waitcnt vmcnt(0)" ::: "memory");
;     __builtin_amdgcn_s_barrier();
;     if (kt + 1 < nk) h_stage(c, kt + 1);
;     const char* st = lds + (kt & 1) * 24576;
; #pragma unroll
;     for (int ks = 0; ks < 2; ++ks) {
;       bf16x8 wf[2], a0[2], a1[2];
; #pragma unroll
;       for (int b = 0; b < 2; ++b) {
;         wf[b] = *(const bf16x8*)(st + c.wro[b] + (((ks * 2 + h) ^ c.wsw[b]) << 4));
;         a0[b] = *(const bf16x8*)(st + c.aro[0][b] + (((ks * 2 + h) ^ c.asw[0][b]) << 4));
;         a1[b] = *(const bf16x8*)(st + c.aro[1][b] + (((ks * 2 + h) ^ c.asw[1][b]) << 4));
;       }
; #pragma unroll
;       for (int nb = 0; nb < 2; ++nb)
; #pragma unroll
;         for (int tb = 0; tb < 2; ++tb) {
;           acc0[nb][tb] = __builtin_amdgcn_mfma_f32_32x32x16_bf16(wf[nb], a0[tb], acc0[nb][tb], 0, 0, 0);
;           acc1[nb][tb] = __builtin_amdgcn_mfma_f32_32x32x16_bf16(wf[nb], a1[tb], acc1[nb][tb], 0, 0, 0);
;         }
	v_add_u32_e32 v194, s6, v248
	v_add_u32_e32 v195, s6, v249
	ds_read_b128 v[170:173], v194
	ds_read_b128 v[174:177], v195 offset:8192
	ds_read_b128 v[186:189], v195 offset:9216
	ds_read_b128 v[178:181], v195 offset:10240
	ds_read_b128 v[190:193], v195 offset:11264
	ds_read_b128 v[230:233], v195 offset:16384
	ds_read_b128 v[234:237], v195 offset:17408
	ds_read_b128 v[238:241], v195 offset:18432
	ds_read_b128 v[242:245], v195 offset:19456
	ds_read_b128 v[182:185], v194 offset:1024
	ds_read_b128 v[222:225], v194 offset:2048
	ds_read_b128 v[226:229], v194 offset:3072
	s_add_i32 s7, s6, 0x6000
	s_cmp_eq_u32 s6, 0xc000
	s_cselect_b32 s6, 0, s7
	s_waitcnt lgkmcnt(10)
	v_mfma_f32_16x16x32_bf16 v[112:115], v[170:173], v[174:177], v[112:115]
	s_waitcnt lgkmcnt(9)
	v_mfma_f32_16x16x32_bf16 v[116:119], v[170:173], v[186:189], v[116:119]
	s_waitcnt lgkmcnt(8)
	v_mfma_f32_16x16x32_bf16 v[80:83], v[170:173], v[178:181], v[80:83]
	s_waitcnt lgkmcnt(7)
	v_mfma_f32_16x16x32_bf16 v[84:87], v[170:173], v[190:193], v[84:87]
	s_waitcnt lgkmcnt(6)
	v_mfma_f32_16x16x32_bf16 v[48:51], v[170:173], v[230:233], v[48:51]
	s_waitcnt lgkmcnt(5)
	v_mfma_f32_16x16x32_bf16 v[52:55], v[170:173], v[234:237], v[52:55]
	s_waitcnt lgkmcnt(4)
	v_mfma_f32_16x16x32_bf16 v[16:19], v[170:173], v[238:241], v[16:19]
	s_waitcnt lgkmcnt(3)
	v_mfma_f32_16x16x32_bf16 v[20:23], v[170:173], v[242:245], v[20:23]
	s_waitcnt lgkmcnt(2)
	v_mfma_f32_16x16x32_bf16 v[120:123], v[182:185], v[174:177], v[120:123]
	v_mfma_f32_16x16x32_bf16 v[124:127], v[182:185], v[186:189], v[124:127]
	v_mfma_f32_16x16x32_bf16 v[88:91], v[182:185], v[178:181], v[88:91]
	v_mfma_f32_16x16x32_bf16 v[92:95], v[182:185], v[190:193], v[92:95]
	v_mfma_f32_16x16x32_bf16 v[56:59], v[182:185], v[230:233], v[56:59]
	v_mfma_f32_16x16x32_bf16 v[60:63], v[182:185], v[234:237], v[60:63]
	v_mfma_f32_16x16x32_bf16 v[24:27], v[182:185], v[238:241], v[24:27]
	v_mfma_f32_16x16x32_bf16 v[28:31], v[182:185], v[242:245], v[28:31]
	s_waitcnt lgkmcnt(1)
	v_mfma_f32_16x16x32_bf16 v[96:99], v[222:225], v[174:177], v[96:99]
	v_mfma_f32_16x16x32_bf16 v[100:103], v[222:225], v[186:189], v[100:103]
	v_mfma_f32_16x16x32_bf16 v[64:67], v[222:225], v[178:181], v[64:67]
	v_mfma_f32_16x16x32_bf16 v[68:71], v[222:225], v[190:193], v[68:71]
	v_mfma_f32_16x16x32_bf16 v[32:35], v[222:225], v[230:233], v[32:35]
	v_mfma_f32_16x16x32_bf16 v[36:39], v[222:225], v[234:237], v[36:39]
	v_mfma_f32_16x16x32_bf16 v[0:3], v[222:225], v[238:241], v[0:3]
	v_mfma_f32_16x16x32_bf16 v[4:7], v[222:225], v[242:245], v[4:7]
	s_waitcnt lgkmcnt(0)
; __device__ __forceinline__ void h_main(f32x16 (&acc0)[2][2], f32x16 (&acc1)[2][2], const WideCtx& c, int nk, char* lds) {
;   const int h = c.h;
;   for (int kt = 0; kt < nk; ++kt) {
;     asm volatile("s_waitcnt vmcnt(0)" ::: "memory");
;     __builtin_amdgcn_s_barrier();
;     if (kt + 1 < nk) h_stage(c, kt + 1);
;     const char* st = lds + (kt & 1) * 24576;
; #pragma unroll
;     for (int ks = 0; ks < 2; ++ks) {
;       bf16x8 wf[2], a0[2], a1[2];
; #pragma unroll
;       for (int b = 0; b < 2; ++b) {
;         wf[b] = *(const bf16x8*)(st + c.wro[b] + (((ks * 2 + h) ^ c.wsw[b]) << 4));
;         a0[b] = *(const bf16x8*)(st + c.aro[0][b] + (((ks * 2 + h) ^ c.asw[0][b]) << 4));
;         a1[b] = *(const bf16x8*)(st + c.aro[1][b] + (((ks * 2 + h) ^ c.asw[1][b]) << 4));
;       }
; #pragma unroll
;       for (int nb = 0; nb < 2; ++nb)
; #pragma unroll
;         for (int tb = 0; tb < 2; ++tb) {
;           acc0[nb][tb] = __builtin_amdgcn_mfma_f32_32x32x16_bf16(wf[nb], a0[tb], acc0[nb][tb], 0, 0, 0);
;           acc1[nb][tb] = __builtin_amdgcn_mfma_f32_32x32x16_bf16(wf[nb], a1[tb], acc1[nb][tb], 0, 0, 0);
;         }
;     }
;   }
; template <class F>
; __device__ __forceinline__ void gemm_phase_w(const u16* A, int lda, int M, const u16* W, int K, int N, char* lds, int* ctr, F&& epi) {
;     ...
;     const int ctm = tm, ctn = tn;
;     par ^= 1;
;     if (c.tid == 0) bw[2 + par] = atomicAdd(myctr, 1);
	v_mfma_f32_16x16x32_bf16 v[104:107], v[226:229], v[174:177], v[104:107]
	v_mfma_f32_16x16x32_bf16 v[108:111], v[226:229], v[186:189], v[108:111]
	v_mfma_f32_16x16x32_bf16 v[72:75], v[226:229], v[178:181], v[72:75]
	v_mfma_f32_16x16x32_bf16 v[76:79], v[226:229], v[190:193], v[76:79]
	v_mfma_f32_16x16x32_bf16 v[40:43], v[226:229], v[230:233], v[40:43]
	v_mfma_f32_16x16x32_bf16 v[44:47], v[226:229], v[234:237], v[44:47]
	v_mfma_f32_16x16x32_bf16 v[8:11], v[226:229], v[238:241], v[8:11]
	v_mfma_f32_16x16x32_bf16 v[12:15], v[226:229], v[242:245], v[12:15]
	s_xor_b32 s25, s25, 1
	s_nop 7
	s_nop 7
	v_permlane16_swap_b32_e32 v112, v116
	v_permlane16_swap_b32_e32 v113, v117
	v_permlane16_swap_b32_e32 v114, v118
	v_permlane16_swap_b32_e32 v115, v119
	v_permlane16_swap_b32_e32 v120, v124
	v_permlane16_swap_b32_e32 v121, v125
	v_permlane16_swap_b32_e32 v122, v126
	v_permlane16_swap_b32_e32 v123, v127
	v_permlane16_swap_b32_e32 v80, v84
	v_permlane16_swap_b32_e32 v81, v85
	v_permlane16_swap_b32_e32 v82, v86
	v_permlane16_swap_b32_e32 v83, v87
	v_permlane16_swap_b32_e32 v88, v92
	v_permlane16_swap_b32_e32 v89, v93
	v_permlane16_swap_b32_e32 v90, v94
	v_permlane16_swap_b32_e32 v91, v95
	v_permlane16_swap_b32_e32 v48, v52
	v_permlane16_swap_b32_e32 v49, v53
	v_permlane16_swap_b32_e32 v50, v54
	v_permlane16_swap_b32_e32 v51, v55
	v_permlane16_swap_b32_e32 v56, v60
	v_permlane16_swap_b32_e32 v57, v61
	v_permlane16_swap_b32_e32 v58, v62
	v_permlane16_swap_b32_e32 v59, v63
	v_permlane16_swap_b32_e32 v16, v20
	v_permlane16_swap_b32_e32 v17, v21
	v_permlane16_swap_b32_e32 v18, v22
	v_permlane16_swap_b32_e32 v19, v23
	v_permlane16_swap_b32_e32 v24, v28
	v_permlane16_swap_b32_e32 v25, v29
	v_permlane16_swap_b32_e32 v26, v30
	v_permlane16_swap_b32_e32 v27, v31
	v_permlane16_swap_b32_e32 v96, v100
	v_permlane16_swap_b32_e32 v97, v101
	v_permlane16_swap_b32_e32 v98, v102
	v_permlane16_swap_b32_e32 v99, v103
	v_permlane16_swap_b32_e32 v104, v108
	v_permlane16_swap_b32_e32 v105, v109
	v_permlane16_swap_b32_e32 v106, v110
	v_permlane16_swap_b32_e32 v107, v111
	v_permlane16_swap_b32_e32 v64, v68
	v_permlane16_swap_b32_e32 v65, v69
	v_permlane16_swap_b32_e32 v66, v70
	v_permlane16_swap_b32_e32 v67, v71
	v_permlane16_swap_b32_e32 v72, v76
	v_permlane16_swap_b32_e32 v73, v77
	v_permlane16_swap_b32_e32 v74, v78
	v_permlane16_swap_b32_e32 v75, v79
	v_permlane16_swap_b32_e32 v32, v36
	v_permlane16_swap_b32_e32 v33, v37
	v_permlane16_swap_b32_e32 v34, v38
	v_permlane16_swap_b32_e32 v35, v39
	v_permlane16_swap_b32_e32 v40, v44
	v_permlane16_swap_b32_e32 v41, v45
	v_permlane16_swap_b32_e32 v42, v46
	v_permlane16_swap_b32_e32 v43, v47
	v_permlane16_swap_b32_e32 v0, v4
	v_permlane16_swap_b32_e32 v1, v5
	v_permlane16_swap_b32_e32 v2, v6
	v_permlane16_swap_b32_e32 v3, v7
	v_permlane16_swap_b32_e32 v8, v12
	v_permlane16_swap_b32_e32 v9, v13
	v_permlane16_swap_b32_e32 v10, v14
	v_permlane16_swap_b32_e32 v11, v15
	v_permlane32_swap_b32_e32 v112, v116
	v_permlane32_swap_b32_e32 v113, v117
	v_permlane32_swap_b32_e32 v114, v118
	v_permlane32_swap_b32_e32 v115, v119
	v_permlane32_swap_b32_e32 v120, v124
	v_permlane32_swap_b32_e32 v121, v125
	v_permlane32_swap_b32_e32 v122, v126
	v_permlane32_swap_b32_e32 v123, v127
	v_permlane32_swap_b32_e32 v80, v84
	v_permlane32_swap_b32_e32 v81, v85
	v_permlane32_swap_b32_e32 v82, v86
	v_permlane32_swap_b32_e32 v83, v87
	v_permlane32_swap_b32_e32 v88, v92
	v_permlane32_swap_b32_e32 v89, v93
	v_permlane32_swap_b32_e32 v90, v94
	v_permlane32_swap_b32_e32 v91, v95
	v_permlane32_swap_b32_e32 v48, v52
	v_permlane32_swap_b32_e32 v49, v53
	v_permlane32_swap_b32_e32 v50, v54
	v_permlane32_swap_b32_e32 v51, v55
	v_permlane32_swap_b32_e32 v56, v60
	v_permlane32_swap_b32_e32 v57, v61
	v_permlane32_swap_b32_e32 v58, v62
	v_permlane32_swap_b32_e32 v59, v63
	v_permlane32_swap_b32_e32 v16, v20
	v_permlane32_swap_b32_e32 v17, v21
	v_permlane32_swap_b32_e32 v18, v22
	v_permlane32_swap_b32_e32 v19, v23
	v_permlane32_swap_b32_e32 v24, v28
	v_permlane32_swap_b32_e32 v25, v29
	v_permlane32_swap_b32_e32 v26, v30
	v_permlane32_swap_b32_e32 v27, v31
	v_permlane32_swap_b32_e32 v96, v100
	v_permlane32_swap_b32_e32 v97, v101
	v_permlane32_swap_b32_e32 v98, v102
	v_permlane32_swap_b32_e32 v99, v103
	v_permlane32_swap_b32_e32 v104, v108
	v_permlane32_swap_b32_e32 v105, v109
	v_permlane32_swap_b32_e32 v106, v110
	v_permlane32_swap_b32_e32 v107, v111
	v_permlane32_swap_b32_e32 v64, v68
	v_permlane32_swap_b32_e32 v65, v69
	v_permlane32_swap_b32_e32 v66, v70
	v_permlane32_swap_b32_e32 v67, v71
	v_permlane32_swap_b32_e32 v72, v76
	v_permlane32_swap_b32_e32 v73, v77
	v_permlane32_swap_b32_e32 v74, v78
	v_permlane32_swap_b32_e32 v75, v79
	v_permlane32_swap_b32_e32 v32, v36
	v_permlane32_swap_b32_e32 v33, v37
	v_permlane32_swap_b32_e32 v34, v38
	v_permlane32_swap_b32_e32 v35, v39
	v_permlane32_swap_b32_e32 v40, v44
	v_permlane32_swap_b32_e32 v41, v45
	v_permlane32_swap_b32_e32 v42, v46
	v_permlane32_swap_b32_e32 v43, v47
	v_permlane32_swap_b32_e32 v0, v4
	v_permlane32_swap_b32_e32 v1, v5
	v_permlane32_swap_b32_e32 v2, v6
	v_permlane32_swap_b32_e32 v3, v7
	v_permlane32_swap_b32_e32 v8, v12
	v_permlane32_swap_b32_e32 v9, v13
	v_permlane32_swap_b32_e32 v10, v14
	v_permlane32_swap_b32_e32 v11, v15
	s_and_saveexec_b64 s[6:7], vcc
	s_cbranch_execz .LBB0_661
	s_mov_b64 s[34:35], exec
	v_mbcnt_lo_u32_b32 v144, s34, 0
	v_mbcnt_hi_u32_b32 v144, s35, v144
	v_cmp_eq_u32_e64 s[38:39], 0, v144
	s_and_saveexec_b64 s[0:1], s[38:39]
	s_cbranch_execz .LBB0_660
	s_bcnt1_i32_b64 s9, s[34:35]
	v_mov_b32_e32 v145, s9
	global_atomic_add v145, v161, v145, s[30:31] offset:256 sc0

; __device__ __forceinline__ unsigned xb_xcc_id() { return (unsigned)__builtin_amdgcn_s_getreg((3 << 11) | 20) & 0xFu; }
; __device__ __forceinline__ void h_tile(WideCtx& c, const u16* __restrict__ A, int lda, int M, int m0, const u16* __restrict__ W, int ldw, int n0) {
; #pragma unroll
;   for (int i = 0; i < 2; ++i) {
;     const int q = c.tid + 256 * i, row = q >> 2, ch = (q & 3) ^ ((row >> 2) & 3);
;     c.wp[i] = W + (size_t)(n0 + row) * ldw + ch * 8;
;   }
; #pragma unroll
;   for (int i = 0; i < 4; ++i) {
;     const int q = c.tid + 256 * i, row = q >> 2, ch = (q & 3) ^ ((row >> 2) & 3);
;     int ar = m0 + row; ar = ar < M ? ar : M - 1;
;     c.ap[i] = A + (size_t)ar * lda + ch * 8;
;   }
; }
; __device__ __forceinline__ void h_stage(const WideCtx& c, int kt) {
;   const unsigned sb = c.lds0 + (kt & 1) * 24576;
; #pragma unroll
;   for (int i = 0; i < 2; ++i) glds16(c.wp[i] + kt * 32, sb + i * 4096);
; #pragma unroll
;   for (int i = 0; i < 4; ++i) glds16(c.ap[i] + kt * 32, sb + 8192 + i * 4096);
; }
; template <class F>
; __device__ __forceinline__ void gemm_phase_w(const u16* A, int lda, int M, const u16* W, int K, int N, char* lds, int* ctr, F&& epi) {
;   const int nN = N >> 7, nM = (M + 255) >> 8, nt = nN * nM, nk = K >> 5;
;   const int xcd = (int)xb_xcc_id() & 7;
;   const int tq = nt >> 3, trm = nt & 7;
;   const int tstart = xcd < trm ? xcd * (tq + 1) : trm * (tq + 1) + (xcd - trm) * tq;
;   const int tcnt = tq + (xcd < trm ? 1 : 0);
;   auto decode = [&](int off, int& tm, int& tn) {
;     const int id = tstart + off, nig = 4 * nN, grp = id / nig, fm = grp * 4;
;     const int gsz = (nM - fm) < 4 ? (nM - fm) : 4, idl = id - grp * nig;
;     tm = fm + idl % gsz; tn = idl / gsz;
;   };
;   WideCtx c;
;   h_init(c, lds);
;   const int wave = c.tid >> 6;
;   volatile int* bw = (volatile int*)(lds + 65536);
;   int* myctr = ctr + xcd;
;   int par = 0;
;   if (c.tid == 0) bw[2] = atomicAdd(myctr, 1);
;   asm volatile("s_waitcnt vmcnt(0) lgkmcnt(0)" ::: "memory");
;   __builtin_amdgcn_s_barrier();
;   int off = bw[2];
;   int tm = 0, tn = 0;
;   if (off < tcnt) { decode(off, tm, tn); h_tile(c, A, lda, M, tm * 256, W, K, tn * 128); h_stage(c, 0); }
.LBB0_689:
	s_or_b64 exec, exec, s[34:35]
	s_mov_b64 s[0:1], src_shared_base
	v_cndmask_b32_e64 v1, 0, 1, s[6:7]
	s_waitcnt vmcnt(0)
	v_mov_b32_e32 v163, s1
	v_add_u32_e32 v156, s24, v1
	s_waitcnt vmcnt(0) lgkmcnt(0)
	s_barrier
	flat_load_dword v1, v[162:163] sc0 sc1
	s_waitcnt vmcnt(0) lgkmcnt(0)
	v_cmp_lt_i32_e64 s[38:39], v1, v156
	s_and_saveexec_b64 s[42:43], s[38:39]
	s_cbranch_execz .LBB0_708
	v_and_b32_e32 v2, 31, v0
	v_lshrrev_b32_e32 v3, 1, v0
	s_mov_b32 s0, 0x3ffffc0
	v_and_or_b32 v2, v3, s0, v2
	v_lshlrev_b32_e32 v158, 6, v2
	v_add_u32_e32 v2, s11, v1
	s_mov_b32 s1, 0x2e8ba2e9
	v_lshlrev_b32_e32 v3, 6, v0
	v_mul_hi_i32 v1, v2, s1
	v_and_b32_e32 v157, 0x17c0, v3
	v_lshrrev_b32_e32 v3, 31, v1
	v_ashrrev_i32_e32 v1, 5, v1
	v_add_u32_e32 v1, v1, v3
	v_lshlrev_b32_e32 v7, 2, v1
	v_sub_u32_e32 v3, s10, v7
	v_min_i32_e32 v8, 4, v3
	v_sub_u32_e32 v3, 0, v8
	v_max_i32_e32 v9, v8, v3
	v_cvt_f32_u32_e32 v10, v9
	s_lshl_b32 s0, s9, 4
	s_and_b32 s33, s0, 0xfffffc00
	s_movk_i32 s0, 0xff50
	v_mad_u64_u32 v[2:3], s[0:1], v1, s0, v[2:3]
	v_rcp_iflag_f32_e32 v1, v10
	v_sub_u32_e32 v11, 0, v9
	v_sub_u32_e32 v10, 0, v2
	v_max_i32_e32 v10, v2, v10
	v_mul_f32_e32 v1, 0x4f7ffffe, v1
	v_cvt_u32_f32_e32 v1, v1
	v_xor_b32_e32 v3, v2, v8
	v_ashrrev_i32_e32 v3, 31, v3
	s_load_dwordx2 s[0:1], s[64:65], 0x120
	v_mul_lo_u32 v11, v11, v1
	v_mul_hi_u32 v11, v1, v11
	v_add_u32_e32 v1, v1, v11
	v_mul_hi_u32 v1, v10, v1
	v_mul_lo_u32 v11, v1, v9
	v_sub_u32_e32 v10, v10, v11
	v_add_u32_e32 v11, 1, v1
	v_cmp_ge_u32_e64 s[38:39], v10, v9
	v_ashrrev_i32_e32 v159, 2, v0
	s_add_i32 s49, s62, -1
	v_cndmask_b32_e64 v1, v1, v11, s[38:39]
	v_sub_u32_e32 v11, v10, v9
	v_cndmask_b32_e64 v10, v10, v11, s[38:39]
	v_add_u32_e32 v11, 1, v1
	v_cmp_ge_u32_e64 s[38:39], v10, v9
	s_add_i32 s50, s33, 0x1000
	s_add_i32 s51, s33, 0x2000
	v_cndmask_b32_e64 v1, v1, v11, s[38:39]
	v_xor_b32_e32 v1, v1, v3
	v_sub_u32_e32 v153, v1, v3
	v_mul_lo_u32 v1, v153, v8
	v_sub_u32_e32 v1, v2, v1
	v_lshrrev_b32_e32 v2, 4, v0
	v_and_b32_e32 v250, 1, v2
	v_lshlrev_b32_e32 v250, 1, v250
	v_xor_b32_e32 v2, v2, v250
	v_xor_b32_e32 v2, v2, v0
	v_add_u32_e32 v154, v1, v7
	v_lshlrev_b32_e32 v7, 7, v153
	v_lshlrev_b32_e32 v2, 4, v2
	v_and_b32_e32 v160, 48, v2
	v_add_u32_e32 v2, v7, v159
	v_ashrrev_i32_e32 v3, 31, v2
	s_waitcnt lgkmcnt(0)
	v_lshl_add_u64 v[128:129], s[0:1], 0, v[160:161]
	v_lshlrev_b64 v[2:3], 11, v[2:3]
	v_lshl_add_u64 v[132:133], v[128:129], 0, v[2:3]
	v_add_u32_e32 v2, 0x100, v0
	v_ashrrev_i32_e32 v163, 2, v2
	v_add_u32_e32 v2, v7, v163
	v_ashrrev_i32_e32 v3, 31, v2
	s_load_dwordx2 s[0:1], s[64:65], 0x1c0
	v_lshlrev_b32_e32 v1, 8, v154
	v_lshlrev_b64 v[2:3], 11, v[2:3]
	v_lshl_add_u64 v[134:135], v[128:129], 0, v[2:3]
	v_add_u32_e32 v2, v1, v159
	v_min_i32_e32 v2, s49, v2
	v_ashrrev_i32_e32 v3, 31, v2
	s_waitcnt lgkmcnt(0)
	v_lshl_add_u64 v[130:131], s[0:1], 0, v[160:161]
	v_lshlrev_b64 v[2:3], 11, v[2:3]
	v_lshl_add_u64 v[136:137], v[130:131], 0, v[2:3]
	v_add_u32_e32 v2, v1, v163
	v_min_i32_e32 v2, s49, v2
	v_ashrrev_i32_e32 v3, 31, v2
	v_lshlrev_b64 v[2:3], 11, v[2:3]
	v_lshl_add_u64 v[138:139], v[130:131], 0, v[2:3]
	v_add_u32_e32 v2, 0x200, v0
	v_ashrrev_i32_e32 v164, 2, v2
	v_add_u32_e32 v2, v1, v164
	v_min_i32_e32 v2, s49, v2
	v_ashrrev_i32_e32 v3, 31, v2
	v_lshlrev_b64 v[2:3], 11, v[2:3]
	v_lshl_add_u64 v[140:141], v[130:131], 0, v[2:3]
	v_add_u32_e32 v2, 0x300, v0
	v_ashrrev_i32_e32 v165, 2, v2
	s_mov_b32 s0, m0
	s_mov_b32 m0, s33
	s_nop 0
	global_load_lds_dwordx4 v[132:133], off
	s_mov_b32 m0, s0
	v_add_u32_e32 v1, v1, v165
	s_mov_b32 s0, m0
	s_mov_b32 m0, s50
	s_nop 0
	global_load_lds_dwordx4 v[134:135], off
	s_mov_b32 m0, s0
	v_min_i32_e32 v2, s49, v1
	s_mov_b32 s0, m0
	s_mov_b32 m0, s51
	s_nop 0
	global_load_lds_dwordx4 v[136:137], off
	s_mov_b32 m0, s0
	v_ashrrev_i32_e32 v3, 31, v2
	s_add_i32 s52, s33, 0x3000
	s_mov_b32 s0, m0
	s_mov_b32 m0, s52
	s_nop 0
	global_load_lds_dwordx4 v[138:139], off
	s_mov_b32 m0, s0
	v_lshlrev_b64 v[2:3], 11, v[2:3]
	s_add_i32 s53, s33, 0x4000
	s_mov_b32 s0, m0
	s_mov_b32 m0, s53
	s_nop 0
	global_load_lds_dwordx4 v[140:141], off
	s_mov_b32 m0, s0
	v_lshl_add_u64 v[142:143], v[130:131], 0, v[2:3]
	s_add_i32 s54, s33, 0x5000
	s_mov_b32 s0, m0
	s_mov_b32 m0, s54
	s_nop 0
	global_load_lds_dwordx4 v[142:143], off
	s_mov_b32 m0, s0
	s_add_i32 m0, s33, 0x5fc0
	s_nop 0
	global_load_lds_dwordx4 v[132:133], off offset:64
	s_add_i32 m0, s50, 0x5fc0
	s_nop 0
	global_load_lds_dwordx4 v[134:135], off offset:64
	s_add_i32 m0, s51, 0x5fc0
	s_nop 0
	global_load_lds_dwordx4 v[136:137], off offset:64
	s_add_i32 m0, s52, 0x5fc0
	s_nop 0
	global_load_lds_dwordx4 v[138:139], off offset:64
	s_add_i32 m0, s53, 0x5fc0
	s_nop 0
	global_load_lds_dwordx4 v[140:141], off offset:64
	s_add_i32 m0, s54, 0x5fc0
	s_nop 0
	global_load_lds_dwordx4 v[142:143], off offset:64
	s_load_dwordx2 s[44:45], s[64:65], 0x220
	v_bfe_u32 v4, v0, 5, 1
	v_lshrrev_b32_e32 v5, 2, v0
	v_bfe_u32 v6, v0, 2, 2
	v_bitop3_b32 v1, v5, v4, 3 bitop3:0x6c
	v_lshlrev_b32_e32 v166, 4, v1
	v_bitop3_b32 v1, v4, v6, 2 bitop3:0x36
	v_and_b32_e32 v168, 64, v0
	v_ashrrev_i32_e32 v0, 1, v0
	s_mov_b32 s48, 0
	v_lshlrev_b32_e32 v167, 4, v1
	v_and_b32_e32 v169, 0xffffffc0, v0
	s_mov_b64 s[46:47], 0
	s_branch .LBB0_692

; __device__ __forceinline__ void h_main(f32x16 (&acc0)[2][2], f32x16 (&acc1)[2][2], const WideCtx& c, int nk, char* lds) {
;   const int h = c.h;
;   for (int kt = 0; kt < nk; ++kt) {
;     asm volatile("s_waitcnt vmcnt(0)" ::: "memory");
;     __builtin_amdgcn_s_barrier();
;     if (kt + 1 < nk) h_stage(c, kt + 1);
;     const char* st = lds + (kt & 1) * 24576;
; #pragma unroll
;     for (int ks = 0; ks < 2; ++ks) {
;       bf16x8 wf[2], a0[2], a1[2];
; #pragma unroll
;       for (int b = 0; b < 2; ++b) {
;         wf[b] = *(const bf16x8*)(st + c.wro[b] + (((ks * 2 + h) ^ c.wsw[b]) << 4));
;         a0[b] = *(const bf16x8*)(st + c.aro[0][b] + (((ks * 2 + h) ^ c.asw[0][b]) << 4));
;         a1[b] = *(const bf16x8*)(st + c.aro[1][b] + (((ks * 2 + h) ^ c.asw[1][b]) << 4));
;       }
; #pragma unroll
;       for (int nb = 0; nb < 2; ++nb)
; #pragma unroll
;         for (int tb = 0; tb < 2; ++tb) {
;           acc0[nb][tb] = __builtin_amdgcn_mfma_f32_32x32x16_bf16(wf[nb], a0[tb], acc0[nb][tb], 0, 0, 0);
;           acc1[nb][tb] = __builtin_amdgcn_mfma_f32_32x32x16_bf16(wf[nb], a1[tb], acc1[nb][tb], 0, 0, 0);
;         }
;     }
;   }
.LBB0_693:
	s_waitcnt vmcnt(6)
	s_barrier
	v_add_u32_e32 v171, s6, v248
	v_add_u32_e32 v196, s6, v249
	ds_read_b128 v[172:175], v171
	ds_read_b128 v[176:179], v196 offset:8192
	ds_read_b128 v[188:191], v196 offset:9216
	ds_read_b128 v[180:183], v196 offset:10240
	ds_read_b128 v[192:195], v196 offset:11264
	ds_read_b128 v[230:233], v196 offset:16384
	ds_read_b128 v[234:237], v196 offset:17408
	ds_read_b128 v[238:241], v196 offset:18432
	ds_read_b128 v[242:245], v196 offset:19456
	ds_read_b128 v[184:187], v171 offset:1024
	ds_read_b128 v[222:225], v171 offset:2048
	ds_read_b128 v[226:229], v171 offset:3072
	s_add_i32 s7, s6, 0xffffa000
	s_cmp_eq_u32 s6, 0
	s_cselect_b32 s7, 0xc000, s7
	s_add_i32 m0, s7, s33
	s_add_i32 s7, s6, 0x6000
	global_load_lds_dwordx4 v154, s[0:1]
	s_add_i32 m0, m0, 0x1000
	s_cmp_eq_u32 s6, 0xc000
	global_load_lds_dwordx4 v152, s[0:1]
	s_cselect_b32 s6, 0, s7
	s_add_i32 m0, m0, 0x1000
	s_waitcnt lgkmcnt(10)
	v_mfma_f32_16x16x32_bf16 v[112:115], v[172:175], v[176:179], v[112:115]
	global_load_lds_dwordx4 v150, s[0:1]
	s_add_i32 m0, m0, 0x1000
	s_waitcnt lgkmcnt(9)
	v_mfma_f32_16x16x32_bf16 v[116:119], v[172:175], v[188:191], v[116:119]
	global_load_lds_dwordx4 v148, s[0:1]
	s_add_i32 m0, m0, 0x1000
	s_waitcnt lgkmcnt(8)
	v_mfma_f32_16x16x32_bf16 v[80:83], v[172:175], v[180:183], v[80:83]
	global_load_lds_dwordx4 v146, s[0:1]
	s_add_i32 m0, m0, 0x1000
	s_waitcnt lgkmcnt(7)
	v_mfma_f32_16x16x32_bf16 v[84:87], v[172:175], v[192:195], v[84:87]
	global_load_lds_dwordx4 v144, s[0:1]
	s_add_u32 s0, s0, 64
	s_addc_u32 s1, s1, 0
	s_waitcnt lgkmcnt(6)
	v_mfma_f32_16x16x32_bf16 v[48:51], v[172:175], v[230:233], v[48:51]
	s_waitcnt lgkmcnt(5)
	v_mfma_f32_16x16x32_bf16 v[52:55], v[172:175], v[234:237], v[52:55]
	s_waitcnt lgkmcnt(4)
	v_mfma_f32_16x16x32_bf16 v[16:19], v[172:175], v[238:241], v[16:19]
	s_waitcnt lgkmcnt(3)
	v_mfma_f32_16x16x32_bf16 v[20:23], v[172:175], v[242:245], v[20:23]
	s_waitcnt lgkmcnt(2)
	v_mfma_f32_16x16x32_bf16 v[120:123], v[184:187], v[176:179], v[120:123]
	v_mfma_f32_16x16x32_bf16 v[124:127], v[184:187], v[188:191], v[124:127]
	v_mfma_f32_16x16x32_bf16 v[88:91], v[184:187], v[180:183], v[88:91]
	v_mfma_f32_16x16x32_bf16 v[92:95], v[184:187], v[192:195], v[92:95]
	v_mfma_f32_16x16x32_bf16 v[56:59], v[184:187], v[230:233], v[56:59]
	v_mfma_f32_16x16x32_bf16 v[60:63], v[184:187], v[234:237], v[60:63]
	v_mfma_f32_16x16x32_bf16 v[24:27], v[184:187], v[238:241], v[24:27]
	v_mfma_f32_16x16x32_bf16 v[28:31], v[184:187], v[242:245], v[28:31]
	s_waitcnt lgkmcnt(1)
	v_mfma_f32_16x16x32_bf16 v[96:99], v[222:225], v[176:179], v[96:99]
	v_mfma_f32_16x16x32_bf16 v[100:103], v[222:225], v[188:191], v[100:103]
	v_mfma_f32_16x16x32_bf16 v[64:67], v[222:225], v[180:183], v[64:67]
	v_mfma_f32_16x16x32_bf16 v[68:71], v[222:225], v[192:195], v[68:71]
	v_mfma_f32_16x16x32_bf16 v[32:35], v[222:225], v[230:233], v[32:35]
	v_mfma_f32_16x16x32_bf16 v[36:39], v[222:225], v[234:237], v[36:39]
	v_mfma_f32_16x16x32_bf16 v[0:3], v[222:225], v[238:241], v[0:3]
	v_mfma_f32_16x16x32_bf16 v[4:7], v[222:225], v[242:245], v[4:7]
	s_waitcnt lgkmcnt(0)
	v_mfma_f32_16x16x32_bf16 v[104:107], v[226:229], v[176:179], v[104:107]
	v_mfma_f32_16x16x32_bf16 v[108:111], v[226:229], v[188:191], v[108:111]
	v_mfma_f32_16x16x32_bf16 v[72:75], v[226:229], v[180:183], v[72:75]
	v_mfma_f32_16x16x32_bf16 v[76:79], v[226:229], v[192:195], v[76:79]
	v_mfma_f32_16x16x32_bf16 v[40:43], v[226:229], v[230:233], v[40:43]
	v_mfma_f32_16x16x32_bf16 v[44:47], v[226:229], v[234:237], v[44:47]
	v_mfma_f32_16x16x32_bf16 v[8:11], v[226:229], v[238:241], v[8:11]
	v_mfma_f32_16x16x32_bf16 v[12:15], v[226:229], v[242:245], v[12:15]
	s_add_i32 s9, s9, 1
	s_cmp_eq_u32 s9, 32
	s_cbranch_scc0 .LBB0_693
	s_waitcnt vmcnt(6)
	s_barrier
	v_add_u32_e32 v171, s6, v248
	v_add_u32_e32 v196, s6, v249
	ds_read_b128 v[172:175], v171
	ds_read_b128 v[176:179], v196 offset:8192
	ds_read_b128 v[188:191], v196 offset:9216
	ds_read_b128 v[180:183], v196 offset:10240
	ds_read_b128 v[192:195], v196 offset:11264
	ds_read_b128 v[230:233], v196 offset:16384
	ds_read_b128 v[234:237], v196 offset:17408
	ds_read_b128 v[238:241], v196 offset:18432
	ds_read_b128 v[242:245], v196 offset:19456
	ds_read_b128 v[184:187], v171 offset:1024
	ds_read_b128 v[222:225], v171 offset:2048
	ds_read_b128 v[226:229], v171 offset:3072
	s_add_i32 s7, s6, 0x6000
	s_cmp_eq_u32 s6, 0xc000
	s_cselect_b32 s6, 0, s7
	s_waitcnt lgkmcnt(10)
	v_mfma_f32_16x16x32_bf16 v[112:115], v[172:175], v[176:179], v[112:115]
	s_waitcnt lgkmcnt(9)
	v_mfma_f32_16x16x32_bf16 v[116:119], v[172:175], v[188:191], v[116:119]
	s_waitcnt lgkmcnt(8)
	v_mfma_f32_16x16x32_bf16 v[80:83], v[172:175], v[180:183], v[80:83]
	s_waitcnt lgkmcnt(7)
	v_mfma_f32_16x16x32_bf16 v[84:87], v[172:175], v[192:195], v[84:87]
	s_waitcnt lgkmcnt(6)
	v_mfma_f32_16x16x32_bf16 v[48:51], v[172:175], v[230:233], v[48:51]
	s_waitcnt lgkmcnt(5)
	v_mfma_f32_16x16x32_bf16 v[52:55], v[172:175], v[234:237], v[52:55]
	s_waitcnt lgkmcnt(4)
	v_mfma_f32_16x16x32_bf16 v[16:19], v[172:175], v[238:241], v[16:19]
	s_waitcnt lgkmcnt(3)
	v_mfma_f32_16x16x32_bf16 v[20:23], v[172:175], v[242:245], v[20:23]
	s_waitcnt lgkmcnt(2)
	v_mfma_f32_16x16x32_bf16 v[120:123], v[184:187], v[176:179], v[120:123]
	v_mfma_f32_16x16x32_bf16 v[124:127], v[184:187], v[188:191], v[124:127]
	v_mfma_f32_16x16x32_bf16 v[88:91], v[184:187], v[180:183], v[88:91]
	v_mfma_f32_16x16x32_bf16 v[92:95], v[184:187], v[192:195], v[92:95]
	v_mfma_f32_16x16x32_bf16 v[56:59], v[184:187], v[230:233], v[56:59]
	v_mfma_f32_16x16x32_bf16 v[60:63], v[184:187], v[234:237], v[60:63]
	v_mfma_f32_16x16x32_bf16 v[24:27], v[184:187], v[238:241], v[24:27]
	v_mfma_f32_16x16x32_bf16 v[28:31], v[184:187], v[242:245], v[28:31]
	s_waitcnt lgkmcnt(1)
	v_mfma_f32_16x16x32_bf16 v[96:99], v[222:225], v[176:179], v[96:99]
	v_mfma_f32_16x16x32_bf16 v[100:103], v[222:225], v[188:191], v[100:103]
	v_mfma_f32_16x16x32_bf16 v[64:67], v[222:225], v[180:183], v[64:67]
	v_mfma_f32_16x16x32_bf16 v[68:71], v[222:225], v[192:195], v[68:71]
	v_mfma_f32_16x16x32_bf16 v[32:35], v[222:225], v[230:233], v[32:35]
	v_mfma_f32_16x16x32_bf16 v[36:39], v[222:225], v[234:237], v[36:39]
	v_mfma_f32_16x16x32_bf16 v[0:3], v[222:225], v[238:241], v[0:3]
	v_mfma_f32_16x16x32_bf16 v[4:7], v[222:225], v[242:245], v[4:7]
	s_waitcnt lgkmcnt(0)
	v_mfma_f32_16x16x32_bf16 v[104:107], v[226:229], v[176:179], v[104:107]
	v_mfma_f32_16x16x32_bf16 v[108:111], v[226:229], v[188:191], v[108:111]
	v_mfma_f32_16x16x32_bf16 v[72:75], v[226:229], v[180:183], v[72:75]
	v_mfma_f32_16x16x32_bf16 v[76:79], v[226:229], v[192:195], v[76:79]
	v_mfma_f32_16x16x32_bf16 v[40:43], v[226:229], v[230:233], v[40:43]
	v_mfma_f32_16x16x32_bf16 v[44:47], v[226:229], v[234:237], v[44:47]
	v_mfma_f32_16x16x32_bf16 v[8:11], v[226:229], v[238:241], v[8:11]
	v_mfma_f32_16x16x32_bf16 v[12:15], v[226:229], v[242:245], v[12:15]
	s_waitcnt vmcnt(0)
	s_barrier
; __device__ __forceinline__ void h_main(f32x16 (&acc0)[2][2], f32x16 (&acc1)[2][2], const WideCtx& c, int nk, char* lds) {
;   const int h = c.h;
;   for (int kt = 0; kt < nk; ++kt) {
;     asm volatile("s_waitcnt vmcnt(0)" ::: "memory");
;     __builtin_amdgcn_s_barrier();
;     if (kt + 1 < nk) h_stage(c, kt + 1);
;     const char* st = lds + (kt & 1) * 24576;
; #pragma unroll
;     for (int ks = 0; ks < 2; ++ks) {
;       bf16x8 wf[2], a0[2], a1[2];
; #pragma unroll
;       for (int b = 0; b < 2; ++b) {
;         wf[b] = *(const bf16x8*)(st + c.wro[b] + (((ks * 2 + h) ^ c.wsw[b]) << 4));
;         a0[b] = *(const bf16x8*)(st + c.aro[0][b] + (((ks * 2 + h) ^ c.asw[0][b]) << 4));
;         a1[b] = *(const bf16x8*)(st + c.aro[1][b] + (((ks * 2 + h) ^ c.asw[1][b]) << 4));
;       }
; #pragma unroll
;       for (int nb = 0; nb < 2; ++nb)
; #pragma unroll
;         for (int tb = 0; tb < 2; ++tb) {
;           acc0[nb][tb] = __builtin_amdgcn_mfma_f32_32x32x16_bf16(wf[nb], a0[tb], acc0[nb][tb], 0, 0, 0);
;           acc1[nb][tb] = __builtin_amdgcn_mfma_f32_32x32x16_bf16(wf[nb], a1[tb], acc1[nb][tb], 0, 0, 0);
;         }
	v_add_u32_e32 v171, s6, v248
	v_add_u32_e32 v196, s6, v249
	ds_read_b128 v[172:175], v171
	ds_read_b128 v[176:179], v196 offset:8192
	ds_read_b128 v[188:191], v196 offset:9216
	ds_read_b128 v[180:183], v196 offset:10240
	ds_read_b128 v[192:195], v196 offset:11264
	ds_read_b128 v[230:233], v196 offset:16384
	ds_read_b128 v[234:237], v196 offset:17408
	ds_read_b128 v[238:241], v196 offset:18432
	ds_read_b128 v[242:245], v196 offset:19456
	ds_read_b128 v[184:187], v171 offset:1024
	ds_read_b128 v[222:225], v171 offset:2048
	ds_read_b128 v[226:229], v171 offset:3072
	s_add_i32 s7, s6, 0x6000
	s_cmp_eq_u32 s6, 0xc000
	s_cselect_b32 s6, 0, s7
	s_waitcnt lgkmcnt(10)
	v_mfma_f32_16x16x32_bf16 v[112:115], v[172:175], v[176:179], v[112:115]
	s_waitcnt lgkmcnt(9)
	v_mfma_f32_16x16x32_bf16 v[116:119], v[172:175], v[188:191], v[116:119]
	s_waitcnt lgkmcnt(8)
	v_mfma_f32_16x16x32_bf16 v[80:83], v[172:175], v[180:183], v[80:83]
	s_waitcnt lgkmcnt(7)
	v_mfma_f32_16x16x32_bf16 v[84:87], v[172:175], v[192:195], v[84:87]
	s_waitcnt lgkmcnt(6)
	v_mfma_f32_16x16x32_bf16 v[48:51], v[172:175], v[230:233], v[48:51]
	s_waitcnt lgkmcnt(5)
	v_mfma_f32_16x16x32_bf16 v[52:55], v[172:175], v[234:237], v[52:55]
	s_waitcnt lgkmcnt(4)
	v_mfma_f32_16x16x32_bf16 v[16:19], v[172:175], v[238:241], v[16:19]
	s_waitcnt lgkmcnt(3)
	v_mfma_f32_16x16x32_bf16 v[20:23], v[172:175], v[242:245], v[20:23]
	s_waitcnt lgkmcnt(2)
	v_mfma_f32_16x16x32_bf16 v[120:123], v[184:187], v[176:179], v[120:123]
	v_mfma_f32_16x16x32_bf16 v[124:127], v[184:187], v[188:191], v[124:127]
	v_mfma_f32_16x16x32_bf16 v[88:91], v[184:187], v[180:183], v[88:91]
	v_mfma_f32_16x16x32_bf16 v[92:95], v[184:187], v[192:195], v[92:95]
	v_mfma_f32_16x16x32_bf16 v[56:59], v[184:187], v[230:233], v[56:59]
	v_mfma_f32_16x16x32_bf16 v[60:63], v[184:187], v[234:237], v[60:63]
	v_mfma_f32_16x16x32_bf16 v[24:27], v[184:187], v[238:241], v[24:27]
	v_mfma_f32_16x16x32_bf16 v[28:31], v[184:187], v[242:245], v[28:31]
	s_waitcnt lgkmcnt(1)
	v_mfma_f32_16x16x32_bf16 v[96:99], v[222:225], v[176:179], v[96:99]
	v_mfma_f32_16x16x32_bf16 v[100:103], v[222:225], v[188:191], v[100:103]
	v_mfma_f32_16x16x32_bf16 v[64:67], v[222:225], v[180:183], v[64:67]
	v_mfma_f32_16x16x32_bf16 v[68:71], v[222:225], v[192:195], v[68:71]
	v_mfma_f32_16x16x32_bf16 v[32:35], v[222:225], v[230:233], v[32:35]
	v_mfma_f32_16x16x32_bf16 v[36:39], v[222:225], v[234:237], v[36:39]
	v_mfma_f32_16x16x32_bf16 v[0:3], v[222:225], v[238:241], v[0:3]
	v_mfma_f32_16x16x32_bf16 v[4:7], v[222:225], v[242:245], v[4:7]
	s_waitcnt lgkmcnt(0)
; __device__ __forceinline__ void h_main(f32x16 (&acc0)[2][2], f32x16 (&acc1)[2][2], const WideCtx& c, int nk, char* lds) {
;   const int h = c.h;
;   for (int kt = 0; kt < nk; ++kt) {
;     asm volatile("s_waitcnt vmcnt(0)" ::: "memory");
;     __builtin_amdgcn_s_barrier();
;     if (kt + 1 < nk) h_stage(c, kt + 1);
;     const char* st = lds + (kt & 1) * 24576;
; #pragma unroll
;     for (int ks = 0; ks < 2; ++ks) {
;       bf16x8 wf[2], a0[2], a1[2];
; #pragma unroll
;       for (int b = 0; b < 2; ++b) {
;         wf[b] = *(const bf16x8*)(st + c.wro[b] + (((ks * 2 + h) ^ c.wsw[b]) << 4));
;         a0[b] = *(const bf16x8*)(st + c.aro[0][b] + (((ks * 2 + h) ^ c.asw[0][b]) << 4));
;         a1[b] = *(const bf16x8*)(st + c.aro[1][b] + (((ks * 2 + h) ^ c.asw[1][b]) << 4));
;       }
; #pragma unroll
;       for (int nb = 0; nb < 2; ++nb)
; #pragma unroll
;         for (int tb = 0; tb < 2; ++tb) {
;           acc0[nb][tb] = __builtin_amdgcn_mfma_f32_32x32x16_bf16(wf[nb], a0[tb], acc0[nb][tb], 0, 0, 0);
;           acc1[nb][tb] = __builtin_amdgcn_mfma_f32_32x32x16_bf16(wf[nb], a1[tb], acc1[nb][tb], 0, 0, 0);
;         }
;     }
;   }
; template <class F>
; __device__ __forceinline__ void gemm_phase_w(const u16* A, int lda, int M, const u16* W, int K, int N, char* lds, int* ctr, F&& epi) {
;     ...
;     const int ctm = tm, ctn = tn;
;     par ^= 1;
;     if (c.tid == 0) bw[2 + par] = atomicAdd(myctr, 1);
	v_mfma_f32_16x16x32_bf16 v[104:107], v[226:229], v[176:179], v[104:107]
	v_mfma_f32_16x16x32_bf16 v[108:111], v[226:229], v[188:191], v[108:111]
	v_mfma_f32_16x16x32_bf16 v[72:75], v[226:229], v[180:183], v[72:75]
	v_mfma_f32_16x16x32_bf16 v[76:79], v[226:229], v[192:195], v[76:79]
	v_mfma_f32_16x16x32_bf16 v[40:43], v[226:229], v[230:233], v[40:43]
	v_mfma_f32_16x16x32_bf16 v[44:47], v[226:229], v[234:237], v[44:47]
	v_mfma_f32_16x16x32_bf16 v[8:11], v[226:229], v[238:241], v[8:11]
	v_mfma_f32_16x16x32_bf16 v[12:15], v[226:229], v[242:245], v[12:15]
	s_xor_b32 s48, s48, 1
	s_nop 7
	s_nop 7
	v_permlane16_swap_b32_e32 v112, v116
	v_permlane16_swap_b32_e32 v113, v117
	v_permlane16_swap_b32_e32 v114, v118
	v_permlane16_swap_b32_e32 v115, v119
	v_permlane16_swap_b32_e32 v120, v124
	v_permlane16_swap_b32_e32 v121, v125
	v_permlane16_swap_b32_e32 v122, v126
	v_permlane16_swap_b32_e32 v123, v127
	v_permlane16_swap_b32_e32 v80, v84
	v_permlane16_swap_b32_e32 v81, v85
	v_permlane16_swap_b32_e32 v82, v86
	v_permlane16_swap_b32_e32 v83, v87
	v_permlane16_swap_b32_e32 v88, v92
	v_permlane16_swap_b32_e32 v89, v93
	v_permlane16_swap_b32_e32 v90, v94
	v_permlane16_swap_b32_e32 v91, v95
	v_permlane16_swap_b32_e32 v48, v52
	v_permlane16_swap_b32_e32 v49, v53
	v_permlane16_swap_b32_e32 v50, v54
	v_permlane16_swap_b32_e32 v51, v55
	v_permlane16_swap_b32_e32 v56, v60
	v_permlane16_swap_b32_e32 v57, v61
	v_permlane16_swap_b32_e32 v58, v62
	v_permlane16_swap_b32_e32 v59, v63
	v_permlane16_swap_b32_e32 v16, v20
	v_permlane16_swap_b32_e32 v17, v21
	v_permlane16_swap_b32_e32 v18, v22
	v_permlane16_swap_b32_e32 v19, v23
	v_permlane16_swap_b32_e32 v24, v28
	v_permlane16_swap_b32_e32 v25, v29
	v_permlane16_swap_b32_e32 v26, v30
	v_permlane16_swap_b32_e32 v27, v31
	v_permlane16_swap_b32_e32 v96, v100
	v_permlane16_swap_b32_e32 v97, v101
	v_permlane16_swap_b32_e32 v98, v102
	v_permlane16_swap_b32_e32 v99, v103
	v_permlane16_swap_b32_e32 v104, v108
	v_permlane16_swap_b32_e32 v105, v109
	v_permlane16_swap_b32_e32 v106, v110
	v_permlane16_swap_b32_e32 v107, v111
	v_permlane16_swap_b32_e32 v64, v68
	v_permlane16_swap_b32_e32 v65, v69
	v_permlane16_swap_b32_e32 v66, v70
	v_permlane16_swap_b32_e32 v67, v71
	v_permlane16_swap_b32_e32 v72, v76
	v_permlane16_swap_b32_e32 v73, v77
	v_permlane16_swap_b32_e32 v74, v78
	v_permlane16_swap_b32_e32 v75, v79
	v_permlane16_swap_b32_e32 v32, v36
	v_permlane16_swap_b32_e32 v33, v37
	v_permlane16_swap_b32_e32 v34, v38
	v_permlane16_swap_b32_e32 v35, v39
	v_permlane16_swap_b32_e32 v40, v44
	v_permlane16_swap_b32_e32 v41, v45
	v_permlane16_swap_b32_e32 v42, v46
	v_permlane16_swap_b32_e32 v43, v47
	v_permlane16_swap_b32_e32 v0, v4
	v_permlane16_swap_b32_e32 v1, v5
	v_permlane16_swap_b32_e32 v2, v6
	v_permlane16_swap_b32_e32 v3, v7
	v_permlane16_swap_b32_e32 v8, v12
	v_permlane16_swap_b32_e32 v9, v13
	v_permlane16_swap_b32_e32 v10, v14
	v_permlane16_swap_b32_e32 v11, v15
	v_permlane32_swap_b32_e32 v112, v116
	v_permlane32_swap_b32_e32 v113, v117
	v_permlane32_swap_b32_e32 v114, v118
	v_permlane32_swap_b32_e32 v115, v119
	v_permlane32_swap_b32_e32 v120, v124
	v_permlane32_swap_b32_e32 v121, v125
	v_permlane32_swap_b32_e32 v122, v126
	v_permlane32_swap_b32_e32 v123, v127
	v_permlane32_swap_b32_e32 v80, v84
	v_permlane32_swap_b32_e32 v81, v85
	v_permlane32_swap_b32_e32 v82, v86
	v_permlane32_swap_b32_e32 v83, v87
	v_permlane32_swap_b32_e32 v88, v92
	v_permlane32_swap_b32_e32 v89, v93
	v_permlane32_swap_b32_e32 v90, v94
	v_permlane32_swap_b32_e32 v91, v95
	v_permlane32_swap_b32_e32 v48, v52
	v_permlane32_swap_b32_e32 v49, v53
	v_permlane32_swap_b32_e32 v50, v54
	v_permlane32_swap_b32_e32 v51, v55
	v_permlane32_swap_b32_e32 v56, v60
	v_permlane32_swap_b32_e32 v57, v61
	v_permlane32_swap_b32_e32 v58, v62
	v_permlane32_swap_b32_e32 v59, v63
	v_permlane32_swap_b32_e32 v16, v20
	v_permlane32_swap_b32_e32 v17, v21
	v_permlane32_swap_b32_e32 v18, v22
	v_permlane32_swap_b32_e32 v19, v23
	v_permlane32_swap_b32_e32 v24, v28
	v_permlane32_swap_b32_e32 v25, v29
	v_permlane32_swap_b32_e32 v26, v30
	v_permlane32_swap_b32_e32 v27, v31
	v_permlane32_swap_b32_e32 v96, v100
	v_permlane32_swap_b32_e32 v97, v101
	v_permlane32_swap_b32_e32 v98, v102
	v_permlane32_swap_b32_e32 v99, v103
	v_permlane32_swap_b32_e32 v104, v108
	v_permlane32_swap_b32_e32 v105, v109
	v_permlane32_swap_b32_e32 v106, v110
	v_permlane32_swap_b32_e32 v107, v111
	v_permlane32_swap_b32_e32 v64, v68
	v_permlane32_swap_b32_e32 v65, v69
	v_permlane32_swap_b32_e32 v66, v70
	v_permlane32_swap_b32_e32 v67, v71
	v_permlane32_swap_b32_e32 v72, v76
	v_permlane32_swap_b32_e32 v73, v77
	v_permlane32_swap_b32_e32 v74, v78
	v_permlane32_swap_b32_e32 v75, v79
	v_permlane32_swap_b32_e32 v32, v36
	v_permlane32_swap_b32_e32 v33, v37
	v_permlane32_swap_b32_e32 v34, v38
	v_permlane32_swap_b32_e32 v35, v39
	v_permlane32_swap_b32_e32 v40, v44
	v_permlane32_swap_b32_e32 v41, v45
	v_permlane32_swap_b32_e32 v42, v46
	v_permlane32_swap_b32_e32 v43, v47
	v_permlane32_swap_b32_e32 v0, v4
	v_permlane32_swap_b32_e32 v1, v5
	v_permlane32_swap_b32_e32 v2, v6
	v_permlane32_swap_b32_e32 v3, v7
	v_permlane32_swap_b32_e32 v8, v12
	v_permlane32_swap_b32_e32 v9, v13
	v_permlane32_swap_b32_e32 v10, v14
	v_permlane32_swap_b32_e32 v11, v15
	s_and_saveexec_b64 s[6:7], vcc
	s_cbranch_execz .LBB0_698
	s_mov_b64 s[34:35], exec
	v_mbcnt_lo_u32_b32 v144, s34, 0
	v_mbcnt_hi_u32_b32 v144, s35, v144
	v_cmp_eq_u32_e64 s[38:39], 0, v144
	s_and_saveexec_b64 s[0:1], s[38:39]
	s_cbranch_execz .LBB0_697
	s_bcnt1_i32_b64 s9, s[34:35]
	v_mov_b32_e32 v145, s9
	global_atomic_add v145, v161, v145, s[30:31] offset:256 sc0
